# adds de-serialised dilated-attention K fragment loads and relaxed store-only waits in the conv-gate epilogue to v34
# speedup vs baseline: 1.0060x; 1.0060x over previous
; #define GAS __attribute__((address_space(1)))
; #define MFMA32(a, b, c) __builtin_amdgcn_mfma_f32_32x32x16_bf16((a), (b), (c), 0, 0, 0)
; DI void dil_phase(int wv, const bf16_t* QK, const bf16_t* VTg, int rows, int nb, int S, int rr, int pat, bf16_t* OUT, float* LSE) {
;     ...
;     for (int k = lw; k < upx; k += lstride) {
;         const int wu = xcd * upx + k;
;         const int inner = wu & (per_sh - 1), sh = wu >> __builtin_ctz(per_sh), head = sh & 7, seq = sh >> 3;
;         const int cls = inner >> __builtin_ctz(ublk), i0 = (inner & (ublk - 1)) * 32;
;         const size_t seq0 = (size_t)seq * S;
;         const int qtok = cls + rr * (i0 + r);
;         const bf16_t* qp = QK + (seq0 + qtok) * 2048 + 1024 + head * 64 + 8 * hi;
;         const bf16_t* kbase = QK + (seq0 + cls) * 2048 + 1536 + head * 64 + 8 * hi;
;         const bf16_t* vbase = VTg + (size_t)head * rows * 64 + ((seq0 + (size_t)cls * Sr) >> 3) * 512 + r * 8;
;         bf16_t* orow = OUT + (seq0 + qtok) * 1024 + 512 + head * 64 + 4 * hi;
;         GAS float* lsep = (GAS float*)(LSE + (seq0 + qtok) * 8 + head);
;         bf16x8 qf[4];
; #pragma unroll
;         for (int ds = 0; ds < 4; ++ds) qf[ds] = *(const GAS bf16x8*)(qp + 16 * ds);
;         bf16x8 kf[4], vf[4], kn[4], vn[4];
;     ...
;         DIL_LOAD(kf, vf, 0);
;     ...
;         for (int kb = 0; kb < 5; ++kb) {
;             if (kb < 4) DIL_LOAD(kn, vn, kb + 1);
;             f32x16 sc;
; #pragma unroll
;             for (int i = 0; i < 16; ++i) sc[i] = 0.f;
; #pragma unroll
;             for (int ds = 0; ds < 4; ++ds) sc = MFMA32(kf[ds], qf[ds], sc);
.LBB0_355:
	v_readlane_b32 s12, v254, 42
	s_add_i32 s12, s12, s6
	v_readlane_b32 s13, v254, 56
	s_and_b32 s74, s12, s13
	v_readlane_b32 s13, v254, 57
	s_ashr_i32 s12, s12, s13
	s_and_b32 s80, s12, 7
	s_ashr_i32 s12, s12, 3
	s_ashr_i32 s13, s12, 31
	s_lshl_b64 s[72:73], s[12:13], s9
	v_readlane_b32 s12, v254, 50
	s_and_b32 s33, s74, s12
	v_readlane_b32 s12, v254, 58
	s_lshl_b32 s40, s80, 7
	s_lshr_b32 s74, s74, s12
	s_lshl_b32 s12, s33, 5
	s_add_u32 s76, s72, s74
	s_addc_u32 s77, s73, 0
	s_lshl_b64 s[76:77], s[76:77], 12
	s_add_u32 s13, s0, s76
	s_addc_u32 s75, s1, s77
	s_add_u32 s76, s13, s40
	s_addc_u32 s77, s75, 0
	s_lshl_b32 s13, s80, s10
	s_lshl_b32 s13, s13, 1
	v_readlane_b32 s78, v254, 44
	s_mov_b32 s75, s41
	v_readlane_b32 s79, v254, 45
	s_add_u32 s13, s78, s13
	s_addc_u32 s81, s79, 0
	s_lshl_b64 s[78:79], s[74:75], s11
	v_or_b32_e32 v0, s12, v73
	s_add_u32 s78, s72, s78
	v_lshl_add_u32 v192, v0, 2, s74
	s_addc_u32 s79, s73, s79
	v_lshl_add_u64 v[16:17], s[72:73], 0, v[192:193]
	v_readlane_b32 s72, v254, 48
	s_lshl_b64 s[78:79], s[78:79], 7
	v_lshlrev_b64 v[0:1], 12, v[16:17]
	v_lshlrev_b64 v[2:3], 11, v[16:17]
	v_readlane_b32 s73, v254, 49
	s_add_u32 s78, s13, s78
	v_lshl_add_u64 v[0:1], s[0:1], 0, v[0:1]
	v_lshl_add_u64 v[2:3], s[72:73], 0, v[2:3]
	s_addc_u32 s79, s81, s79
	v_lshlrev_b32_e32 v192, 1, v72
	v_lshl_add_u64 v[0:1], v[0:1], 0, s[40:41]
	v_lshl_add_u64 v[18:19], v[2:3], 0, s[40:41]
	s_lshl_b32 s40, s80, 2
	s_sub_i32 s13, s12, 64
	v_lshl_add_u64 v[30:31], v[0:1], 0, v[192:193]
	s_cmp_lt_u32 s33, 2
	v_or_b32_e32 v0, s13, v93
	v_lshl_add_u64 v[86:87], s[76:77], 0, v[192:193]
	v_min_i32_e32 v0, s8, v0
	s_cselect_b64 s[76:77], -1, 0
	v_or_b32_e32 v4, s13, v72
	v_cndmask_b32_e64 v192, v0, 0, s[76:77]
	v_lshrrev_b32_e32 v2, 3, v4
	v_cmp_gt_i32_e64 s[72:73], s7, v4
	v_or_b32_e32 v4, 16, v4
	v_lshlrev_b64 v[0:1], 14, v[192:193]
	v_cndmask_b32_e64 v192, 0, v2, s[72:73]
	v_lshrrev_b32_e32 v5, 3, v4
	v_cmp_gt_i32_e64 s[74:75], s7, v4
	v_lshlrev_b64 v[2:3], 9, v[192:193]
	v_cndmask_b32_e64 v21, v3, 0, s[76:77]
	v_cndmask_b32_e64 v192, 0, v5, s[74:75]
	v_cndmask_b32_e64 v20, v2, 0, s[76:77]
	v_lshlrev_b64 v[2:3], 9, v[192:193]
	v_cndmask_b32_e64 v23, v3, 0, s[76:77]
	v_cndmask_b32_e64 v22, v2, 0, s[76:77]
	s_sub_i32 s76, s12, 32
	v_or_b32_e32 v2, s76, v72
	v_lshrrev_b32_e32 v3, 3, v2
	v_cmp_gt_i32_e64 s[74:75], s7, v2
	v_add_u32_e32 v4, s12, v209
	v_lshrrev_b32_e32 v5, 3, v4
	v_cndmask_b32_e64 v192, 0, v3, s[74:75]
	v_cmp_gt_i32_e64 s[74:75], s7, v4
	s_cmp_eq_u32 s33, 0
	v_lshlrev_b64 v[2:3], 9, v[192:193]
	v_cndmask_b32_e64 v192, 0, v5, s[74:75]
	s_cselect_b64 s[74:75], -1, 0
	v_cndmask_b32_e64 v25, v3, 0, s[74:75]
	v_cndmask_b32_e64 v24, v2, 0, s[74:75]
	v_lshlrev_b64 v[2:3], 9, v[192:193]
	v_lshl_add_u64 v[40:41], v[86:87], 0, v[0:1]
	v_cndmask_b32_e64 v27, v3, 0, s[74:75]
	v_cndmask_b32_e64 v26, v2, 0, s[74:75]
	global_load_dwordx4 v[0:3], v[40:41], off offset:3072
	global_load_dwordx4 v[60:63], v[30:31], off offset:2048
	global_load_dwordx4 v[32:35], v[40:41], off offset:3104
	global_load_dwordx4 v[56:59], v[30:31], off offset:2080
	global_load_dwordx4 v[36:39], v[40:41], off offset:3136
	global_load_dwordx4 v[52:55], v[30:31], off offset:2112
	global_load_dwordx4 v[64:67], v[40:41], off offset:3168
	global_load_dwordx4 v[48:51], v[30:31], off offset:2144
	v_or_b32_e32 v4, s76, v93
	v_min_i32_e32 v4, s8, v4
	v_cndmask_b32_e64 v28, v4, 0, s[74:75]
	s_cmp_gt_u32 s33, 1
	s_cselect_b64 s[74:75], -1, 0
	v_readlane_b32 s76, v254, 59
	s_and_b64 s[72:73], s[74:75], s[72:73]
	v_readlane_b32 s77, v254, 60
	s_and_b64 s[72:73], s[72:73], s[76:77]
	v_mov_b32_e32 v250, 0xff800000
	v_readlane_b32 s76, v254, 61
	v_readlane_b32 s77, v254, 62
	v_ashrrev_i32_e32 v29, 31, v28
	v_mov_b32_e32 v77, v193
	v_lshl_add_u64 v[78:79], s[78:79], 0, v[76:77]
	v_mov_b32_e32 v75, v193
	v_lshl_add_u64 v[80:81], v[18:19], 0, v[74:75]
	v_lshlrev_b64 v[16:17], 5, v[16:17]
	v_lshl_add_u64 v[20:21], v[20:21], 1, v[78:79]
	v_lshl_add_u64 v[246:247], v[24:25], 1, v[78:79]
	v_lshl_add_u64 v[248:249], v[26:27], 1, v[78:79]
	s_add_i32 s33, s12, 32
	v_cmp_lt_i32_e64 s[78:79], s13, v179
	s_waitcnt vmcnt(0)
	v_mfma_f32_32x32x16_bf16 v[0:15], v[0:3], v[60:63], 0
	v_cmp_lt_i32_e64 s[80:81], s13, v180
	v_cmp_lt_i32_e64 s[82:83], s13, v181
	v_cmp_lt_i32_e64 s[84:85], s13, v182
	v_cmp_lt_i32_e64 s[86:87], s13, v183
	v_cmp_lt_i32_e64 s[88:89], s13, v184
	v_mfma_f32_32x32x16_bf16 v[0:15], v[32:35], v[56:59], v[0:15]
	s_nop 0
	s_nop 0
	s_nop 0
	s_waitcnt vmcnt(2)
	v_mfma_f32_32x32x16_bf16 v[0:15], v[36:39], v[52:55], v[0:15]
	s_waitcnt vmcnt(0)
; #define MFMA32(a, b, c) __builtin_amdgcn_mfma_f32_32x32x16_bf16((a), (b), (c), 0, 0, 0)
; DI void dil_phase(int wv, const bf16_t* QK, const bf16_t* VTg, int rows, int nb, int S, int rr, int pat, bf16_t* OUT, float* LSE) {
;     ...
;         for (int kb = 0; kb < 5; ++kb) {
;             if (kb < 4) DIL_LOAD(kn, vn, kb + 1);
;             f32x16 sc;
; #pragma unroll
;             for (int i = 0; i < 16; ++i) sc[i] = 0.f;
; #pragma unroll
;             for (int ds = 0; ds < 4; ++ds) sc = MFMA32(kf[ds], qf[ds], sc);
;             float mx = -3.0e38f;
; #pragma unroll
;             for (int i = 0; i < 16; ++i) {
;                 const int kk = 32 * kb + 16 * (i >> 3) + 8 * hi + (i & 7), mk = i0 - 64 + kk, dd = kk - r;
;                 const bool ok = (mk >= 0) && (mk < Sr) && (dd >= 0) && (dd <= 128);
;                 const float v = ok ? sc[i] : -INFINITY; sc[i] = v; mx = fmaxf(mx, v);
	v_mfma_f32_32x32x16_bf16 v[0:15], v[64:67], v[48:51], v[0:15]
	s_nop 11
	v_cndmask_b32_e64 v32, v250, v0, s[72:73]
	v_or_b32_e32 v0, s13, v122
	v_cmp_gt_i32_e64 s[72:73], s7, v0
	s_and_b64 s[72:73], s[74:75], s[72:73]
	s_and_b64 s[72:73], s[72:73], s[76:77]
	v_or_b32_e32 v0, s13, v123
	v_cndmask_b32_e64 v33, v250, v1, s[72:73]
	v_cmp_gt_i32_e64 s[72:73], s7, v0
	v_readlane_b32 s76, v254, 63
	s_and_b64 s[72:73], s[74:75], s[72:73]
	v_readlane_b32 s77, v255, 0
	s_and_b64 s[72:73], s[72:73], s[76:77]
	v_or_b32_e32 v0, s13, v124
	v_cndmask_b32_e64 v34, v250, v2, s[72:73]
	v_cmp_gt_i32_e64 s[72:73], s7, v0
	v_readlane_b32 s76, v255, 1
	s_and_b64 s[72:73], s[74:75], s[72:73]
	v_readlane_b32 s77, v255, 2
	s_and_b64 s[72:73], s[72:73], s[76:77]
	v_or_b32_e32 v0, s13, v125
	v_cndmask_b32_e64 v35, v250, v3, s[72:73]
	v_cmp_gt_i32_e64 s[72:73], s7, v0
	s_and_b64 s[72:73], s[74:75], s[72:73]
	s_and_b64 s[72:73], s[72:73], s[14:15]
	v_or_b32_e32 v0, s13, v126
	v_cndmask_b32_e64 v36, v250, v4, s[72:73]
	v_cmp_gt_i32_e64 s[72:73], s7, v0
	s_and_b64 s[72:73], s[74:75], s[72:73]
	s_and_b64 s[72:73], s[72:73], s[16:17]
	v_or_b32_e32 v0, s13, v127
	v_cndmask_b32_e64 v37, v250, v5, s[72:73]
	v_cmp_gt_i32_e64 s[72:73], s7, v0
	s_and_b64 s[72:73], s[74:75], s[72:73]
	s_and_b64 s[72:73], s[72:73], s[18:19]
	v_or_b32_e32 v0, s13, v128
	v_cndmask_b32_e64 v38, v250, v6, s[72:73]
	v_cmp_gt_i32_e64 s[72:73], s7, v0
	s_and_b64 s[72:73], s[74:75], s[72:73]
	s_and_b64 s[72:73], s[72:73], s[20:21]
	v_or_b32_e32 v0, s13, v129
	v_cndmask_b32_e64 v39, v250, v7, s[72:73]
	v_cmp_gt_i32_e64 s[72:73], s7, v0
	s_and_b64 s[72:73], s[74:75], s[72:73]
	s_and_b64 s[72:73], s[72:73], s[22:23]
	v_or_b32_e32 v0, s13, v130
	v_cndmask_b32_e64 v40, v250, v8, s[72:73]
	v_cmp_gt_i32_e64 s[72:73], s7, v0
	s_and_b64 s[72:73], s[74:75], s[72:73]
	s_and_b64 s[72:73], s[72:73], s[24:25]
	v_or_b32_e32 v0, s13, v131
	v_cndmask_b32_e64 v41, v250, v9, s[72:73]
	v_cmp_gt_i32_e64 s[72:73], s7, v0
	s_and_b64 s[72:73], s[74:75], s[72:73]
	s_and_b64 s[72:73], s[72:73], s[26:27]
	v_or_b32_e32 v0, s13, v132
	v_cndmask_b32_e64 v42, v250, v10, s[72:73]
	v_cmp_gt_i32_e64 s[72:73], s7, v0
	s_and_b64 s[72:73], s[74:75], s[72:73]
	s_and_b64 s[72:73], s[72:73], s[28:29]
	v_or_b32_e32 v0, s13, v133
	v_cndmask_b32_e64 v43, v250, v11, s[72:73]
	v_cmp_gt_i32_e64 s[72:73], s7, v0
	s_and_b64 s[72:73], s[74:75], s[72:73]
	s_and_b64 s[72:73], s[72:73], s[30:31]
	v_or_b32_e32 v0, s13, v134
	v_cndmask_b32_e64 v45, v250, v12, s[72:73]
	v_cmp_gt_i32_e64 s[72:73], s7, v0
	s_and_b64 s[72:73], s[74:75], s[72:73]
	s_and_b64 s[72:73], s[72:73], s[34:35]
	v_or_b32_e32 v0, s13, v135
	v_cndmask_b32_e64 v46, v250, v13, s[72:73]
	v_cmp_gt_i32_e64 s[72:73], s7, v0
	s_and_b64 s[72:73], s[74:75], s[72:73]
	s_and_b64 s[72:73], s[72:73], s[36:37]
	v_or_b32_e32 v0, s13, v136
	v_cndmask_b32_e64 v47, v250, v14, s[72:73]
	v_cmp_gt_i32_e64 s[72:73], s7, v0
	s_and_b64 s[72:73], s[74:75], s[72:73]
	v_or_b32_e32 v0, s12, v93
	s_and_b64 s[72:73], s[72:73], s[38:39]
	v_min_i32_e32 v192, s8, v0
	v_or_b32_e32 v0, s12, v72
	v_cndmask_b32_e64 v44, v250, v15, s[72:73]
	v_lshrrev_b32_e32 v1, 3, v0
	v_cmp_gt_u32_e64 s[72:73], s7, v0
	v_or_b32_e32 v0, s12, v129
	v_lshlrev_b64 v[30:31], 14, v[192:193]
	v_cndmask_b32_e64 v192, 0, v1, s[72:73]
	v_lshrrev_b32_e32 v1, 3, v0
	v_cmp_gt_u32_e64 s[72:73], s7, v0
	v_add_u32_e32 v0, s13, v137
	v_lshlrev_b64 v[84:85], 10, v[192:193]
	v_cndmask_b32_e64 v192, 0, v1, s[72:73]
	v_cmp_lt_i32_e64 s[72:73], -1, v0
	v_cmp_gt_i32_e64 s[74:75], s7, v0
	v_lshlrev_b64 v[0:1], 14, v[28:29]
	v_lshl_add_u64 v[28:29], v[86:87], 0, v[0:1]
	global_load_dwordx4 v[0:3], v[28:29], off offset:3072
	global_load_dwordx4 v[64:67], v[28:29], off offset:3104
	global_load_dwordx4 v[226:229], v[28:29], off offset:3136
	global_load_dwordx4 v[230:233], v[28:29], off offset:3168
	s_waitcnt vmcnt(3)
	v_mfma_f32_32x32x16_bf16 v[0:15], v[0:3], v[60:63], 0
	s_and_b64 s[72:73], s[72:73], s[74:75]
	v_cmp_lt_i32_e64 s[76:77], s13, v178
	s_waitcnt vmcnt(2)
	v_mfma_f32_32x32x16_bf16 v[0:15], v[64:67], v[56:59], v[0:15]
	s_nop 0
	s_waitcnt vmcnt(1)
	v_mfma_f32_32x32x16_bf16 v[0:15], v[226:229], v[52:55], v[0:15]
	s_nop 0
	v_lshl_add_u64 v[28:29], v[86:87], 0, v[30:31]
	s_waitcnt vmcnt(0)
; #define GAS __attribute__((address_space(1)))
; DI float bf_lo(unsigned u) { return __uint_as_float(u << 16); }
; DI float bf_hi(unsigned u) { return __uint_as_float(u & 0xffff0000u); }
; #define MFMA32(a, b, c) __builtin_amdgcn_mfma_f32_32x32x16_bf16((a), (b), (c), 0, 0, 0)
; DI void dil_phase(int wv, const bf16_t* QK, const bf16_t* VTg, int rows, int nb, int S, int rr, int pat, bf16_t* OUT, float* LSE) {
;     ...
;         if (pat > 0) {
;             mrun = *lsep; lrun = hi == 0 ? 1.0f : 0.0f;
; #pragma unroll
;             for (int cb = 0; cb < 2; ++cb)
; #pragma unroll
;                 for (int j4 = 0; j4 < 4; ++j4) { const u32x2 w = *(const GAS u32x2*)(orow + 32 * cb + 8 * j4);
;                     O[cb][4 * j4] = bf_lo(w.x); O[cb][4 * j4 + 1] = bf_hi(w.x); O[cb][4 * j4 + 2] = bf_lo(w.y); O[cb][4 * j4 + 3] = bf_hi(w.y); }
;     ...
;         for (int kb = 0; kb < 5; ++kb) {
;             if (kb < 4) DIL_LOAD(kn, vn, kb + 1);
;             f32x16 sc;
; #pragma unroll
;             for (int i = 0; i < 16; ++i) sc[i] = 0.f;
; #pragma unroll
;             for (int ds = 0; ds < 4; ++ds) sc = MFMA32(kf[ds], qf[ds], sc);
;             float mx = -3.0e38f;
; #pragma unroll
;             for (int i = 0; i < 16; ++i) {
;                 const int kk = 32 * kb + 16 * (i >> 3) + 8 * hi + (i & 7), mk = i0 - 64 + kk, dd = kk - r;
;                 const bool ok = (mk >= 0) && (mk < Sr) && (dd >= 0) && (dd <= 128);
;                 const float v = ok ? sc[i] : -INFINITY; sc[i] = v; mx = fmaxf(mx, v);
	v_mfma_f32_32x32x16_bf16 v[0:15], v[230:233], v[48:51], v[0:15]
	global_load_dwordx4 v[64:67], v[28:29], off offset:3104
	global_load_dwordx4 v[234:237], v[28:29], off offset:3072
	global_load_dwordx4 v[226:229], v[28:29], off offset:3136
	global_load_dwordx4 v[230:233], v[28:29], off offset:3168
	s_nop 10
	v_cndmask_b32_e64 v88, v250, v0, s[72:73]
	v_add_u32_e32 v0, s13, v138
	v_cmp_lt_i32_e64 s[72:73], -1, v0
	v_cmp_gt_i32_e64 s[74:75], s7, v0
	s_and_b64 s[72:73], s[72:73], s[74:75]
	v_add_u32_e32 v0, s13, v139
	v_cndmask_b32_e64 v90, v250, v1, s[72:73]
	v_cmp_lt_i32_e64 s[72:73], -1, v0
	v_cmp_gt_i32_e64 s[74:75], s7, v0
	s_and_b64 s[72:73], s[72:73], s[74:75]
	v_add_u32_e32 v0, s13, v140
	v_cndmask_b32_e64 v94, v250, v2, s[72:73]
	v_cmp_lt_i32_e64 s[72:73], -1, v0
	v_cmp_gt_i32_e64 s[74:75], s7, v0
	s_and_b64 s[72:73], s[72:73], s[74:75]
	v_add_u32_e32 v0, s13, v141
	v_cndmask_b32_e64 v96, v250, v3, s[72:73]
	v_cmp_lt_i32_e64 s[72:73], -1, v0
	v_cmp_gt_i32_e64 s[74:75], s7, v0
	s_and_b64 s[72:73], s[72:73], s[74:75]
	v_add_u32_e32 v0, s13, v142
	v_cndmask_b32_e64 v98, v250, v4, s[72:73]
	v_cmp_lt_i32_e64 s[72:73], -1, v0
	v_cmp_gt_i32_e64 s[74:75], s7, v0
	s_and_b64 s[72:73], s[72:73], s[74:75]
	v_add_u32_e32 v0, s13, v143
	v_cndmask_b32_e64 v100, v250, v5, s[72:73]
	v_cmp_lt_i32_e64 s[72:73], -1, v0
	v_cmp_gt_i32_e64 s[74:75], s7, v0
	s_and_b64 s[72:73], s[72:73], s[74:75]
	v_add_u32_e32 v0, s13, v144
	v_cndmask_b32_e64 v102, v250, v6, s[72:73]
	v_cmp_lt_i32_e64 s[72:73], -1, v0
	v_cmp_gt_i32_e64 s[74:75], s7, v0
	s_and_b64 s[72:73], s[72:73], s[74:75]
	v_add_u32_e32 v0, s13, v145
	v_cndmask_b32_e64 v104, v250, v7, s[72:73]
	v_cmp_lt_i32_e64 s[72:73], -1, v0
	v_cmp_gt_i32_e64 s[74:75], s7, v0
	s_and_b64 s[72:73], s[72:73], s[74:75]
	v_add_u32_e32 v0, s13, v146
	v_cndmask_b32_e64 v110, v250, v8, s[72:73]
	v_cmp_lt_i32_e64 s[72:73], -1, v0
	v_cmp_gt_i32_e64 s[74:75], s7, v0
	s_and_b64 s[72:73], s[72:73], s[74:75]
	v_add_u32_e32 v0, s13, v147
	v_cndmask_b32_e64 v114, v250, v9, s[72:73]
	v_cmp_lt_i32_e64 s[72:73], -1, v0
	v_cmp_gt_i32_e64 s[74:75], s7, v0
	s_and_b64 s[72:73], s[72:73], s[74:75]
	v_add_u32_e32 v0, s13, v148
	v_cndmask_b32_e64 v106, v250, v10, s[72:73]
	v_cmp_lt_i32_e64 s[72:73], -1, v0
	v_cmp_gt_i32_e64 s[74:75], s7, v0
	s_and_b64 s[72:73], s[72:73], s[74:75]
	v_add_u32_e32 v0, s13, v149
	v_cndmask_b32_e64 v108, v250, v11, s[72:73]
	v_cmp_lt_i32_e64 s[72:73], -1, v0
	v_cmp_gt_i32_e64 s[74:75], s7, v0
	s_and_b64 s[72:73], s[72:73], s[74:75]
	v_add_u32_e32 v0, s13, v150
	v_cndmask_b32_e64 v112, v250, v12, s[72:73]
	v_cmp_lt_i32_e64 s[72:73], -1, v0
	v_cmp_gt_i32_e64 s[74:75], s7, v0
	s_and_b64 s[72:73], s[72:73], s[74:75]
	v_add_u32_e32 v0, s13, v151
	v_cndmask_b32_e64 v116, v250, v13, s[72:73]
	v_cmp_lt_i32_e64 s[72:73], -1, v0
	v_cmp_gt_i32_e64 s[74:75], s7, v0
	s_and_b64 s[72:73], s[72:73], s[74:75]
	v_add_u32_e32 v0, s13, v152
	v_cndmask_b32_e64 v195, v250, v14, s[72:73]
	v_cmp_lt_i32_e64 s[72:73], -1, v0
	v_cmp_gt_i32_e64 s[74:75], s7, v0
	s_nop 0
	s_and_b64 s[72:73], s[72:73], s[74:75]
	v_cndmask_b32_e64 v194, v250, v15, s[72:73]
	s_waitcnt vmcnt(0)
	v_mfma_f32_32x32x16_bf16 v[0:15], v[234:237], v[60:63], 0
	v_cmp_lt_i32_e64 s[72:73], s13, v153
	v_cmp_lt_i32_e64 s[74:75], s13, v177
	v_mfma_f32_32x32x16_bf16 v[0:15], v[64:67], v[56:59], v[0:15]
	s_nop 0
	s_nop 0
	s_nop 0
	s_waitcnt vmcnt(1)
	v_mfma_f32_32x32x16_bf16 v[0:15], v[226:229], v[52:55], v[0:15]
	v_lshl_add_u64 v[64:65], v[22:23], 1, v[78:79]
	s_waitcnt vmcnt(0)
	v_mfma_f32_32x32x16_bf16 v[0:15], v[230:233], v[48:51], v[0:15]
	s_nop 11
	v_cndmask_b32_e64 v89, v250, v0, s[72:73]
	v_cmp_lt_i32_e64 s[72:73], s13, v154
	s_nop 1
	v_cndmask_b32_e64 v91, v250, v1, s[72:73]
	v_cmp_lt_i32_e64 s[72:73], s13, v155
	s_nop 1
	v_cndmask_b32_e64 v95, v250, v2, s[72:73]
	v_cmp_lt_i32_e64 s[72:73], s13, v156
	s_nop 1
	v_cndmask_b32_e64 v77, v250, v3, s[72:73]
	v_cmp_lt_i32_e64 s[72:73], s13, v157
	s_nop 1
	v_cndmask_b32_e64 v99, v250, v4, s[72:73]
	v_cmp_lt_i32_e64 s[72:73], s13, v158
	s_nop 1
	v_cndmask_b32_e64 v101, v250, v5, s[72:73]
	v_cmp_lt_i32_e64 s[72:73], s13, v159
	s_nop 1
	v_cndmask_b32_e64 v103, v250, v6, s[72:73]
	v_cmp_lt_i32_e64 s[72:73], s13, v160
	s_nop 1
	v_cndmask_b32_e64 v105, v250, v7, s[72:73]
	v_cmp_lt_i32_e64 s[72:73], s13, v161
	s_nop 1
	v_cndmask_b32_e64 v107, v250, v8, s[72:73]
	v_cmp_lt_i32_e64 s[72:73], s13, v162
	s_nop 1
	v_cndmask_b32_e64 v109, v250, v9, s[72:73]
	v_cmp_lt_i32_e64 s[72:73], s13, v163
	s_nop 1
	v_cndmask_b32_e64 v111, v250, v10, s[72:73]
	v_cmp_lt_i32_e64 s[72:73], s13, v164
	s_nop 1
	v_cndmask_b32_e64 v113, v250, v11, s[72:73]
	v_cmp_lt_i32_e64 s[72:73], s13, v165
	s_nop 1
	v_cndmask_b32_e64 v115, v250, v12, s[72:73]
	v_cmp_lt_i32_e64 s[72:73], s13, v166
	s_nop 1
	v_cndmask_b32_e64 v117, v250, v13, s[72:73]
	v_cmp_lt_i32_e64 s[72:73], s13, v167
	s_nop 1
	v_cndmask_b32_e64 v201, v250, v14, s[72:73]
	v_cmp_lt_i32_e64 s[72:73], s13, v168
	s_nop 1
	v_cndmask_b32_e64 v200, v250, v15, s[72:73]
	global_load_dwordx2 v[0:1], v[80:81], off offset:1024
	global_load_dwordx2 v[2:3], v[80:81], off offset:1040
	global_load_dwordx2 v[4:5], v[80:81], off offset:1056
	global_load_dwordx2 v[6:7], v[80:81], off offset:1072
	global_load_dwordx2 v[8:9], v[80:81], off offset:1088
	global_load_dwordx2 v[10:11], v[80:81], off offset:1104
	global_load_dwordx2 v[12:13], v[80:81], off offset:1120
	global_load_dwordx2 v[14:15], v[80:81], off offset:1136
	v_readlane_b32 s72, v254, 52
	v_readlane_b32 s73, v254, 53
	s_waitcnt vmcnt(6)
; #define GAS __attribute__((address_space(1)))
; DI unsigned pk2(float lo, float hi) { f32x2 v = {lo, hi}; bf16x2_t b = __builtin_convertvector(v, bf16x2_t); return __builtin_bit_cast(unsigned, b); }
; DI float bf_lo(unsigned u) { return __uint_as_float(u << 16); }
; DI float bf_hi(unsigned u) { return __uint_as_float(u & 0xffff0000u); }
; DI float swap_max(float m) { auto rr = __builtin_amdgcn_permlane32_swap(__float_as_uint(m), __float_as_uint(m), false, false); return fmaxf(__uint_as_float(rr[0]), __uint_as_float(rr[1])); }
; DI float ex2(float x) { return __builtin_amdgcn_exp2f(x); }
; #define MFMA32(a, b, c) __builtin_amdgcn_mfma_f32_32x32x16_bf16((a), (b), (c), 0, 0, 0)
; DI void dil_phase(int wv, const bf16_t* QK, const bf16_t* VTg, int rows, int nb, int S, int rr, int pat, bf16_t* OUT, float* LSE) {
;     ...
;         if (pat > 0) {
;             mrun = *lsep; lrun = hi == 0 ? 1.0f : 0.0f;
; #pragma unroll
;             for (int cb = 0; cb < 2; ++cb)
; #pragma unroll
;                 for (int j4 = 0; j4 < 4; ++j4) { const u32x2 w = *(const GAS u32x2*)(orow + 32 * cb + 8 * j4);
;                     O[cb][4 * j4] = bf_lo(w.x); O[cb][4 * j4 + 1] = bf_hi(w.x); O[cb][4 * j4 + 2] = bf_lo(w.y); O[cb][4 * j4 + 3] = bf_hi(w.y); }
;     ...
;             mx = swap_max(mx);
;             const float mnew = fmaxf(mrun, mx), alpha = ex2(mrun - mnew);
;             float ps = 0.f;
; #pragma unroll
;             for (int i = 0; i < 16; ++i) { const float p = ex2(sc[i] - mnew); sc[i] = p; ps += p; }
;             lrun = lrun * alpha + ps; mrun = mnew;
; #pragma unroll
;             for (int cb = 0; cb < 2; ++cb) O[cb] = O[cb] * alpha;
;             u32x4 w0, w1;
;             w0.x = pk2(sc[0], sc[1]); w0.y = pk2(sc[2], sc[3]); w0.z = pk2(sc[4], sc[5]); w0.w = pk2(sc[6], sc[7]);
;             w1.x = pk2(sc[8], sc[9]); w1.y = pk2(sc[10], sc[11]); w1.z = pk2(sc[12], sc[13]); w1.w = pk2(sc[14], sc[15]);
;             const bf16x8 pf0 = __builtin_bit_cast(bf16x8, w0), pf1 = __builtin_bit_cast(bf16x8, w1);
; #pragma unroll
;             for (int cb = 0; cb < 2; ++cb) { O[cb] = MFMA32(vf[cb], pf0, O[cb]); O[cb] = MFMA32(vf[2 + cb], pf1, O[cb]); }
	v_lshlrev_b32_e32 v66, 16, v2
	v_lshl_add_u64 v[16:17], s[72:73], 0, v[16:17]
	v_lshl_add_u64 v[82:83], v[16:17], 0, s[40:41]
	global_load_dword v75, v[82:83], off
	global_load_dwordx4 v[16:19], v[20:21], off
	global_load_dwordx4 v[28:31], v[20:21], off offset:512
	s_nop 0
	global_load_dwordx4 v[20:23], v[64:65], off
	global_load_dwordx4 v[226:229], v[64:65], off offset:512
	s_mov_b32 s40, 0xff61b1e6
	s_waitcnt vmcnt(8)
	v_lshlrev_b32_e32 v120, 16, v8
	v_and_b32_e32 v121, 0xffff0000, v8
	v_max3_f32 v8, v32, s40, v33
	v_max3_f32 v8, v8, v34, v35
	v_max3_f32 v8, v8, v36, v37
	v_max3_f32 v8, v8, v38, v39
	v_max3_f32 v8, v8, v40, v41
	v_max3_f32 v8, v8, v42, v43
	v_max3_f32 v8, v8, v45, v46
	v_max3_f32 v8, v8, v47, v44
	v_lshlrev_b32_e32 v196, 16, v9
	v_and_b32_e32 v197, 0xffff0000, v9
	v_mov_b32_e32 v9, v8
	s_nop 1
	v_permlane32_swap_b32_e32 v8, v9
	v_lshlrev_b32_e32 v64, 16, v0
	v_and_b32_e32 v65, 0xffff0000, v0
	v_lshlrev_b32_e32 v0, 16, v1
	v_and_b32_e32 v1, 0xffff0000, v1
	v_and_b32_e32 v67, 0xffff0000, v2
	v_lshlrev_b32_e32 v2, 16, v3
	v_and_b32_e32 v3, 0xffff0000, v3
	v_lshlrev_b32_e32 v68, 16, v4
	v_and_b32_e32 v69, 0xffff0000, v4
	v_lshlrev_b32_e32 v4, 16, v5
	v_and_b32_e32 v5, 0xffff0000, v5
	v_lshlrev_b32_e32 v70, 16, v6
	v_and_b32_e32 v71, 0xffff0000, v6
	v_lshlrev_b32_e32 v6, 16, v7
	v_and_b32_e32 v7, 0xffff0000, v7
	s_waitcnt vmcnt(7)
	v_lshlrev_b32_e32 v234, 16, v10
	v_and_b32_e32 v235, 0xffff0000, v10
	v_lshlrev_b32_e32 v236, 16, v11
	v_and_b32_e32 v237, 0xffff0000, v11
	s_waitcnt vmcnt(6)
	v_lshlrev_b32_e32 v238, 16, v12
	v_and_b32_e32 v239, 0xffff0000, v12
	v_lshlrev_b32_e32 v240, 16, v13
	v_and_b32_e32 v241, 0xffff0000, v13
	s_waitcnt vmcnt(5)
	v_lshlrev_b32_e32 v242, 16, v14
	v_and_b32_e32 v243, 0xffff0000, v14
	v_lshlrev_b32_e32 v244, 16, v15
	v_and_b32_e32 v245, 0xffff0000, v15
	global_load_dwordx4 v[230:233], v[246:247], off
	v_cmp_lt_i32_e64 s[72:73], s13, v169
	s_waitcnt vmcnt(5)
	v_max3_f32 v118, v75, v8, v9
	v_sub_f32_e32 v9, v32, v118
	v_exp_f32_e32 v223, v9
	v_sub_f32_e32 v9, v33, v118
	v_exp_f32_e32 v224, v9
	v_sub_f32_e32 v9, v34, v118
	v_exp_f32_e32 v219, v9
	v_sub_f32_e32 v9, v35, v118
	v_exp_f32_e32 v220, v9
	v_sub_f32_e32 v9, v36, v118
	v_exp_f32_e32 v221, v9
	v_sub_f32_e32 v9, v37, v118
	v_exp_f32_e32 v222, v9
	v_sub_f32_e32 v9, v38, v118
	v_exp_f32_e32 v217, v9
	v_sub_f32_e32 v9, v39, v118
	v_exp_f32_e32 v218, v9
	v_sub_f32_e32 v9, v40, v118
	v_sub_f32_e32 v8, v75, v118
	v_exp_f32_e32 v215, v9
	v_sub_f32_e32 v9, v41, v118
	v_exp_f32_e32 v216, v9
	v_sub_f32_e32 v9, v42, v118
	v_exp_f32_e32 v92, v8
	v_exp_f32_e32 v75, v9
	v_sub_f32_e32 v9, v43, v118
	v_exp_f32_e32 v97, v9
	v_sub_f32_e32 v9, v45, v118
	v_exp_f32_e32 v211, v9
	v_sub_f32_e32 v9, v46, v118
	v_sub_f32_e32 v8, v47, v118
	v_exp_f32_e32 v212, v9
	v_exp_f32_e32 v213, v8
	v_pk_mul_f32 v[14:15], v[6:7], v[92:93] op_sel_hi:[1,0]
	v_pk_mul_f32 v[12:13], v[70:71], v[92:93] op_sel_hi:[1,0]
	v_pk_mul_f32 v[10:11], v[4:5], v[92:93] op_sel_hi:[1,0]
	v_pk_mul_f32 v[8:9], v[68:69], v[92:93] op_sel_hi:[1,0]
	v_pk_mul_f32 v[6:7], v[2:3], v[92:93] op_sel_hi:[1,0]
	v_pk_mul_f32 v[4:5], v[66:67], v[92:93] op_sel_hi:[1,0]
	v_pk_mul_f32 v[2:3], v[0:1], v[92:93] op_sel_hi:[1,0]
	v_pk_mul_f32 v[0:1], v[64:65], v[92:93] op_sel_hi:[1,0]
	v_pk_mul_f32 v[38:39], v[92:93], v[236:237] op_sel_hi:[0,1]
	v_pk_mul_f32 v[36:37], v[92:93], v[234:235] op_sel_hi:[0,1]
	global_load_dwordx4 v[234:237], v[248:249], off
	global_load_dwordx4 v[68:71], v[246:247], off offset:512
	global_load_dwordx4 v[64:67], v[248:249], off offset:512
	v_cvt_pk_bf16_f32 v24, v223, v224
	v_cvt_pk_bf16_f32 v25, v219, v220
	v_cvt_pk_bf16_f32 v26, v221, v222
	v_cvt_pk_bf16_f32 v27, v217, v218
	v_pk_mul_f32 v[46:47], v[92:93], v[244:245] op_sel_hi:[0,1]
	v_pk_mul_f32 v[42:43], v[92:93], v[240:241] op_sel_hi:[0,1]
	s_waitcnt vmcnt(7)
	v_mfma_f32_32x32x16_bf16 v[0:15], v[16:19], v[24:27], v[0:15]
	v_sub_f32_e32 v16, v44, v118
	v_mul_f32_e64 v44, v92, v242
	v_mul_f32_e64 v45, v92, v243
	v_mul_f32_e64 v40, v92, v238
	v_mul_f32_e64 v41, v92, v239
	v_pk_mul_f32 v[34:35], v[92:93], v[196:197] op_sel_hi:[0,1]
	v_pk_mul_f32 v[32:33], v[92:93], v[120:121] op_sel_hi:[0,1]
	v_exp_f32_e32 v214, v16
	v_cvt_pk_bf16_f32 v16, v215, v216
	s_waitcnt vmcnt(6)
	v_mfma_f32_32x32x16_bf16 v[32:47], v[28:31], v[24:27], v[32:47]
	v_cvt_pk_bf16_f32 v17, v75, v97
	v_cvt_pk_bf16_f32 v18, v211, v212
	v_cvt_pk_bf16_f32 v19, v213, v214
	v_lshlrev_b64 v[120:121], 10, v[192:193]
	s_waitcnt vmcnt(5)
	v_mfma_f32_32x32x16_bf16 v[0:15], v[20:23], v[16:19], v[0:15]
	s_waitcnt vmcnt(4)
; DI unsigned pk2(float lo, float hi) { f32x2 v = {lo, hi}; bf16x2_t b = __builtin_convertvector(v, bf16x2_t); return __builtin_bit_cast(unsigned, b); }
; DI float swap_max(float m) { auto rr = __builtin_amdgcn_permlane32_swap(__float_as_uint(m), __float_as_uint(m), false, false); return fmaxf(__uint_as_float(rr[0]), __uint_as_float(rr[1])); }
; DI float ex2(float x) { return __builtin_amdgcn_exp2f(x); }
; #define MFMA32(a, b, c) __builtin_amdgcn_mfma_f32_32x32x16_bf16((a), (b), (c), 0, 0, 0)
; DI void dil_phase(int wv, const bf16_t* QK, const bf16_t* VTg, int rows, int nb, int S, int rr, int pat, bf16_t* OUT, float* LSE) {
;     ...
;         for (int kb = 0; kb < 5; ++kb) {
;             if (kb < 4) DIL_LOAD(kn, vn, kb + 1);
;             f32x16 sc;
; #pragma unroll
;             for (int i = 0; i < 16; ++i) sc[i] = 0.f;
; #pragma unroll
;             for (int ds = 0; ds < 4; ++ds) sc = MFMA32(kf[ds], qf[ds], sc);
;             float mx = -3.0e38f;
; #pragma unroll
;             for (int i = 0; i < 16; ++i) {
;                 const int kk = 32 * kb + 16 * (i >> 3) + 8 * hi + (i & 7), mk = i0 - 64 + kk, dd = kk - r;
;                 const bool ok = (mk >= 0) && (mk < Sr) && (dd >= 0) && (dd <= 128);
;                 const float v = ok ? sc[i] : -INFINITY; sc[i] = v; mx = fmaxf(mx, v);
;             }
;             mx = swap_max(mx);
;             const float mnew = fmaxf(mrun, mx), alpha = ex2(mrun - mnew);
;             float ps = 0.f;
; #pragma unroll
;             for (int i = 0; i < 16; ++i) { const float p = ex2(sc[i] - mnew); sc[i] = p; ps += p; }
;             lrun = lrun * alpha + ps; mrun = mnew;
; #pragma unroll
;             for (int cb = 0; cb < 2; ++cb) O[cb] = O[cb] * alpha;
;             u32x4 w0, w1;
;             w0.x = pk2(sc[0], sc[1]); w0.y = pk2(sc[2], sc[3]); w0.z = pk2(sc[4], sc[5]); w0.w = pk2(sc[6], sc[7]);
;             w1.x = pk2(sc[8], sc[9]); w1.y = pk2(sc[10], sc[11]); w1.z = pk2(sc[12], sc[13]); w1.w = pk2(sc[14], sc[15]);
;             const bf16x8 pf0 = __builtin_bit_cast(bf16x8, w0), pf1 = __builtin_bit_cast(bf16x8, w1);
; #pragma unroll
;             for (int cb = 0; cb < 2; ++cb) { O[cb] = MFMA32(vf[cb], pf0, O[cb]); O[cb] = MFMA32(vf[2 + cb], pf1, O[cb]); }
	v_mfma_f32_32x32x16_bf16 v[32:47], v[226:229], v[16:19], v[32:47]
	v_max3_f32 v16, v88, s40, v90
	v_max3_f32 v16, v16, v94, v96
	v_max3_f32 v16, v16, v98, v100
	v_max3_f32 v16, v16, v102, v104
	v_max3_f32 v16, v16, v110, v114
	v_max3_f32 v16, v16, v106, v108
	v_max3_f32 v16, v16, v112, v116
	v_max3_f32 v16, v16, v195, v194
	v_mov_b32_e32 v17, v16
	s_nop 1
	v_permlane32_swap_b32_e32 v16, v17
	v_max3_f32 v196, v118, v16, v17
	v_sub_f32_e32 v17, v88, v196
	v_exp_f32_e32 v225, v17
	v_sub_f32_e32 v17, v90, v196
	v_exp_f32_e32 v226, v17
	v_sub_f32_e32 v17, v94, v196
	v_sub_f32_e32 v16, v118, v196
	v_exp_f32_e32 v88, v17
	v_sub_f32_e32 v17, v96, v196
	v_exp_f32_e32 v90, v17
	v_sub_f32_e32 v17, v98, v196
	v_exp_f32_e32 v118, v16
	v_exp_f32_e32 v94, v17
	v_sub_f32_e32 v17, v100, v196
	v_exp_f32_e32 v96, v17
	v_sub_f32_e32 v17, v102, v196
	v_exp_f32_e32 v98, v17
	v_sub_f32_e32 v17, v104, v196
	v_sub_f32_e32 v16, v110, v196
	v_exp_f32_e32 v100, v17
	v_exp_f32_e32 v102, v16
	v_pk_mul_f32 v[16:17], v[0:1], v[118:119] op_sel_hi:[1,0]
	v_pk_mul_f32 v[0:1], v[32:33], v[118:119] op_sel_hi:[1,0]
	v_sub_f32_e32 v32, v106, v196
	v_exp_f32_e32 v106, v32
	v_sub_f32_e32 v32, v108, v196
	v_pk_mul_f32 v[24:25], v[8:9], v[118:119] op_sel_hi:[1,0]
	v_pk_mul_f32 v[8:9], v[40:41], v[118:119] op_sel_hi:[1,0]
	v_exp_f32_e32 v108, v32
	v_sub_f32_e32 v32, v112, v196
	v_or_b32_e32 v40, s33, v93
	v_exp_f32_e32 v110, v32
	v_sub_f32_e32 v32, v116, v196
	v_min_i32_e32 v192, s8, v40
	v_exp_f32_e32 v112, v32
	v_sub_f32_e32 v32, v195, v196
	v_lshlrev_b64 v[40:41], 14, v[192:193]
	v_sub_f32_e32 v104, v114, v196
	v_pk_mul_f32 v[30:31], v[14:15], v[118:119] op_sel_hi:[1,0]
	v_pk_mul_f32 v[28:29], v[12:13], v[118:119] op_sel_hi:[1,0]
	v_pk_mul_f32 v[26:27], v[10:11], v[118:119] op_sel_hi:[1,0]
	v_pk_mul_f32 v[22:23], v[6:7], v[118:119] op_sel_hi:[1,0]
	v_pk_mul_f32 v[20:21], v[4:5], v[118:119] op_sel_hi:[1,0]
	v_pk_mul_f32 v[18:19], v[2:3], v[118:119] op_sel_hi:[1,0]
	v_pk_mul_f32 v[14:15], v[46:47], v[118:119] op_sel_hi:[1,0]
	v_pk_mul_f32 v[12:13], v[44:45], v[118:119] op_sel_hi:[1,0]
	v_pk_mul_f32 v[10:11], v[42:43], v[118:119] op_sel_hi:[1,0]
	v_pk_mul_f32 v[6:7], v[38:39], v[118:119] op_sel_hi:[1,0]
	v_pk_mul_f32 v[4:5], v[36:37], v[118:119] op_sel_hi:[1,0]
	v_pk_mul_f32 v[2:3], v[34:35], v[118:119] op_sel_hi:[1,0]
	v_cvt_pk_bf16_f32 v36, v225, v226
	v_cvt_pk_bf16_f32 v37, v88, v90
	v_cvt_pk_bf16_f32 v38, v94, v96
	v_cvt_pk_bf16_f32 v39, v98, v100
	v_exp_f32_e32 v114, v32
	v_sub_f32_e32 v32, v194, v196
	v_lshl_add_u64 v[194:195], v[86:87], 0, v[40:41]
	global_load_dwordx4 v[40:43], v[194:195], off offset:3072
	global_load_dwordx4 v[238:241], v[194:195], off offset:3104
	global_load_dwordx4 v[242:245], v[194:195], off offset:3136
	global_load_dwordx4 v[246:249], v[194:195], off offset:3168
	s_waitcnt vmcnt(5)
	v_mfma_f32_32x32x16_bf16 v[0:15], v[68:71], v[36:39], v[0:15]
	v_exp_f32_e32 v104, v104
	v_exp_f32_e32 v116, v32
	v_cvt_pk_bf16_f32 v33, v106, v108
	v_cvt_pk_bf16_f32 v34, v110, v112
	v_cvt_pk_bf16_f32 v32, v102, v104
	v_cvt_pk_bf16_f32 v35, v114, v116
	v_mfma_f32_32x32x16_bf16 v[16:31], v[230:233], v[36:39], v[16:31]
	v_max3_f32 v36, v89, s40, v91
	v_max3_f32 v36, v36, v95, v77
	v_max3_f32 v36, v36, v99, v101
	v_max3_f32 v36, v36, v103, v105
	v_max3_f32 v36, v36, v107, v109
	v_max3_f32 v36, v36, v111, v113
	v_max3_f32 v36, v36, v115, v117
	s_waitcnt vmcnt(4)
	v_mfma_f32_32x32x16_bf16 v[0:15], v[64:67], v[32:35], v[0:15]
	s_nop 0
	v_max3_f32 v36, v36, v201, v200
	v_mov_b32_e32 v37, v36
	s_nop 1
	v_permlane32_swap_b32_e32 v36, v37
	v_max3_f32 v69, v196, v36, v37
	v_sub_f32_e32 v36, v196, v69
	v_mfma_f32_32x32x16_bf16 v[16:31], v[234:237], v[32:35], v[16:31]
	v_exp_f32_e32 v68, v36
	s_nop 1
	v_pk_mul_f32 v[14:15], v[14:15], v[68:69] op_sel_hi:[1,0]
	v_pk_mul_f32 v[12:13], v[12:13], v[68:69] op_sel_hi:[1,0]
	v_pk_mul_f32 v[10:11], v[10:11], v[68:69] op_sel_hi:[1,0]
	s_waitcnt vmcnt(3)
	v_mfma_f32_32x32x16_bf16 v[32:47], v[40:43], v[60:63], 0
	s_nop 3
	v_mul_f32_e64 v30, v30, v68
	v_mul_f32_e64 v31, v31, v68
	v_mul_f32_e64 v28, v28, v68
	v_mul_f32_e64 v29, v29, v68
	v_mul_f32_e64 v26, v26, v68
	v_mul_f32_e64 v27, v27, v68
	v_pk_mul_f32 v[24:25], v[24:25], v[68:69] op_sel_hi:[1,0]
	v_pk_mul_f32 v[22:23], v[22:23], v[68:69] op_sel_hi:[1,0]
	v_pk_mul_f32 v[20:21], v[20:21], v[68:69] op_sel_hi:[1,0]
	v_pk_mul_f32 v[18:19], v[18:19], v[68:69] op_sel_hi:[1,0]
	s_waitcnt vmcnt(2)
	v_mfma_f32_32x32x16_bf16 v[32:47], v[238:241], v[56:59], v[32:47]
	s_nop 0
	v_mul_f32_e64 v16, v16, v68
	v_mul_f32_e64 v17, v17, v68
	v_mul_f32_e64 v8, v8, v68
	v_mul_f32_e64 v9, v9, v68
	v_pk_mul_f32 v[6:7], v[6:7], v[68:69] op_sel_hi:[1,0]
	v_pk_mul_f32 v[4:5], v[4:5], v[68:69] op_sel_hi:[1,0]
	v_pk_mul_f32 v[2:3], v[2:3], v[68:69] op_sel_hi:[1,0]
	v_pk_mul_f32 v[0:1], v[0:1], v[68:69] op_sel_hi:[1,0]
	s_waitcnt vmcnt(1)
	v_mfma_f32_32x32x16_bf16 v[32:47], v[242:245], v[52:55], v[32:47]
	s_nop 0
	s_waitcnt vmcnt(0)
; DI unsigned pk2(float lo, float hi) { f32x2 v = {lo, hi}; bf16x2_t b = __builtin_convertvector(v, bf16x2_t); return __builtin_bit_cast(unsigned, b); }
; DI float swap_max(float m) { auto rr = __builtin_amdgcn_permlane32_swap(__float_as_uint(m), __float_as_uint(m), false, false); return fmaxf(__uint_as_float(rr[0]), __uint_as_float(rr[1])); }
; DI float ex2(float x) { return __builtin_amdgcn_exp2f(x); }
; #define MFMA32(a, b, c) __builtin_amdgcn_mfma_f32_32x32x16_bf16((a), (b), (c), 0, 0, 0)
; DI void dil_phase(int wv, const bf16_t* QK, const bf16_t* VTg, int rows, int nb, int S, int rr, int pat, bf16_t* OUT, float* LSE) {
;     ...
;         for (int kb = 0; kb < 5; ++kb) {
;             if (kb < 4) DIL_LOAD(kn, vn, kb + 1);
;             f32x16 sc;
; #pragma unroll
;             for (int i = 0; i < 16; ++i) sc[i] = 0.f;
; #pragma unroll
;             for (int ds = 0; ds < 4; ++ds) sc = MFMA32(kf[ds], qf[ds], sc);
;             float mx = -3.0e38f;
; #pragma unroll
;             for (int i = 0; i < 16; ++i) {
;                 const int kk = 32 * kb + 16 * (i >> 3) + 8 * hi + (i & 7), mk = i0 - 64 + kk, dd = kk - r;
;                 const bool ok = (mk >= 0) && (mk < Sr) && (dd >= 0) && (dd <= 128);
;                 const float v = ok ? sc[i] : -INFINITY; sc[i] = v; mx = fmaxf(mx, v);
;             }
;             mx = swap_max(mx);
;             const float mnew = fmaxf(mrun, mx), alpha = ex2(mrun - mnew);
;             float ps = 0.f;
; #pragma unroll
;             for (int i = 0; i < 16; ++i) { const float p = ex2(sc[i] - mnew); sc[i] = p; ps += p; }
;             lrun = lrun * alpha + ps; mrun = mnew;
; #pragma unroll
;             for (int cb = 0; cb < 2; ++cb) O[cb] = O[cb] * alpha;
;             u32x4 w0, w1;
;             w0.x = pk2(sc[0], sc[1]); w0.y = pk2(sc[2], sc[3]); w0.z = pk2(sc[4], sc[5]); w0.w = pk2(sc[6], sc[7]);
;             w1.x = pk2(sc[8], sc[9]); w1.y = pk2(sc[10], sc[11]); w1.z = pk2(sc[12], sc[13]); w1.w = pk2(sc[14], sc[15]);
;             const bf16x8 pf0 = __builtin_bit_cast(bf16x8, w0), pf1 = __builtin_bit_cast(bf16x8, w1);
; #pragma unroll
;             for (int cb = 0; cb < 2; ++cb) { O[cb] = MFMA32(vf[cb], pf0, O[cb]); O[cb] = MFMA32(vf[2 + cb], pf1, O[cb]); }
	v_mfma_f32_32x32x16_bf16 v[32:47], v[246:249], v[48:51], v[32:47]
	s_nop 11
	v_cndmask_b32_e64 v228, v250, v32, s[72:73]
	v_cmp_lt_i32_e64 s[72:73], s13, v170
	v_or_b32_e32 v32, s33, v72
	s_add_i32 s33, s12, 64
	v_cndmask_b32_e64 v229, v250, v33, s[72:73]
	v_cmp_lt_i32_e64 s[72:73], s13, v171
	v_lshrrev_b32_e32 v33, 3, v32
	v_cndmask_b32_e64 v248, v250, v40, s[74:75]
	v_cndmask_b32_e64 v230, v250, v34, s[72:73]
	v_cmp_lt_i32_e64 s[72:73], s13, v172
	v_cndmask_b32_e64 v247, v250, v41, s[76:77]
	v_cndmask_b32_e64 v246, v250, v42, s[78:79]
	v_cndmask_b32_e64 v231, v250, v35, s[72:73]
	v_cmp_lt_i32_e64 s[72:73], s13, v173
	v_cndmask_b32_e64 v245, v250, v43, s[80:81]
	v_cndmask_b32_e64 v244, v250, v44, s[82:83]
	v_cndmask_b32_e64 v232, v250, v36, s[72:73]
	v_cmp_lt_i32_e64 s[72:73], s13, v174
	v_cndmask_b32_e64 v243, v250, v45, s[84:85]
	v_cndmask_b32_e64 v235, v250, v46, s[86:87]
	v_cndmask_b32_e64 v233, v250, v37, s[72:73]
	v_cmp_lt_i32_e64 s[72:73], s13, v175
	v_cndmask_b32_e64 v227, v250, v47, s[88:89]
	v_cmp_lt_i32_e64 s[74:75], s13, v206
	v_cndmask_b32_e64 v234, v250, v38, s[72:73]
	v_cmp_lt_i32_e64 s[72:73], s13, v176
	s_and_b64 s[74:75], s[74:75], s[66:67]
	v_cmp_lt_i32_e64 s[76:77], s13, v207
	v_cndmask_b32_e64 v249, v250, v39, s[72:73]
	v_cmp_gt_u32_e64 s[72:73], s7, v32
	v_add_u32_e32 v32, s12, v145
	s_and_b64 s[76:77], s[76:77], s[68:69]
	v_cndmask_b32_e64 v192, 0, v33, s[72:73]
	v_lshrrev_b32_e32 v33, 3, v32
	v_cmp_gt_u32_e64 s[72:73], s7, v32
	v_lshlrev_b64 v[64:65], 10, v[192:193]
	v_or_b32_e32 v32, s33, v93
	v_cndmask_b32_e64 v192, 0, v33, s[72:73]
	v_lshlrev_b64 v[66:67], 10, v[192:193]
	v_min_i32_e32 v192, s8, v32
	v_lshlrev_b64 v[32:33], 14, v[192:193]
	v_lshl_add_u64 v[70:71], v[86:87], 0, v[32:33]
	global_load_dwordx4 v[32:35], v[70:71], off offset:3072
	global_load_dwordx4 v[194:197], v[70:71], off offset:3104
	global_load_dwordx4 v[236:239], v[70:71], off offset:3136
	s_waitcnt vmcnt(2)
	v_mfma_f32_32x32x16_bf16 v[32:47], v[32:35], v[60:63], 0
	global_load_dwordx4 v[60:63], v[70:71], off offset:3168
	v_cmp_lt_i32_e64 s[72:73], s13, v185
	s_and_b64 s[72:73], s[72:73], s[42:43]
	v_cmp_lt_i32_e64 s[78:79], s13, v208
	s_and_b64 s[78:79], s[78:79], s[70:71]
	s_waitcnt vmcnt(2)
	v_mfma_f32_32x32x16_bf16 v[32:47], v[194:197], v[56:59], v[32:47]
	s_nop 0
	s_nop 0
	s_waitcnt vmcnt(1)
	v_mfma_f32_32x32x16_bf16 v[32:47], v[236:239], v[52:55], v[32:47]
	s_nop 0
	s_waitcnt vmcnt(0)
	v_mfma_f32_32x32x16_bf16 v[32:47], v[60:63], v[48:51], v[32:47]
	v_lshl_add_u64 v[62:63], v[78:79], 0, v[64:65]
	s_nop 11
	v_cndmask_b32_e64 v49, v250, v32, s[72:73]
	v_cmp_lt_i32_e64 s[72:73], s13, v186
	s_and_b64 s[72:73], s[72:73], s[44:45]
	v_or_b32_e32 v32, s33, v72
	v_cndmask_b32_e64 v51, v250, v33, s[72:73]
	v_cmp_lt_i32_e64 s[72:73], s13, v187
	s_and_b64 s[72:73], s[72:73], s[46:47]
	v_lshrrev_b32_e32 v33, 3, v32
	v_cndmask_b32_e64 v53, v250, v34, s[72:73]
	v_cmp_lt_i32_e64 s[72:73], s13, v188
	s_and_b64 s[72:73], s[72:73], s[48:49]
	v_cndmask_b32_e64 v195, v250, v45, s[74:75]
	v_cndmask_b32_e64 v55, v250, v35, s[72:73]
	v_cmp_lt_i32_e64 s[72:73], s13, v189
	s_and_b64 s[72:73], s[72:73], s[50:51]
	v_cndmask_b32_e64 v194, v250, v46, s[76:77]
	v_cndmask_b32_e64 v57, v250, v36, s[72:73]
	v_cmp_lt_i32_e64 s[72:73], s13, v190
	s_and_b64 s[82:83], s[72:73], s[52:53]
	v_cmp_lt_i32_e64 s[72:73], s13, v191
	s_and_b64 s[84:85], s[72:73], s[54:55]
	v_cmp_lt_i32_e64 s[72:73], s13, v198
	s_and_b64 s[86:87], s[72:73], s[4:5]
	v_cmp_lt_i32_e64 s[72:73], s13, v199
	s_and_b64 s[88:89], s[72:73], s[56:57]
	v_cmp_lt_i32_e64 s[72:73], s13, v202
	s_and_b64 s[90:91], s[72:73], s[58:59]
	v_cmp_lt_i32_e64 s[72:73], s13, v203
	s_and_b64 s[92:93], s[72:73], s[60:61]
	v_cmp_lt_i32_e64 s[72:73], s13, v204
	s_and_b64 s[80:81], s[72:73], s[62:63]
	v_cmp_lt_i32_e64 s[72:73], s13, v205
	s_and_b64 s[72:73], s[72:73], s[64:65]
	v_cndmask_b32_e64 v251, v250, v40, s[88:89]
	v_cndmask_b32_e64 v196, v250, v44, s[72:73]
	v_cmp_gt_u32_e64 s[72:73], s7, v32
	v_add_u32_e32 v32, s12, v210
	v_cndmask_b32_e64 v252, v250, v41, s[90:91]
	v_cndmask_b32_e64 v192, 0, v33, s[72:73]
	v_lshrrev_b32_e32 v33, 3, v32
	v_cmp_gt_u32_e64 s[72:73], s7, v32
	v_add_f32_e32 v32, 0, v223
	v_lshl_add_u64 v[40:41], v[78:79], 0, v[84:85]
	v_lshlrev_b64 v[70:71], 10, v[192:193]
	v_cndmask_b32_e64 v192, 0, v33, s[72:73]
	v_add_f32_e32 v36, v224, v32
	global_load_dwordx4 v[32:35], v[40:41], off
	v_add_f32_e32 v36, v219, v36
	v_add_f32_e32 v36, v220, v36
	v_add_f32_e32 v36, v221, v36
	v_cndmask_b32_e64 v241, v250, v42, s[92:93]
	v_add_f32_e32 v42, v222, v36
	v_lshl_add_u64 v[44:45], v[78:79], 0, v[120:121]
	v_add_f32_e32 v42, v217, v42
	v_cndmask_b32_e64 v59, v250, v37, s[82:83]
	v_cndmask_b32_e64 v61, v250, v38, s[84:85]
	v_cndmask_b32_e64 v87, v250, v39, s[86:87]
	v_cndmask_b32_e64 v242, v250, v43, s[80:81]
	global_load_dwordx4 v[36:39], v[44:45], off
	v_add_f32_e32 v46, v218, v42
	global_load_dwordx4 v[40:43], v[40:41], off offset:512
	v_add_f32_e32 v46, v215, v46
	v_cndmask_b32_e64 v250, v250, v47, s[78:79]
	v_add_f32_e32 v48, v216, v46
	global_load_dwordx4 v[44:47], v[44:45], off offset:512
	v_add_f32_e32 v48, v75, v48
	v_add_f32_e32 v48, v97, v48
	v_add_f32_e32 v48, v211, v48
	v_add_f32_e32 v48, v212, v48
	v_add_f32_e32 v48, v213, v48
	v_add_f32_e32 v48, v214, v48
	global_load_dwordx4 v[212:215], v[62:63], off
	global_load_dwordx4 v[216:219], v[62:63], off offset:512
	v_fmac_f32_e32 v48, v119, v92
	v_mul_f32_e32 v120, v48, v118
	v_add_f32_e32 v48, 0, v225
	v_add_f32_e32 v84, v226, v48
	v_sub_f32_e32 v48, v89, v69
	v_exp_f32_e32 v89, v48
	v_sub_f32_e32 v48, v91, v69
	v_exp_f32_e32 v91, v48
	v_sub_f32_e32 v48, v95, v69
	v_exp_f32_e32 v95, v48
	v_sub_f32_e32 v48, v77, v69
	v_exp_f32_e32 v97, v48
	v_sub_f32_e32 v48, v99, v69
	v_exp_f32_e32 v99, v48
	v_sub_f32_e32 v48, v101, v69
	v_exp_f32_e32 v101, v48
	v_sub_f32_e32 v48, v103, v69
	v_exp_f32_e32 v103, v48
	v_sub_f32_e32 v48, v105, v69
	v_exp_f32_e32 v105, v48
	v_sub_f32_e32 v48, v107, v69
	v_exp_f32_e32 v107, v48
	v_sub_f32_e32 v48, v109, v69
	v_lshl_add_u64 v[62:63], v[78:79], 0, v[66:67]
	v_exp_f32_e32 v109, v48
	v_sub_f32_e32 v48, v111, v69
	global_load_dwordx4 v[220:223], v[62:63], off
	global_load_dwordx4 v[236:239], v[62:63], off offset:512
	v_exp_f32_e32 v111, v48
	v_sub_f32_e32 v48, v113, v69
	v_cvt_pk_bf16_f32 v62, v89, v91
	v_cvt_pk_bf16_f32 v63, v95, v97
	v_cvt_pk_bf16_f32 v64, v99, v101
	v_cvt_pk_bf16_f32 v65, v103, v105
	v_exp_f32_e32 v113, v48
	v_sub_f32_e32 v48, v115, v69
	s_waitcnt vmcnt(7)
; DI unsigned pk2(float lo, float hi) { f32x2 v = {lo, hi}; bf16x2_t b = __builtin_convertvector(v, bf16x2_t); return __builtin_bit_cast(unsigned, b); }
; DI float swap_max(float m) { auto rr = __builtin_amdgcn_permlane32_swap(__float_as_uint(m), __float_as_uint(m), false, false); return fmaxf(__uint_as_float(rr[0]), __uint_as_float(rr[1])); }
; DI float ex2(float x) { return __builtin_amdgcn_exp2f(x); }
; #define MFMA32(a, b, c) __builtin_amdgcn_mfma_f32_32x32x16_bf16((a), (b), (c), 0, 0, 0)
; DI void dil_phase(int wv, const bf16_t* QK, const bf16_t* VTg, int rows, int nb, int S, int rr, int pat, bf16_t* OUT, float* LSE) {
;     ...
;             mx = swap_max(mx);
;             const float mnew = fmaxf(mrun, mx), alpha = ex2(mrun - mnew);
;             float ps = 0.f;
; #pragma unroll
;             for (int i = 0; i < 16; ++i) { const float p = ex2(sc[i] - mnew); sc[i] = p; ps += p; }
;             lrun = lrun * alpha + ps; mrun = mnew;
; #pragma unroll
;             for (int cb = 0; cb < 2; ++cb) O[cb] = O[cb] * alpha;
;             u32x4 w0, w1;
;             w0.x = pk2(sc[0], sc[1]); w0.y = pk2(sc[2], sc[3]); w0.z = pk2(sc[4], sc[5]); w0.w = pk2(sc[6], sc[7]);
;             w1.x = pk2(sc[8], sc[9]); w1.y = pk2(sc[10], sc[11]); w1.z = pk2(sc[12], sc[13]); w1.w = pk2(sc[14], sc[15]);
;             const bf16x8 pf0 = __builtin_bit_cast(bf16x8, w0), pf1 = __builtin_bit_cast(bf16x8, w1);
; #pragma unroll
;             for (int cb = 0; cb < 2; ++cb) { O[cb] = MFMA32(vf[cb], pf0, O[cb]); O[cb] = MFMA32(vf[2 + cb], pf1, O[cb]); }
	v_mfma_f32_32x32x16_bf16 v[16:31], v[32:35], v[62:65], v[16:31]
	v_exp_f32_e32 v115, v48
	v_sub_f32_e32 v48, v117, v69
	v_exp_f32_e32 v117, v48
	v_sub_f32_e32 v48, v201, v69
	v_sub_f32_e32 v32, v200, v69
	v_exp_f32_e32 v121, v48
	v_exp_f32_e32 v67, v32
	v_mov_b32_e32 v85, v193
	v_cvt_pk_bf16_f32 v32, v107, v109
	v_cvt_pk_bf16_f32 v33, v111, v113
	v_cvt_pk_bf16_f32 v34, v115, v117
	v_cvt_pk_bf16_f32 v35, v121, v67
	s_waitcnt vmcnt(5)
	v_mfma_f32_32x32x16_bf16 v[0:15], v[40:43], v[62:65], v[0:15]
	v_max3_f32 v40, v228, s40, v229
	v_max3_f32 v40, v40, v230, v231
	v_max3_f32 v40, v40, v232, v233
	v_max3_f32 v40, v40, v234, v249
	v_max3_f32 v40, v40, v248, v247
	v_max3_f32 v40, v40, v246, v245
	v_max3_f32 v40, v40, v244, v243
	v_mfma_f32_32x32x16_bf16 v[16:31], v[36:39], v[32:35], v[16:31]
	v_add_f32_e64 v36, v88, v84
	v_add_f32_e64 v37, v89, v85
	v_max3_f32 v40, v40, v235, v227
	v_add_f32_e64 v36, v90, v36
	v_add_f32_e64 v37, v91, v37
	v_mov_b32_e32 v41, v40
	v_pk_add_f32 v[36:37], v[94:95], v[36:37]
	s_nop 0
	v_permlane32_swap_b32_e32 v40, v41
	v_pk_add_f32 v[36:37], v[96:97], v[36:37]
	v_max3_f32 v63, v69, v40, v41
	v_pk_add_f32 v[36:37], v[98:99], v[36:37]
	v_sub_f32_e32 v41, v228, v63
	v_pk_add_f32 v[36:37], v[100:101], v[36:37]
	v_exp_f32_e32 v65, v41
	v_pk_add_f32 v[36:37], v[102:103], v[36:37]
	v_sub_f32_e32 v41, v229, v63
	v_pk_add_f32 v[36:37], v[104:105], v[36:37]
	v_sub_f32_e32 v40, v69, v63
	v_pk_add_f32 v[36:37], v[106:107], v[36:37]
	v_exp_f32_e32 v69, v41
	v_pk_add_f32 v[36:37], v[108:109], v[36:37]
	v_sub_f32_e32 v41, v230, v63
	v_pk_add_f32 v[36:37], v[110:111], v[36:37]
	v_exp_f32_e32 v84, v41
	v_pk_add_f32 v[36:37], v[112:113], v[36:37]
	v_sub_f32_e32 v41, v231, v63
	v_pk_add_f32 v[36:37], v[114:115], v[36:37]
	s_waitcnt vmcnt(4)
	v_mfma_f32_32x32x16_bf16 v[0:15], v[44:47], v[32:35], v[0:15]
	v_add_f32_e64 v94, v116, v36
	v_add_f32_e64 v95, v117, v37
	v_lshlrev_b64 v[36:37], 10, v[192:193]
	v_lshl_add_u64 v[32:33], v[78:79], 0, v[70:71]
	v_lshl_add_u64 v[96:97], v[78:79], 0, v[36:37]
	v_exp_f32_e32 v78, v41
	v_sub_f32_e32 v41, v232, v63
	global_load_dwordx4 v[44:47], v[32:33], off
	s_nop 0
	global_load_dwordx4 v[32:35], v[32:33], off offset:512
	v_exp_f32_e32 v70, v41
	v_sub_f32_e32 v41, v233, v63
	v_exp_f32_e32 v66, v41
	v_sub_f32_e32 v41, v234, v63
	v_exp_f32_e32 v64, v41
	v_sub_f32_e32 v41, v249, v63
	v_exp_f32_e32 v62, v41
	v_sub_f32_e32 v41, v248, v63
	v_exp_f32_e32 v60, v41
	v_sub_f32_e32 v41, v247, v63
	v_exp_f32_e32 v58, v41
	v_sub_f32_e32 v41, v246, v63
	v_exp_f32_e32 v92, v40
	v_exp_f32_e32 v56, v41
	v_sub_f32_e32 v41, v245, v63
	v_exp_f32_e32 v54, v41
	v_sub_f32_e32 v41, v244, v63
	v_exp_f32_e32 v52, v41
	v_sub_f32_e32 v41, v243, v63
	v_sub_f32_e32 v40, v235, v63
	v_exp_f32_e32 v50, v41
	v_exp_f32_e32 v48, v40
	v_pk_mul_f32 v[30:31], v[30:31], v[92:93] op_sel_hi:[1,0]
	v_pk_mul_f32 v[28:29], v[28:29], v[92:93] op_sel_hi:[1,0]
	v_pk_mul_f32 v[26:27], v[26:27], v[92:93] op_sel_hi:[1,0]
	v_pk_mul_f32 v[24:25], v[24:25], v[92:93] op_sel_hi:[1,0]
	v_pk_mul_f32 v[22:23], v[22:23], v[92:93] op_sel_hi:[1,0]
	v_pk_mul_f32 v[20:21], v[20:21], v[92:93] op_sel_hi:[1,0]
	v_pk_mul_f32 v[18:19], v[18:19], v[92:93] op_sel_hi:[1,0]
	v_pk_mul_f32 v[16:17], v[16:17], v[92:93] op_sel_hi:[1,0]
	v_cvt_pk_bf16_f32 v40, v65, v69
	v_cvt_pk_bf16_f32 v41, v84, v78
	v_cvt_pk_bf16_f32 v42, v70, v66
	v_cvt_pk_bf16_f32 v43, v64, v62
	v_pk_mul_f32 v[14:15], v[14:15], v[92:93] op_sel_hi:[1,0]
	v_pk_mul_f32 v[12:13], v[12:13], v[92:93] op_sel_hi:[1,0]
	v_pk_mul_f32 v[10:11], v[10:11], v[92:93] op_sel_hi:[1,0]
	v_pk_mul_f32 v[8:9], v[8:9], v[92:93] op_sel_hi:[1,0]
	v_pk_mul_f32 v[6:7], v[6:7], v[92:93] op_sel_hi:[1,0]
	v_pk_mul_f32 v[4:5], v[4:5], v[92:93] op_sel_hi:[1,0]
	v_pk_mul_f32 v[2:3], v[2:3], v[92:93] op_sel_hi:[1,0]
	v_pk_mul_f32 v[0:1], v[0:1], v[92:93] op_sel_hi:[1,0]
	s_waitcnt vmcnt(5)
	v_mfma_f32_32x32x16_bf16 v[16:31], v[212:215], v[40:43], v[16:31]
	global_load_dwordx4 v[36:39], v[96:97], off
	v_add_f32_e32 v65, 0, v65
	v_add_f32_e32 v192, v69, v65
	v_max3_f32 v65, v49, s40, v51
	v_max3_f32 v65, v65, v53, v55
	v_max3_f32 v65, v65, v57, v59
	v_max3_f32 v65, v65, v61, v87
	s_waitcnt vmcnt(5)
	v_mfma_f32_32x32x16_bf16 v[0:15], v[216:219], v[40:43], v[0:15]
	v_add_f32_e64 v40, v120, v94
	v_add_f32_e64 v41, v121, v95
	v_max3_f32 v65, v65, v251, v252
	v_add_f32_e32 v67, v41, v67
	v_fmac_f32_e32 v67, v40, v68
	global_load_dwordx4 v[40:43], v[96:97], off offset:512
	v_max3_f32 v65, v65, v241, v242
	v_max3_f32 v65, v65, v196, v195
	v_max3_f32 v65, v65, v194, v250
	v_mul_f32_e32 v68, v67, v92
	v_mov_b32_e32 v67, v65
	v_sub_f32_e32 v71, v227, v63
	s_nop 0
	v_permlane32_swap_b32_e32 v65, v67
	v_exp_f32_e32 v86, v71
	v_max3_f32 v75, v63, v65, v67
	v_sub_f32_e32 v49, v49, v75
	v_exp_f32_e32 v85, v49
	v_sub_f32_e32 v49, v51, v75
	v_exp_f32_e32 v79, v49
	v_sub_f32_e32 v49, v53, v75
	v_cvt_pk_bf16_f32 v88, v60, v58
	v_cvt_pk_bf16_f32 v89, v56, v54
	v_cvt_pk_bf16_f32 v90, v52, v50
	v_cvt_pk_bf16_f32 v91, v48, v86
	v_exp_f32_e32 v71, v49
	v_sub_f32_e32 v49, v55, v75
	s_waitcnt vmcnt(4)
; #define GAS __attribute__((address_space(1)))
; DI unsigned pk2(float lo, float hi) { f32x2 v = {lo, hi}; bf16x2_t b = __builtin_convertvector(v, bf16x2_t); return __builtin_bit_cast(unsigned, b); }
; DI float swap_max(float m) { auto rr = __builtin_amdgcn_permlane32_swap(__float_as_uint(m), __float_as_uint(m), false, false); return fmaxf(__uint_as_float(rr[0]), __uint_as_float(rr[1])); }
; DI float swap_sum(float m) { auto rr = __builtin_amdgcn_permlane32_swap(__float_as_uint(m), __float_as_uint(m), false, false); return __uint_as_float(rr[0]) + __uint_as_float(rr[1]); }
; DI float ex2(float x) { return __builtin_amdgcn_exp2f(x); }
; #define MFMA32(a, b, c) __builtin_amdgcn_mfma_f32_32x32x16_bf16((a), (b), (c), 0, 0, 0)
; DI void dil_phase(int wv, const bf16_t* QK, const bf16_t* VTg, int rows, int nb, int S, int rr, int pat, bf16_t* OUT, float* LSE) {
;     ...
;             mx = swap_max(mx);
;             const float mnew = fmaxf(mrun, mx), alpha = ex2(mrun - mnew);
;             float ps = 0.f;
; #pragma unroll
;             for (int i = 0; i < 16; ++i) { const float p = ex2(sc[i] - mnew); sc[i] = p; ps += p; }
;             lrun = lrun * alpha + ps; mrun = mnew;
; #pragma unroll
;             for (int cb = 0; cb < 2; ++cb) O[cb] = O[cb] * alpha;
;             u32x4 w0, w1;
;             w0.x = pk2(sc[0], sc[1]); w0.y = pk2(sc[2], sc[3]); w0.z = pk2(sc[4], sc[5]); w0.w = pk2(sc[6], sc[7]);
;             w1.x = pk2(sc[8], sc[9]); w1.y = pk2(sc[10], sc[11]); w1.z = pk2(sc[12], sc[13]); w1.w = pk2(sc[14], sc[15]);
;             const bf16x8 pf0 = __builtin_bit_cast(bf16x8, w0), pf1 = __builtin_bit_cast(bf16x8, w1);
; #pragma unroll
;             for (int cb = 0; cb < 2; ++cb) { O[cb] = MFMA32(vf[cb], pf0, O[cb]); O[cb] = MFMA32(vf[2 + cb], pf1, O[cb]); }
;             if (kb < 4) {
; #pragma unroll
;                 for (int i = 0; i < 4; ++i) { kf[i] = kn[i]; vf[i] = vn[i]; }
;             }
;         }
;     ...
;         const float lt = swap_sum(lrun), inv = __builtin_amdgcn_rcpf(lt);
; #pragma unroll
;         for (int cb = 0; cb < 2; ++cb)
; #pragma unroll
;             for (int j4 = 0; j4 < 4; ++j4) { u32x2 w; w.x = pk2(O[cb][4 * j4] * inv, O[cb][4 * j4 + 1] * inv); w.y = pk2(O[cb][4 * j4 + 2] * inv, O[cb][4 * j4 + 3] * inv); *(GAS u32x2*)(orow + 32 * cb + 8 * j4) = w; }
;         if (hi == 0) *lsep = mrun + __log2f(lt);
	v_mfma_f32_32x32x16_bf16 v[0:15], v[236:239], v[88:91], v[0:15]
	v_exp_f32_e32 v67, v49
	v_sub_f32_e32 v49, v57, v75
	v_exp_f32_e32 v65, v49
	v_sub_f32_e32 v49, v59, v75
	v_sub_f32_e32 v69, v63, v75
	v_exp_f32_e32 v63, v49
	v_sub_f32_e32 v49, v61, v75
	v_exp_f32_e32 v61, v49
	v_sub_f32_e32 v49, v87, v75
	v_exp_f32_e32 v59, v49
	v_exp_f32_e32 v92, v69
	v_mfma_f32_32x32x16_bf16 v[16:31], v[220:223], v[88:91], v[16:31]
	v_cvt_pk_bf16_f32 v88, v85, v79
	v_cvt_pk_bf16_f32 v89, v71, v67
	v_cvt_pk_bf16_f32 v90, v65, v63
	v_cvt_pk_bf16_f32 v91, v61, v59
	v_mul_f32_e64 v14, v14, v92
	v_mul_f32_e64 v15, v15, v92
	v_pk_mul_f32 v[12:13], v[12:13], v[92:93] op_sel_hi:[1,0]
	v_pk_mul_f32 v[10:11], v[10:11], v[92:93] op_sel_hi:[1,0]
	v_pk_mul_f32 v[8:9], v[8:9], v[92:93] op_sel_hi:[1,0]
	v_pk_mul_f32 v[6:7], v[6:7], v[92:93] op_sel_hi:[1,0]
	v_pk_mul_f32 v[4:5], v[4:5], v[92:93] op_sel_hi:[1,0]
	v_pk_mul_f32 v[2:3], v[2:3], v[92:93] op_sel_hi:[1,0]
	v_pk_mul_f32 v[0:1], v[0:1], v[92:93] op_sel_hi:[1,0]
	v_sub_f32_e32 v49, v251, v75
	v_exp_f32_e32 v57, v49
	s_waitcnt vmcnt(2)
	v_mfma_f32_32x32x16_bf16 v[0:15], v[32:35], v[88:91], v[0:15]
	v_add_f32_e64 v32, v84, v192
	v_add_f32_e64 v33, v85, v193
	v_sub_f32_e32 v49, v252, v75
	v_add_f32_e64 v32, v78, v32
	v_add_f32_e64 v33, v79, v33
	v_exp_f32_e32 v55, v49
	v_pk_add_f32 v[32:33], v[70:71], v[32:33]
	v_sub_f32_e32 v49, v241, v75
	v_pk_add_f32 v[32:33], v[66:67], v[32:33]
	v_exp_f32_e32 v53, v49
	v_pk_add_f32 v[32:33], v[64:65], v[32:33]
	v_sub_f32_e32 v49, v242, v75
	v_pk_add_f32 v[32:33], v[62:63], v[32:33]
	v_exp_f32_e32 v51, v49
	v_pk_add_f32 v[32:33], v[60:61], v[32:33]
	v_sub_f32_e32 v49, v196, v75
	v_pk_mul_f32 v[30:31], v[30:31], v[92:93] op_sel_hi:[1,0]
	v_pk_mul_f32 v[28:29], v[28:29], v[92:93] op_sel_hi:[1,0]
	v_pk_mul_f32 v[26:27], v[26:27], v[92:93] op_sel_hi:[1,0]
	v_pk_mul_f32 v[24:25], v[24:25], v[92:93] op_sel_hi:[1,0]
	v_pk_mul_f32 v[22:23], v[22:23], v[92:93] op_sel_hi:[1,0]
	v_pk_mul_f32 v[20:21], v[20:21], v[92:93] op_sel_hi:[1,0]
	v_pk_mul_f32 v[18:19], v[18:19], v[92:93] op_sel_hi:[1,0]
	v_pk_mul_f32 v[16:17], v[16:17], v[92:93] op_sel_hi:[1,0]
	v_pk_add_f32 v[32:33], v[58:59], v[32:33]
	v_exp_f32_e32 v49, v49
	v_sub_f32_e32 v77, v195, v75
	v_mfma_f32_32x32x16_bf16 v[16:31], v[44:47], v[88:91], v[16:31]
	v_add_f32_e64 v32, v56, v32
	v_add_f32_e64 v33, v57, v33
	v_exp_f32_e32 v87, v77
	v_sub_f32_e32 v69, v194, v75
	v_pk_add_f32 v[32:33], v[54:55], v[32:33]
	v_exp_f32_e32 v69, v69
	v_sub_f32_e32 v44, v250, v75
	v_pk_add_f32 v[32:33], v[52:53], v[32:33]
	v_exp_f32_e32 v77, v44
	v_pk_add_f32 v[32:33], v[50:51], v[32:33]
	v_cvt_pk_bf16_f32 v44, v57, v55
	v_pk_add_f32 v[32:33], v[48:49], v[32:33]
	v_cvt_pk_bf16_f32 v45, v53, v51
	v_pk_add_f32 v[32:33], v[86:87], v[32:33]
	v_cvt_pk_bf16_f32 v46, v49, v87
	v_pk_add_f32 v[32:33], v[68:69], v[32:33]
	v_cvt_pk_bf16_f32 v47, v69, v77
	v_add_f32_e32 v33, v77, v33
	v_fmac_f32_e32 v33, v92, v32
	s_waitcnt vmcnt(1)
	v_mfma_f32_32x32x16_bf16 v[16:31], v[36:39], v[44:47], v[16:31]
	v_mov_b32_e32 v32, v33
	s_nop 1
	v_permlane32_swap_b32_e32 v33, v32
	v_add_f32_e32 v32, v33, v32
	v_rcp_f32_e32 v34, v32
	s_mov_b32 s82, 0xff61b1e6
	s_nop 4
	v_pk_mul_f32 v[16:17], v[16:17], v[34:35] op_sel_hi:[1,0]
	s_waitcnt vmcnt(0)
	v_mfma_f32_32x32x16_bf16 v[0:15], v[40:43], v[44:47], v[0:15]
	v_mul_f32_e64 v18, v18, v34
	v_mul_f32_e64 v19, v19, v34
	v_cvt_pk_bf16_f32 v16, v16, v17
	v_cvt_pk_bf16_f32 v17, v18, v19
	global_store_dwordx2 v[80:81], v[16:17], off offset:1024
	v_pk_mul_f32 v[16:17], v[20:21], v[34:35] op_sel_hi:[1,0]
	v_pk_mul_f32 v[18:19], v[22:23], v[34:35] op_sel_hi:[1,0]
	v_cvt_pk_bf16_f32 v16, v16, v17
	s_nop 3
	v_pk_mul_f32 v[0:1], v[0:1], v[34:35] op_sel_hi:[1,0]
	v_pk_mul_f32 v[2:3], v[2:3], v[34:35] op_sel_hi:[1,0]
	v_cvt_pk_bf16_f32 v0, v0, v1
	v_cvt_pk_bf16_f32 v1, v2, v3
	global_store_dwordx2 v[80:81], v[0:1], off offset:1088
	v_pk_mul_f32 v[0:1], v[4:5], v[34:35] op_sel_hi:[1,0]
	v_pk_mul_f32 v[2:3], v[6:7], v[34:35] op_sel_hi:[1,0]
	v_cvt_pk_bf16_f32 v17, v18, v19
	v_cvt_pk_bf16_f32 v0, v0, v1
	v_cvt_pk_bf16_f32 v1, v2, v3
	global_store_dwordx2 v[80:81], v[16:17], off offset:1040
	v_pk_mul_f32 v[16:17], v[24:25], v[34:35] op_sel_hi:[1,0]
	v_pk_mul_f32 v[18:19], v[26:27], v[34:35] op_sel_hi:[1,0]
	global_store_dwordx2 v[80:81], v[0:1], off offset:1104
	v_pk_mul_f32 v[0:1], v[8:9], v[34:35] op_sel_hi:[1,0]
	v_pk_mul_f32 v[2:3], v[10:11], v[34:35] op_sel_hi:[1,0]
	v_cvt_pk_bf16_f32 v16, v16, v17
	v_cvt_pk_bf16_f32 v17, v18, v19
	v_cvt_pk_bf16_f32 v0, v0, v1
	v_cvt_pk_bf16_f32 v1, v2, v3
	global_store_dwordx2 v[80:81], v[16:17], off offset:1056
	v_pk_mul_f32 v[16:17], v[28:29], v[34:35] op_sel_hi:[1,0]
	v_pk_mul_f32 v[18:19], v[30:31], v[34:35] op_sel_hi:[1,0]
	global_store_dwordx2 v[80:81], v[0:1], off offset:1120
	v_pk_mul_f32 v[0:1], v[12:13], v[34:35] op_sel_hi:[1,0]
	v_pk_mul_f32 v[2:3], v[14:15], v[34:35] op_sel_hi:[1,0]
	v_cvt_pk_bf16_f32 v16, v16, v17
	v_cvt_pk_bf16_f32 v17, v18, v19
	v_cvt_pk_bf16_f32 v0, v0, v1
	v_cvt_pk_bf16_f32 v1, v2, v3
	global_store_dwordx2 v[80:81], v[16:17], off offset:1072
	global_store_dwordx2 v[80:81], v[0:1], off offset:1136
	s_and_saveexec_b64 s[72:73], vcc
	s_cbranch_execz .LBB0_354
	v_log_f32_e32 v0, v32
	s_nop 0
	v_add_f32_e32 v0, v75, v0
	global_store_dword v[82:83], v0, off
	s_branch .LBB0_354

; #define GAS __attribute__((address_space(1)))
; DI float bf_lo(unsigned u) { return __uint_as_float(u << 16); }
; DI float bf_hi(unsigned u) { return __uint_as_float(u & 0xffff0000u); }
; DI void dil_phase(int wv, const bf16_t* QK, const bf16_t* VTg, int rows, int nb, int S, int rr, int pat, bf16_t* OUT, float* LSE) {
;     ...
;     for (int k = lw; k < upx; k += lstride) {
;         const int wu = xcd * upx + k;
;         const int inner = wu & (per_sh - 1), sh = wu >> __builtin_ctz(per_sh), head = sh & 7, seq = sh >> 3;
;         const int cls = inner >> __builtin_ctz(ublk), i0 = (inner & (ublk - 1)) * 32;
;         const size_t seq0 = (size_t)seq * S;
;         const int qtok = cls + rr * (i0 + r);
;         const bf16_t* qp = QK + (seq0 + qtok) * 2048 + 1024 + head * 64 + 8 * hi;
;         const bf16_t* kbase = QK + (seq0 + cls) * 2048 + 1536 + head * 64 + 8 * hi;
;         const bf16_t* vbase = VTg + (size_t)head * rows * 64 + ((seq0 + (size_t)cls * Sr) >> 3) * 512 + r * 8;
;         bf16_t* orow = OUT + (seq0 + qtok) * 1024 + 512 + head * 64 + 4 * hi;
;         GAS float* lsep = (GAS float*)(LSE + (seq0 + qtok) * 8 + head);
;         bf16x8 qf[4];
; #pragma unroll
;         for (int ds = 0; ds < 4; ++ds) qf[ds] = *(const GAS bf16x8*)(qp + 16 * ds);
;         bf16x8 kf[4], vf[4], kn[4], vn[4];
;     ...
;         DIL_LOAD(kf, vf, 0);
;         f32x16 O[2]; float mrun, lrun;
;         if (pat > 0) {
;             mrun = *lsep; lrun = hi == 0 ? 1.0f : 0.0f;
; #pragma unroll
;             for (int cb = 0; cb < 2; ++cb)
; #pragma unroll
;                 for (int j4 = 0; j4 < 4; ++j4) { const u32x2 w = *(const GAS u32x2*)(orow + 32 * cb + 8 * j4);
;                     O[cb][4 * j4] = bf_lo(w.x); O[cb][4 * j4 + 1] = bf_hi(w.x); O[cb][4 * j4 + 2] = bf_lo(w.y); O[cb][4 * j4 + 3] = bf_hi(w.y); }
;         } else {
;             mrun = -1.0e30f; lrun = 0.f;
; #pragma unroll
;             for (int cb = 0; cb < 2; ++cb)
; #pragma unroll
;                 for (int i = 0; i < 16; ++i) O[cb][i] = 0.f;
;         }
; #pragma unroll
;         for (int kb = 0; kb < 5; ++kb) {
;             if (kb < 4) DIL_LOAD(kn, vn, kb + 1);
;             f32x16 sc;
; #pragma unroll
;             for (int i = 0; i < 16; ++i) sc[i] = 0.f;
; #pragma unroll
;             for (int ds = 0; ds < 4; ++ds) sc = MFMA32(kf[ds], qf[ds], sc);
.LBB0_407:
	v_readlane_b32 s11, v254, 44
	s_add_i32 s11, s11, s6
	v_readlane_b32 s12, v254, 42
	s_and_b32 s33, s11, s12
	v_readlane_b32 s12, v254, 56
	s_ashr_i32 s11, s11, s12
	s_ashr_i32 s12, s11, 3
	s_and_b32 s80, s11, 7
	s_ashr_i32 s13, s12, 31
	v_readlane_b32 s11, v254, 58
	s_lshl_b64 s[72:73], s[12:13], s8
	s_and_b32 s13, s33, s11
	v_readlane_b32 s11, v254, 57
	s_lshl_b32 s40, s80, 7
	s_lshr_b32 s74, s33, s11
	s_lshl_b32 s11, s13, 5
	s_add_u32 s76, s72, s74
	s_addc_u32 s77, s73, 0
	s_lshl_b64 s[76:77], s[76:77], 12
	s_add_u32 s12, s0, s76
	s_addc_u32 s33, s1, s77
	s_add_u32 s76, s12, s40
	s_addc_u32 s77, s33, 0
	s_lshl_b32 s12, s80, s9
	s_lshl_b32 s12, s12, 1
	v_readlane_b32 s78, v254, 46
	s_mov_b32 s75, s41
	v_readlane_b32 s79, v254, 47
	s_add_u32 s12, s78, s12
	s_addc_u32 s33, s79, 0
	s_lshl_b64 s[78:79], s[74:75], s10
	v_or_b32_e32 v0, s11, v73
	s_add_u32 s78, s72, s78
	v_lshl_add_u32 v192, v0, 4, s74
	s_addc_u32 s79, s73, s79
	v_lshl_add_u64 v[16:17], s[72:73], 0, v[192:193]
	v_readlane_b32 s72, v254, 48
	s_lshl_b64 s[78:79], s[78:79], 7
	v_lshlrev_b64 v[0:1], 12, v[16:17]
	v_lshlrev_b64 v[2:3], 11, v[16:17]
	v_readlane_b32 s73, v254, 49
	s_add_u32 s78, s12, s78
	v_lshl_add_u64 v[0:1], s[0:1], 0, v[0:1]
	v_lshl_add_u64 v[2:3], s[72:73], 0, v[2:3]
	s_addc_u32 s79, s33, s79
	v_lshlrev_b32_e32 v192, 1, v72
	v_lshl_add_u64 v[0:1], v[0:1], 0, s[40:41]
	v_lshl_add_u64 v[18:19], v[2:3], 0, s[40:41]
	s_lshl_b32 s40, s80, 2
	s_sub_i32 s12, s11, 64
	v_lshl_add_u64 v[30:31], v[0:1], 0, v[192:193]
	s_cmp_lt_u32 s13, 2
	v_or_b32_e32 v0, s12, v93
	v_lshl_add_u64 v[86:87], s[76:77], 0, v[192:193]
	v_min_i32_e32 v0, s94, v0
	s_cselect_b64 s[76:77], -1, 0
	v_or_b32_e32 v4, s12, v72
	v_cndmask_b32_e64 v192, v0, 0, s[76:77]
	v_lshrrev_b32_e32 v2, 3, v4
	v_cmp_gt_i32_e64 s[72:73], s7, v4
	v_or_b32_e32 v4, 16, v4
	v_lshlrev_b64 v[0:1], 16, v[192:193]
	v_cndmask_b32_e64 v192, 0, v2, s[72:73]
	v_lshrrev_b32_e32 v5, 3, v4
	v_cmp_gt_i32_e64 s[74:75], s7, v4
	v_lshlrev_b64 v[2:3], 9, v[192:193]
	v_cndmask_b32_e64 v21, v3, 0, s[76:77]
	v_cndmask_b32_e64 v192, 0, v5, s[74:75]
	v_cndmask_b32_e64 v20, v2, 0, s[76:77]
	v_lshlrev_b64 v[2:3], 9, v[192:193]
	s_sub_i32 s33, s11, 32
	v_cndmask_b32_e64 v22, v2, 0, s[76:77]
	v_or_b32_e32 v2, s33, v72
	v_cndmask_b32_e64 v23, v3, 0, s[76:77]
	v_lshrrev_b32_e32 v3, 3, v2
	v_cmp_gt_i32_e64 s[74:75], s7, v2
	v_add_u32_e32 v4, s11, v209
	v_lshrrev_b32_e32 v5, 3, v4
	v_cndmask_b32_e64 v192, 0, v3, s[74:75]
	v_cmp_gt_i32_e64 s[74:75], s7, v4
	s_cmp_eq_u32 s13, 0
	v_lshlrev_b64 v[2:3], 9, v[192:193]
	v_cndmask_b32_e64 v192, 0, v5, s[74:75]
	s_cselect_b64 s[74:75], -1, 0
	v_cndmask_b32_e64 v25, v3, 0, s[74:75]
	v_cndmask_b32_e64 v24, v2, 0, s[74:75]
	v_lshlrev_b64 v[2:3], 9, v[192:193]
	v_lshl_add_u64 v[40:41], v[86:87], 0, v[0:1]
	v_cndmask_b32_e64 v27, v3, 0, s[74:75]
	v_cndmask_b32_e64 v26, v2, 0, s[74:75]
	global_load_dwordx4 v[0:3], v[40:41], off offset:3072
	global_load_dwordx4 v[60:63], v[30:31], off offset:2048
	global_load_dwordx4 v[32:35], v[40:41], off offset:3104
	global_load_dwordx4 v[56:59], v[30:31], off offset:2080
	global_load_dwordx4 v[36:39], v[40:41], off offset:3136
	global_load_dwordx4 v[52:55], v[30:31], off offset:2112
	global_load_dwordx4 v[64:67], v[40:41], off offset:3168
	global_load_dwordx4 v[48:51], v[30:31], off offset:2144
	v_or_b32_e32 v4, s33, v93
	v_min_i32_e32 v4, s94, v4
	v_cndmask_b32_e64 v28, v4, 0, s[74:75]
	s_cmp_gt_u32 s13, 1
	s_cselect_b64 s[74:75], -1, 0
	v_readlane_b32 s76, v254, 50
	s_and_b64 s[72:73], s[74:75], s[72:73]
	v_readlane_b32 s77, v254, 51
	s_and_b64 s[72:73], s[72:73], s[76:77]
	v_mov_b32_e32 v250, 0xff800000
	v_readlane_b32 s76, v254, 59
	v_readlane_b32 s77, v254, 60
	v_ashrrev_i32_e32 v29, 31, v28
	v_mov_b32_e32 v77, v193
	v_lshl_add_u64 v[78:79], s[78:79], 0, v[76:77]
	v_mov_b32_e32 v75, v193
	v_lshl_add_u64 v[80:81], v[18:19], 0, v[74:75]
	v_lshlrev_b64 v[16:17], 5, v[16:17]
	v_lshl_add_u64 v[20:21], v[20:21], 1, v[78:79]
	s_mov_b32 s33, 0xff61b1e6
	v_lshl_add_u64 v[246:247], v[24:25], 1, v[78:79]
	s_waitcnt vmcnt(0)
	v_mfma_f32_32x32x16_bf16 v[0:15], v[0:3], v[60:63], 0
	v_lshl_add_u64 v[248:249], v[26:27], 1, v[78:79]
	s_add_i32 s13, s11, 32
	v_cmp_lt_i32_e64 s[78:79], s12, v179
	v_cmp_lt_i32_e64 s[80:81], s12, v180
	v_cmp_lt_i32_e64 s[82:83], s12, v181
	v_cmp_lt_i32_e64 s[84:85], s12, v182
	v_cmp_lt_i32_e64 s[86:87], s12, v183
	v_mfma_f32_32x32x16_bf16 v[0:15], v[32:35], v[56:59], v[0:15]
	s_nop 0
	s_nop 0
	s_nop 0
	v_cmp_lt_i32_e64 s[88:89], s12, v184
	s_waitcnt vmcnt(2)
	v_mfma_f32_32x32x16_bf16 v[0:15], v[36:39], v[52:55], v[0:15]
	s_waitcnt vmcnt(0)
; #define MFMA32(a, b, c) __builtin_amdgcn_mfma_f32_32x32x16_bf16((a), (b), (c), 0, 0, 0)
; DI void dil_phase(int wv, const bf16_t* QK, const bf16_t* VTg, int rows, int nb, int S, int rr, int pat, bf16_t* OUT, float* LSE) {
;     ...
;         for (int kb = 0; kb < 5; ++kb) {
;             if (kb < 4) DIL_LOAD(kn, vn, kb + 1);
;             f32x16 sc;
; #pragma unroll
;             for (int i = 0; i < 16; ++i) sc[i] = 0.f;
; #pragma unroll
;             for (int ds = 0; ds < 4; ++ds) sc = MFMA32(kf[ds], qf[ds], sc);
;             float mx = -3.0e38f;
; #pragma unroll
;             for (int i = 0; i < 16; ++i) {
;                 const int kk = 32 * kb + 16 * (i >> 3) + 8 * hi + (i & 7), mk = i0 - 64 + kk, dd = kk - r;
;                 const bool ok = (mk >= 0) && (mk < Sr) && (dd >= 0) && (dd <= 128);
;                 const float v = ok ? sc[i] : -INFINITY; sc[i] = v; mx = fmaxf(mx, v);
;             }
	v_mfma_f32_32x32x16_bf16 v[0:15], v[64:67], v[48:51], v[0:15]
	s_nop 11
	v_cndmask_b32_e64 v32, v250, v0, s[72:73]
	v_or_b32_e32 v0, s12, v122
	v_cmp_gt_i32_e64 s[72:73], s7, v0
	s_and_b64 s[72:73], s[74:75], s[72:73]
	s_and_b64 s[72:73], s[72:73], s[76:77]
	v_or_b32_e32 v0, s12, v123
	v_cndmask_b32_e64 v33, v250, v1, s[72:73]
	v_cmp_gt_i32_e64 s[72:73], s7, v0
	v_readlane_b32 s76, v254, 61
	s_and_b64 s[72:73], s[74:75], s[72:73]
	v_readlane_b32 s77, v254, 62
	s_and_b64 s[72:73], s[72:73], s[76:77]
	v_or_b32_e32 v0, s12, v124
	v_cndmask_b32_e64 v34, v250, v2, s[72:73]
	v_cmp_gt_i32_e64 s[72:73], s7, v0
	v_readlane_b32 s76, v254, 63
	s_and_b64 s[72:73], s[74:75], s[72:73]
	v_readlane_b32 s77, v255, 0
	s_and_b64 s[72:73], s[72:73], s[76:77]
	v_or_b32_e32 v0, s12, v125
	v_cndmask_b32_e64 v35, v250, v3, s[72:73]
	v_cmp_gt_i32_e64 s[72:73], s7, v0
	s_and_b64 s[72:73], s[74:75], s[72:73]
	s_and_b64 s[72:73], s[72:73], s[14:15]
	v_or_b32_e32 v0, s12, v126
	v_cndmask_b32_e64 v36, v250, v4, s[72:73]
	v_cmp_gt_i32_e64 s[72:73], s7, v0
	s_and_b64 s[72:73], s[74:75], s[72:73]
	s_and_b64 s[72:73], s[72:73], s[16:17]
	v_or_b32_e32 v0, s12, v127
	v_cndmask_b32_e64 v37, v250, v5, s[72:73]
	v_cmp_gt_i32_e64 s[72:73], s7, v0
	s_and_b64 s[72:73], s[74:75], s[72:73]
	s_and_b64 s[72:73], s[72:73], s[18:19]
	v_or_b32_e32 v0, s12, v128
	v_cndmask_b32_e64 v38, v250, v6, s[72:73]
	v_cmp_gt_i32_e64 s[72:73], s7, v0
	s_and_b64 s[72:73], s[74:75], s[72:73]
	s_and_b64 s[72:73], s[72:73], s[20:21]
	v_or_b32_e32 v0, s12, v129
	v_cndmask_b32_e64 v39, v250, v7, s[72:73]
	v_cmp_gt_i32_e64 s[72:73], s7, v0
	s_and_b64 s[72:73], s[74:75], s[72:73]
	s_and_b64 s[72:73], s[72:73], s[22:23]
	v_or_b32_e32 v0, s12, v130
	v_cndmask_b32_e64 v40, v250, v8, s[72:73]
	v_cmp_gt_i32_e64 s[72:73], s7, v0
	s_and_b64 s[72:73], s[74:75], s[72:73]
	s_and_b64 s[72:73], s[72:73], s[24:25]
	v_or_b32_e32 v0, s12, v131
	v_cndmask_b32_e64 v41, v250, v9, s[72:73]
	v_cmp_gt_i32_e64 s[72:73], s7, v0
	s_and_b64 s[72:73], s[74:75], s[72:73]
	s_and_b64 s[72:73], s[72:73], s[26:27]
	v_or_b32_e32 v0, s12, v132
	v_cndmask_b32_e64 v42, v250, v10, s[72:73]
	v_cmp_gt_i32_e64 s[72:73], s7, v0
	s_and_b64 s[72:73], s[74:75], s[72:73]
	s_and_b64 s[72:73], s[72:73], s[28:29]
	v_or_b32_e32 v0, s12, v133
	v_cndmask_b32_e64 v43, v250, v11, s[72:73]
	v_cmp_gt_i32_e64 s[72:73], s7, v0
	s_and_b64 s[72:73], s[74:75], s[72:73]
	s_and_b64 s[72:73], s[72:73], s[30:31]
	v_or_b32_e32 v0, s12, v134
	v_cndmask_b32_e64 v45, v250, v12, s[72:73]
	v_cmp_gt_i32_e64 s[72:73], s7, v0
	s_and_b64 s[72:73], s[74:75], s[72:73]
	s_and_b64 s[72:73], s[72:73], s[34:35]
	v_or_b32_e32 v0, s12, v135
	v_cndmask_b32_e64 v46, v250, v13, s[72:73]
	v_cmp_gt_i32_e64 s[72:73], s7, v0
	s_and_b64 s[72:73], s[74:75], s[72:73]
	s_and_b64 s[72:73], s[72:73], s[36:37]
	v_or_b32_e32 v0, s12, v136
	v_cndmask_b32_e64 v47, v250, v14, s[72:73]
	v_cmp_gt_i32_e64 s[72:73], s7, v0
	s_and_b64 s[72:73], s[74:75], s[72:73]
	v_or_b32_e32 v0, s11, v93
	s_and_b64 s[72:73], s[72:73], s[38:39]
	v_min_i32_e32 v192, s94, v0
	v_or_b32_e32 v0, s11, v72
	v_cndmask_b32_e64 v44, v250, v15, s[72:73]
	v_lshrrev_b32_e32 v1, 3, v0
	v_cmp_gt_u32_e64 s[72:73], s7, v0
	v_or_b32_e32 v0, s11, v129
	v_lshlrev_b64 v[30:31], 16, v[192:193]
	v_cndmask_b32_e64 v192, 0, v1, s[72:73]
	v_lshrrev_b32_e32 v1, 3, v0
	v_cmp_gt_u32_e64 s[72:73], s7, v0
	v_add_u32_e32 v0, s12, v137
	v_lshlrev_b64 v[84:85], 10, v[192:193]
	v_cndmask_b32_e64 v192, 0, v1, s[72:73]
	v_cmp_lt_i32_e64 s[72:73], -1, v0
	v_cmp_gt_i32_e64 s[74:75], s7, v0
	v_lshlrev_b64 v[0:1], 16, v[28:29]
	v_lshl_add_u64 v[28:29], v[86:87], 0, v[0:1]
	global_load_dwordx4 v[0:3], v[28:29], off offset:3072
	global_load_dwordx4 v[64:67], v[28:29], off offset:3104
	global_load_dwordx4 v[226:229], v[28:29], off offset:3136
	global_load_dwordx4 v[230:233], v[28:29], off offset:3168
	s_waitcnt vmcnt(3)
	v_mfma_f32_32x32x16_bf16 v[0:15], v[0:3], v[60:63], 0
	s_and_b64 s[72:73], s[72:73], s[74:75]
	v_cmp_lt_i32_e64 s[76:77], s12, v178
	s_waitcnt vmcnt(2)
	v_mfma_f32_32x32x16_bf16 v[0:15], v[64:67], v[56:59], v[0:15]
	s_nop 0
	s_waitcnt vmcnt(1)
	v_mfma_f32_32x32x16_bf16 v[0:15], v[226:229], v[52:55], v[0:15]
	s_nop 0
	v_lshl_add_u64 v[28:29], v[86:87], 0, v[30:31]
	s_waitcnt vmcnt(0)
; #define GAS __attribute__((address_space(1)))
; DI float bf_lo(unsigned u) { return __uint_as_float(u << 16); }
; DI float bf_hi(unsigned u) { return __uint_as_float(u & 0xffff0000u); }
; #define MFMA32(a, b, c) __builtin_amdgcn_mfma_f32_32x32x16_bf16((a), (b), (c), 0, 0, 0)
; DI void dil_phase(int wv, const bf16_t* QK, const bf16_t* VTg, int rows, int nb, int S, int rr, int pat, bf16_t* OUT, float* LSE) {
;     ...
;                 for (int j4 = 0; j4 < 4; ++j4) { const u32x2 w = *(const GAS u32x2*)(orow + 32 * cb + 8 * j4);
;                     O[cb][4 * j4] = bf_lo(w.x); O[cb][4 * j4 + 1] = bf_hi(w.x); O[cb][4 * j4 + 2] = bf_lo(w.y); O[cb][4 * j4 + 3] = bf_hi(w.y); }
;     ...
;         for (int kb = 0; kb < 5; ++kb) {
;             if (kb < 4) DIL_LOAD(kn, vn, kb + 1);
;             f32x16 sc;
; #pragma unroll
;             for (int i = 0; i < 16; ++i) sc[i] = 0.f;
; #pragma unroll
;             for (int ds = 0; ds < 4; ++ds) sc = MFMA32(kf[ds], qf[ds], sc);
;             float mx = -3.0e38f;
; #pragma unroll
;             for (int i = 0; i < 16; ++i) {
;                 const int kk = 32 * kb + 16 * (i >> 3) + 8 * hi + (i & 7), mk = i0 - 64 + kk, dd = kk - r;
;                 const bool ok = (mk >= 0) && (mk < Sr) && (dd >= 0) && (dd <= 128);
;                 const float v = ok ? sc[i] : -INFINITY; sc[i] = v; mx = fmaxf(mx, v);
;             }
	v_mfma_f32_32x32x16_bf16 v[0:15], v[230:233], v[48:51], v[0:15]
	global_load_dwordx4 v[64:67], v[28:29], off offset:3104
	global_load_dwordx4 v[234:237], v[28:29], off offset:3072
	global_load_dwordx4 v[226:229], v[28:29], off offset:3136
	global_load_dwordx4 v[230:233], v[28:29], off offset:3168
	s_nop 10
	v_cndmask_b32_e64 v88, v250, v0, s[72:73]
	v_add_u32_e32 v0, s12, v138
	v_cmp_lt_i32_e64 s[72:73], -1, v0
	v_cmp_gt_i32_e64 s[74:75], s7, v0
	s_and_b64 s[72:73], s[72:73], s[74:75]
	v_add_u32_e32 v0, s12, v139
	v_cndmask_b32_e64 v90, v250, v1, s[72:73]
	v_cmp_lt_i32_e64 s[72:73], -1, v0
	v_cmp_gt_i32_e64 s[74:75], s7, v0
	s_and_b64 s[72:73], s[72:73], s[74:75]
	v_add_u32_e32 v0, s12, v140
	v_cndmask_b32_e64 v94, v250, v2, s[72:73]
	v_cmp_lt_i32_e64 s[72:73], -1, v0
	v_cmp_gt_i32_e64 s[74:75], s7, v0
	s_and_b64 s[72:73], s[72:73], s[74:75]
	v_add_u32_e32 v0, s12, v141
	v_cndmask_b32_e64 v96, v250, v3, s[72:73]
	v_cmp_lt_i32_e64 s[72:73], -1, v0
	v_cmp_gt_i32_e64 s[74:75], s7, v0
	s_and_b64 s[72:73], s[72:73], s[74:75]
	v_add_u32_e32 v0, s12, v142
	v_cndmask_b32_e64 v98, v250, v4, s[72:73]
	v_cmp_lt_i32_e64 s[72:73], -1, v0
	v_cmp_gt_i32_e64 s[74:75], s7, v0
	s_and_b64 s[72:73], s[72:73], s[74:75]
	v_add_u32_e32 v0, s12, v143
	v_cndmask_b32_e64 v100, v250, v5, s[72:73]
	v_cmp_lt_i32_e64 s[72:73], -1, v0
	v_cmp_gt_i32_e64 s[74:75], s7, v0
	s_and_b64 s[72:73], s[72:73], s[74:75]
	v_add_u32_e32 v0, s12, v144
	v_cndmask_b32_e64 v102, v250, v6, s[72:73]
	v_cmp_lt_i32_e64 s[72:73], -1, v0
	v_cmp_gt_i32_e64 s[74:75], s7, v0
	s_and_b64 s[72:73], s[72:73], s[74:75]
	v_add_u32_e32 v0, s12, v145
	v_cndmask_b32_e64 v104, v250, v7, s[72:73]
	v_cmp_lt_i32_e64 s[72:73], -1, v0
	v_cmp_gt_i32_e64 s[74:75], s7, v0
	s_and_b64 s[72:73], s[72:73], s[74:75]
	v_add_u32_e32 v0, s12, v146
	v_cndmask_b32_e64 v110, v250, v8, s[72:73]
	v_cmp_lt_i32_e64 s[72:73], -1, v0
	v_cmp_gt_i32_e64 s[74:75], s7, v0
	s_and_b64 s[72:73], s[72:73], s[74:75]
	v_add_u32_e32 v0, s12, v147
	v_cndmask_b32_e64 v114, v250, v9, s[72:73]
	v_cmp_lt_i32_e64 s[72:73], -1, v0
	v_cmp_gt_i32_e64 s[74:75], s7, v0
	s_and_b64 s[72:73], s[72:73], s[74:75]
	v_add_u32_e32 v0, s12, v148
	v_cndmask_b32_e64 v106, v250, v10, s[72:73]
	v_cmp_lt_i32_e64 s[72:73], -1, v0
	v_cmp_gt_i32_e64 s[74:75], s7, v0
	s_and_b64 s[72:73], s[72:73], s[74:75]
	v_add_u32_e32 v0, s12, v149
	v_cndmask_b32_e64 v108, v250, v11, s[72:73]
	v_cmp_lt_i32_e64 s[72:73], -1, v0
	v_cmp_gt_i32_e64 s[74:75], s7, v0
	s_and_b64 s[72:73], s[72:73], s[74:75]
	v_add_u32_e32 v0, s12, v150
	v_cndmask_b32_e64 v112, v250, v12, s[72:73]
	v_cmp_lt_i32_e64 s[72:73], -1, v0
	v_cmp_gt_i32_e64 s[74:75], s7, v0
	s_and_b64 s[72:73], s[72:73], s[74:75]
	v_add_u32_e32 v0, s12, v151
	v_cndmask_b32_e64 v116, v250, v13, s[72:73]
	v_cmp_lt_i32_e64 s[72:73], -1, v0
	v_cmp_gt_i32_e64 s[74:75], s7, v0
	s_and_b64 s[72:73], s[72:73], s[74:75]
	v_add_u32_e32 v0, s12, v152
	v_cndmask_b32_e64 v195, v250, v14, s[72:73]
	v_cmp_lt_i32_e64 s[72:73], -1, v0
	v_cmp_gt_i32_e64 s[74:75], s7, v0
	s_nop 0
	s_and_b64 s[72:73], s[72:73], s[74:75]
	v_cndmask_b32_e64 v194, v250, v15, s[72:73]
	s_waitcnt vmcnt(0)
	v_mfma_f32_32x32x16_bf16 v[0:15], v[234:237], v[60:63], 0
	v_cmp_lt_i32_e64 s[72:73], s12, v153
	v_cmp_lt_i32_e64 s[74:75], s12, v177
	v_mfma_f32_32x32x16_bf16 v[0:15], v[64:67], v[56:59], v[0:15]
	s_nop 0
	s_nop 0
	s_nop 0
	s_waitcnt vmcnt(1)
	v_mfma_f32_32x32x16_bf16 v[0:15], v[226:229], v[52:55], v[0:15]
	v_lshl_add_u64 v[64:65], v[22:23], 1, v[78:79]
	s_waitcnt vmcnt(0)
	v_mfma_f32_32x32x16_bf16 v[0:15], v[230:233], v[48:51], v[0:15]
	s_nop 11
	v_cndmask_b32_e64 v89, v250, v0, s[72:73]
	v_cmp_lt_i32_e64 s[72:73], s12, v154
	s_nop 1
	v_cndmask_b32_e64 v91, v250, v1, s[72:73]
	v_cmp_lt_i32_e64 s[72:73], s12, v155
	s_nop 1
	v_cndmask_b32_e64 v95, v250, v2, s[72:73]
	v_cmp_lt_i32_e64 s[72:73], s12, v156
	s_nop 1
	v_cndmask_b32_e64 v77, v250, v3, s[72:73]
	v_cmp_lt_i32_e64 s[72:73], s12, v157
	s_nop 1
	v_cndmask_b32_e64 v99, v250, v4, s[72:73]
	v_cmp_lt_i32_e64 s[72:73], s12, v158
	s_nop 1
	v_cndmask_b32_e64 v101, v250, v5, s[72:73]
	v_cmp_lt_i32_e64 s[72:73], s12, v159
	s_nop 1
	v_cndmask_b32_e64 v103, v250, v6, s[72:73]
	v_cmp_lt_i32_e64 s[72:73], s12, v160
	s_nop 1
	v_cndmask_b32_e64 v105, v250, v7, s[72:73]
	v_cmp_lt_i32_e64 s[72:73], s12, v161
	s_nop 1
	v_cndmask_b32_e64 v107, v250, v8, s[72:73]
	v_cmp_lt_i32_e64 s[72:73], s12, v162
	s_nop 1
	v_cndmask_b32_e64 v109, v250, v9, s[72:73]
	v_cmp_lt_i32_e64 s[72:73], s12, v163
	s_nop 1
	v_cndmask_b32_e64 v111, v250, v10, s[72:73]
	v_cmp_lt_i32_e64 s[72:73], s12, v164
	s_nop 1
	v_cndmask_b32_e64 v113, v250, v11, s[72:73]
	v_cmp_lt_i32_e64 s[72:73], s12, v165
	s_nop 1
	v_cndmask_b32_e64 v115, v250, v12, s[72:73]
	v_cmp_lt_i32_e64 s[72:73], s12, v166
	s_nop 1
	v_cndmask_b32_e64 v117, v250, v13, s[72:73]
	v_cmp_lt_i32_e64 s[72:73], s12, v167
	s_nop 1
	v_cndmask_b32_e64 v201, v250, v14, s[72:73]
	v_cmp_lt_i32_e64 s[72:73], s12, v168
	s_nop 1
	v_cndmask_b32_e64 v200, v250, v15, s[72:73]
	global_load_dwordx2 v[0:1], v[80:81], off offset:1024
	global_load_dwordx2 v[2:3], v[80:81], off offset:1040
	global_load_dwordx2 v[4:5], v[80:81], off offset:1056
	global_load_dwordx2 v[6:7], v[80:81], off offset:1072
	global_load_dwordx2 v[8:9], v[80:81], off offset:1088
	global_load_dwordx2 v[10:11], v[80:81], off offset:1104
	global_load_dwordx2 v[12:13], v[80:81], off offset:1120
	global_load_dwordx2 v[14:15], v[80:81], off offset:1136
	v_readlane_b32 s72, v254, 52
	v_readlane_b32 s73, v254, 53
	s_waitcnt vmcnt(6)
; DI void dil_phase(int wv, const bf16_t* QK, const bf16_t* VTg, int rows, int nb, int S, int rr, int pat, bf16_t* OUT, float* LSE) {
;     ...
;         if (pat > 0) {
;             mrun = *lsep; lrun = hi == 0 ? 1.0f : 0.0f;
; #pragma unroll
;             for (int cb = 0; cb < 2; ++cb)
; #pragma unroll
;                 for (int j4 = 0; j4 < 4; ++j4) { const u32x2 w = *(const GAS u32x2*)(orow + 32 * cb + 8 * j4);
;                     O[cb][4 * j4] = bf_lo(w.x); O[cb][4 * j4 + 1] = bf_hi(w.x); O[cb][4 * j4 + 2] = bf_lo(w.y); O[cb][4 * j4 + 3] = bf_hi(w.y); }
;         } else {
;             mrun = -1.0e30f; lrun = 0.f;
; #pragma unroll
;             for (int cb = 0; cb < 2; ++cb)
; #pragma unroll
;                 for (int i = 0; i < 16; ++i) O[cb][i] = 0.f;
;         }
; #pragma unroll
;         for (int kb = 0; kb < 5; ++kb) {
;             if (kb < 4) DIL_LOAD(kn, vn, kb + 1);
;             f32x16 sc;
; #pragma unroll
;             for (int i = 0; i < 16; ++i) sc[i] = 0.f;
; #pragma unroll
;             for (int ds = 0; ds < 4; ++ds) sc = MFMA32(kf[ds], qf[ds], sc);
;             float mx = -3.0e38f;
; #pragma unroll
;             for (int i = 0; i < 16; ++i) {
;                 const int kk = 32 * kb + 16 * (i >> 3) + 8 * hi + (i & 7), mk = i0 - 64 + kk, dd = kk - r;
;                 const bool ok = (mk >= 0) && (mk < Sr) && (dd >= 0) && (dd <= 128);
;                 const float v = ok ? sc[i] : -INFINITY; sc[i] = v; mx = fmaxf(mx, v);
;             }
;             mx = swap_max(mx);
;             const float mnew = fmaxf(mrun, mx), alpha = ex2(mrun - mnew);
;             float ps = 0.f;
; #pragma unroll
;             for (int i = 0; i < 16; ++i) { const float p = ex2(sc[i] - mnew); sc[i] = p; ps += p; }
;             lrun = lrun * alpha + ps; mrun = mnew;
; #pragma unroll
;             for (int cb = 0; cb < 2; ++cb) O[cb] = O[cb] * alpha;
;             u32x4 w0, w1;
;             w0.x = pk2(sc[0], sc[1]); w0.y = pk2(sc[2], sc[3]); w0.z = pk2(sc[4], sc[5]); w0.w = pk2(sc[6], sc[7]);
;             w1.x = pk2(sc[8], sc[9]); w1.y = pk2(sc[10], sc[11]); w1.z = pk2(sc[12], sc[13]); w1.w = pk2(sc[14], sc[15]);
;             const bf16x8 pf0 = __builtin_bit_cast(bf16x8, w0), pf1 = __builtin_bit_cast(bf16x8, w1);
; #pragma unroll
;             for (int cb = 0; cb < 2; ++cb) { O[cb] = MFMA32(vf[cb], pf0, O[cb]); O[cb] = MFMA32(vf[2 + cb], pf1, O[cb]); }
	v_lshlrev_b32_e32 v66, 16, v2
	v_lshl_add_u64 v[16:17], s[72:73], 0, v[16:17]
	v_lshl_add_u64 v[82:83], v[16:17], 0, s[40:41]
	global_load_dword v75, v[82:83], off
	global_load_dwordx4 v[16:19], v[20:21], off
	global_load_dwordx4 v[28:31], v[20:21], off offset:512
	s_nop 0
	global_load_dwordx4 v[20:23], v[64:65], off
	global_load_dwordx4 v[226:229], v[64:65], off offset:512
	s_waitcnt vmcnt(8)
	v_lshlrev_b32_e32 v120, 16, v8
	v_and_b32_e32 v121, 0xffff0000, v8
	v_max3_f32 v8, v32, s33, v33
	v_max3_f32 v8, v8, v34, v35
	v_max3_f32 v8, v8, v36, v37
	v_max3_f32 v8, v8, v38, v39
	v_max3_f32 v8, v8, v40, v41
	v_max3_f32 v8, v8, v42, v43
	v_max3_f32 v8, v8, v45, v46
	v_max3_f32 v8, v8, v47, v44
	v_lshlrev_b32_e32 v196, 16, v9
	v_and_b32_e32 v197, 0xffff0000, v9
	v_mov_b32_e32 v9, v8
	s_nop 1
	v_permlane32_swap_b32_e32 v8, v9
	v_lshlrev_b32_e32 v64, 16, v0
	v_and_b32_e32 v65, 0xffff0000, v0
	v_lshlrev_b32_e32 v0, 16, v1
	v_and_b32_e32 v1, 0xffff0000, v1
	v_and_b32_e32 v67, 0xffff0000, v2
	v_lshlrev_b32_e32 v2, 16, v3
	v_and_b32_e32 v3, 0xffff0000, v3
	v_lshlrev_b32_e32 v68, 16, v4
	v_and_b32_e32 v69, 0xffff0000, v4
	v_lshlrev_b32_e32 v4, 16, v5
	v_and_b32_e32 v5, 0xffff0000, v5
	v_lshlrev_b32_e32 v70, 16, v6
	v_and_b32_e32 v71, 0xffff0000, v6
	v_lshlrev_b32_e32 v6, 16, v7
	v_and_b32_e32 v7, 0xffff0000, v7
	s_waitcnt vmcnt(7)
	v_lshlrev_b32_e32 v234, 16, v10
	v_and_b32_e32 v235, 0xffff0000, v10
	v_lshlrev_b32_e32 v236, 16, v11
	v_and_b32_e32 v237, 0xffff0000, v11
	s_waitcnt vmcnt(6)
	v_lshlrev_b32_e32 v238, 16, v12
	v_and_b32_e32 v239, 0xffff0000, v12
	v_lshlrev_b32_e32 v240, 16, v13
	v_and_b32_e32 v241, 0xffff0000, v13
	s_waitcnt vmcnt(5)
	v_lshlrev_b32_e32 v242, 16, v14
	v_and_b32_e32 v243, 0xffff0000, v14
	v_lshlrev_b32_e32 v244, 16, v15
	v_and_b32_e32 v245, 0xffff0000, v15
	global_load_dwordx4 v[230:233], v[246:247], off
	v_cmp_lt_i32_e64 s[72:73], s12, v169
	s_waitcnt vmcnt(5)
	v_max3_f32 v118, v75, v8, v9
	v_sub_f32_e32 v9, v32, v118
	v_exp_f32_e32 v223, v9
	v_sub_f32_e32 v9, v33, v118
	v_exp_f32_e32 v224, v9
	v_sub_f32_e32 v9, v34, v118
	v_exp_f32_e32 v219, v9
	v_sub_f32_e32 v9, v35, v118
	v_exp_f32_e32 v220, v9
	v_sub_f32_e32 v9, v36, v118
	v_exp_f32_e32 v221, v9
	v_sub_f32_e32 v9, v37, v118
	v_exp_f32_e32 v222, v9
	v_sub_f32_e32 v9, v38, v118
	v_exp_f32_e32 v217, v9
	v_sub_f32_e32 v9, v39, v118
	v_exp_f32_e32 v218, v9
	v_sub_f32_e32 v9, v40, v118
	v_sub_f32_e32 v8, v75, v118
	v_exp_f32_e32 v215, v9
	v_sub_f32_e32 v9, v41, v118
	v_exp_f32_e32 v216, v9
	v_sub_f32_e32 v9, v42, v118
	v_exp_f32_e32 v92, v8
	v_exp_f32_e32 v75, v9
	v_sub_f32_e32 v9, v43, v118
	v_exp_f32_e32 v97, v9
	v_sub_f32_e32 v9, v45, v118
	v_exp_f32_e32 v211, v9
	v_sub_f32_e32 v9, v46, v118
	v_sub_f32_e32 v8, v47, v118
	v_exp_f32_e32 v212, v9
	v_exp_f32_e32 v213, v8
	v_pk_mul_f32 v[14:15], v[6:7], v[92:93] op_sel_hi:[1,0]
	v_pk_mul_f32 v[12:13], v[70:71], v[92:93] op_sel_hi:[1,0]
	v_pk_mul_f32 v[10:11], v[4:5], v[92:93] op_sel_hi:[1,0]
	v_pk_mul_f32 v[8:9], v[68:69], v[92:93] op_sel_hi:[1,0]
	v_pk_mul_f32 v[6:7], v[2:3], v[92:93] op_sel_hi:[1,0]
	v_pk_mul_f32 v[4:5], v[66:67], v[92:93] op_sel_hi:[1,0]
	v_pk_mul_f32 v[2:3], v[0:1], v[92:93] op_sel_hi:[1,0]
	v_pk_mul_f32 v[0:1], v[64:65], v[92:93] op_sel_hi:[1,0]
	v_pk_mul_f32 v[38:39], v[92:93], v[236:237] op_sel_hi:[0,1]
	v_pk_mul_f32 v[36:37], v[92:93], v[234:235] op_sel_hi:[0,1]
	global_load_dwordx4 v[234:237], v[248:249], off
	global_load_dwordx4 v[68:71], v[246:247], off offset:512
	global_load_dwordx4 v[64:67], v[248:249], off offset:512
	v_cvt_pk_bf16_f32 v24, v223, v224
	v_cvt_pk_bf16_f32 v25, v219, v220
	v_cvt_pk_bf16_f32 v26, v221, v222
	v_cvt_pk_bf16_f32 v27, v217, v218
	v_pk_mul_f32 v[46:47], v[92:93], v[244:245] op_sel_hi:[0,1]
	v_pk_mul_f32 v[42:43], v[92:93], v[240:241] op_sel_hi:[0,1]
	s_waitcnt vmcnt(7)
	v_mfma_f32_32x32x16_bf16 v[0:15], v[16:19], v[24:27], v[0:15]
	v_sub_f32_e32 v16, v44, v118
	v_mul_f32_e64 v44, v92, v242
	v_mul_f32_e64 v45, v92, v243
	v_mul_f32_e64 v40, v92, v238
	v_mul_f32_e64 v41, v92, v239
	v_pk_mul_f32 v[34:35], v[92:93], v[196:197] op_sel_hi:[0,1]
	v_pk_mul_f32 v[32:33], v[92:93], v[120:121] op_sel_hi:[0,1]
	v_exp_f32_e32 v214, v16
	v_cvt_pk_bf16_f32 v16, v215, v216
	s_waitcnt vmcnt(6)
	v_mfma_f32_32x32x16_bf16 v[32:47], v[28:31], v[24:27], v[32:47]
	v_cvt_pk_bf16_f32 v17, v75, v97
	v_cvt_pk_bf16_f32 v18, v211, v212
	v_cvt_pk_bf16_f32 v19, v213, v214
	v_lshlrev_b64 v[120:121], 10, v[192:193]
	s_waitcnt vmcnt(5)
	v_mfma_f32_32x32x16_bf16 v[0:15], v[20:23], v[16:19], v[0:15]
	s_waitcnt vmcnt(4)
; DI unsigned pk2(float lo, float hi) { f32x2 v = {lo, hi}; bf16x2_t b = __builtin_convertvector(v, bf16x2_t); return __builtin_bit_cast(unsigned, b); }
; DI float swap_max(float m) { auto rr = __builtin_amdgcn_permlane32_swap(__float_as_uint(m), __float_as_uint(m), false, false); return fmaxf(__uint_as_float(rr[0]), __uint_as_float(rr[1])); }
; DI float ex2(float x) { return __builtin_amdgcn_exp2f(x); }
; #define MFMA32(a, b, c) __builtin_amdgcn_mfma_f32_32x32x16_bf16((a), (b), (c), 0, 0, 0)
; DI void dil_phase(int wv, const bf16_t* QK, const bf16_t* VTg, int rows, int nb, int S, int rr, int pat, bf16_t* OUT, float* LSE) {
;     ...
;             float mx = -3.0e38f;
; #pragma unroll
;             for (int i = 0; i < 16; ++i) {
;                 const int kk = 32 * kb + 16 * (i >> 3) + 8 * hi + (i & 7), mk = i0 - 64 + kk, dd = kk - r;
;                 const bool ok = (mk >= 0) && (mk < Sr) && (dd >= 0) && (dd <= 128);
;                 const float v = ok ? sc[i] : -INFINITY; sc[i] = v; mx = fmaxf(mx, v);
;             }
;             mx = swap_max(mx);
;             const float mnew = fmaxf(mrun, mx), alpha = ex2(mrun - mnew);
;             float ps = 0.f;
; #pragma unroll
;             for (int i = 0; i < 16; ++i) { const float p = ex2(sc[i] - mnew); sc[i] = p; ps += p; }
;             lrun = lrun * alpha + ps; mrun = mnew;
; #pragma unroll
;             for (int cb = 0; cb < 2; ++cb) O[cb] = O[cb] * alpha;
;             u32x4 w0, w1;
;             w0.x = pk2(sc[0], sc[1]); w0.y = pk2(sc[2], sc[3]); w0.z = pk2(sc[4], sc[5]); w0.w = pk2(sc[6], sc[7]);
;             w1.x = pk2(sc[8], sc[9]); w1.y = pk2(sc[10], sc[11]); w1.z = pk2(sc[12], sc[13]); w1.w = pk2(sc[14], sc[15]);
;             const bf16x8 pf0 = __builtin_bit_cast(bf16x8, w0), pf1 = __builtin_bit_cast(bf16x8, w1);
; #pragma unroll
;             for (int cb = 0; cb < 2; ++cb) { O[cb] = MFMA32(vf[cb], pf0, O[cb]); O[cb] = MFMA32(vf[2 + cb], pf1, O[cb]); }
	v_mfma_f32_32x32x16_bf16 v[32:47], v[226:229], v[16:19], v[32:47]
	v_max3_f32 v16, v88, s33, v90
	v_max3_f32 v16, v16, v94, v96
	v_max3_f32 v16, v16, v98, v100
	v_max3_f32 v16, v16, v102, v104
	v_max3_f32 v16, v16, v110, v114
	v_max3_f32 v16, v16, v106, v108
	v_max3_f32 v16, v16, v112, v116
	v_max3_f32 v16, v16, v195, v194
	v_mov_b32_e32 v17, v16
	s_nop 1
	v_permlane32_swap_b32_e32 v16, v17
	v_max3_f32 v196, v118, v16, v17
	v_sub_f32_e32 v17, v88, v196
	v_exp_f32_e32 v225, v17
	v_sub_f32_e32 v17, v90, v196
	v_exp_f32_e32 v226, v17
	v_sub_f32_e32 v17, v94, v196
	v_sub_f32_e32 v16, v118, v196
	v_exp_f32_e32 v88, v17
	v_sub_f32_e32 v17, v96, v196
	v_exp_f32_e32 v90, v17
	v_sub_f32_e32 v17, v98, v196
	v_exp_f32_e32 v118, v16
	v_exp_f32_e32 v94, v17
	v_sub_f32_e32 v17, v100, v196
	v_exp_f32_e32 v96, v17
	v_sub_f32_e32 v17, v102, v196
	v_exp_f32_e32 v98, v17
	v_sub_f32_e32 v17, v104, v196
	v_sub_f32_e32 v16, v110, v196
	v_exp_f32_e32 v100, v17
	v_exp_f32_e32 v102, v16
	v_pk_mul_f32 v[16:17], v[0:1], v[118:119] op_sel_hi:[1,0]
	v_pk_mul_f32 v[0:1], v[32:33], v[118:119] op_sel_hi:[1,0]
	v_sub_f32_e32 v32, v106, v196
	v_exp_f32_e32 v106, v32
	v_sub_f32_e32 v32, v108, v196
	v_pk_mul_f32 v[24:25], v[8:9], v[118:119] op_sel_hi:[1,0]
	v_pk_mul_f32 v[8:9], v[40:41], v[118:119] op_sel_hi:[1,0]
	v_exp_f32_e32 v108, v32
	v_sub_f32_e32 v32, v112, v196
	v_or_b32_e32 v40, s13, v93
	v_exp_f32_e32 v110, v32
	v_sub_f32_e32 v32, v116, v196
	v_min_i32_e32 v192, s94, v40
	v_exp_f32_e32 v112, v32
	v_sub_f32_e32 v32, v195, v196
	v_lshlrev_b64 v[40:41], 16, v[192:193]
	v_sub_f32_e32 v104, v114, v196
	v_pk_mul_f32 v[30:31], v[14:15], v[118:119] op_sel_hi:[1,0]
	v_pk_mul_f32 v[28:29], v[12:13], v[118:119] op_sel_hi:[1,0]
	v_pk_mul_f32 v[26:27], v[10:11], v[118:119] op_sel_hi:[1,0]
	v_pk_mul_f32 v[22:23], v[6:7], v[118:119] op_sel_hi:[1,0]
	v_pk_mul_f32 v[20:21], v[4:5], v[118:119] op_sel_hi:[1,0]
	v_pk_mul_f32 v[18:19], v[2:3], v[118:119] op_sel_hi:[1,0]
	v_pk_mul_f32 v[14:15], v[46:47], v[118:119] op_sel_hi:[1,0]
	v_pk_mul_f32 v[12:13], v[44:45], v[118:119] op_sel_hi:[1,0]
	v_pk_mul_f32 v[10:11], v[42:43], v[118:119] op_sel_hi:[1,0]
	v_pk_mul_f32 v[6:7], v[38:39], v[118:119] op_sel_hi:[1,0]
	v_pk_mul_f32 v[4:5], v[36:37], v[118:119] op_sel_hi:[1,0]
	v_pk_mul_f32 v[2:3], v[34:35], v[118:119] op_sel_hi:[1,0]
	v_cvt_pk_bf16_f32 v36, v225, v226
	v_cvt_pk_bf16_f32 v37, v88, v90
	v_cvt_pk_bf16_f32 v38, v94, v96
	v_cvt_pk_bf16_f32 v39, v98, v100
	v_exp_f32_e32 v114, v32
	v_sub_f32_e32 v32, v194, v196
	v_lshl_add_u64 v[194:195], v[86:87], 0, v[40:41]
	global_load_dwordx4 v[40:43], v[194:195], off offset:3072
	global_load_dwordx4 v[238:241], v[194:195], off offset:3104
	global_load_dwordx4 v[242:245], v[194:195], off offset:3136
	global_load_dwordx4 v[246:249], v[194:195], off offset:3168
	s_waitcnt vmcnt(5)
	v_mfma_f32_32x32x16_bf16 v[0:15], v[68:71], v[36:39], v[0:15]
	v_exp_f32_e32 v104, v104
	v_exp_f32_e32 v116, v32
	v_cvt_pk_bf16_f32 v33, v106, v108
	v_cvt_pk_bf16_f32 v34, v110, v112
	v_cvt_pk_bf16_f32 v32, v102, v104
	v_cvt_pk_bf16_f32 v35, v114, v116
	v_mfma_f32_32x32x16_bf16 v[16:31], v[230:233], v[36:39], v[16:31]
	v_max3_f32 v36, v89, s33, v91
	v_max3_f32 v36, v36, v95, v77
	v_max3_f32 v36, v36, v99, v101
	v_max3_f32 v36, v36, v103, v105
	v_max3_f32 v36, v36, v107, v109
	v_max3_f32 v36, v36, v111, v113
	v_max3_f32 v36, v36, v115, v117
	s_waitcnt vmcnt(4)
	v_mfma_f32_32x32x16_bf16 v[0:15], v[64:67], v[32:35], v[0:15]
	s_nop 0
	v_max3_f32 v36, v36, v201, v200
	v_mov_b32_e32 v37, v36
	s_nop 1
	v_permlane32_swap_b32_e32 v36, v37
	v_max3_f32 v69, v196, v36, v37
	v_sub_f32_e32 v36, v196, v69
	v_mfma_f32_32x32x16_bf16 v[16:31], v[234:237], v[32:35], v[16:31]
	v_exp_f32_e32 v68, v36
	s_nop 1
	v_pk_mul_f32 v[14:15], v[14:15], v[68:69] op_sel_hi:[1,0]
	v_pk_mul_f32 v[12:13], v[12:13], v[68:69] op_sel_hi:[1,0]
	v_pk_mul_f32 v[10:11], v[10:11], v[68:69] op_sel_hi:[1,0]
	s_waitcnt vmcnt(3)
	v_mfma_f32_32x32x16_bf16 v[32:47], v[40:43], v[60:63], 0
	s_nop 3
	v_mul_f32_e64 v30, v30, v68
	v_mul_f32_e64 v31, v31, v68
	v_mul_f32_e64 v28, v28, v68
	v_mul_f32_e64 v29, v29, v68
	v_mul_f32_e64 v26, v26, v68
	v_mul_f32_e64 v27, v27, v68
	v_pk_mul_f32 v[24:25], v[24:25], v[68:69] op_sel_hi:[1,0]
	v_pk_mul_f32 v[22:23], v[22:23], v[68:69] op_sel_hi:[1,0]
	v_pk_mul_f32 v[20:21], v[20:21], v[68:69] op_sel_hi:[1,0]
	v_pk_mul_f32 v[18:19], v[18:19], v[68:69] op_sel_hi:[1,0]
	s_waitcnt vmcnt(2)
	v_mfma_f32_32x32x16_bf16 v[32:47], v[238:241], v[56:59], v[32:47]
	s_nop 0
	v_mul_f32_e64 v16, v16, v68
	v_mul_f32_e64 v17, v17, v68
	v_mul_f32_e64 v8, v8, v68
	v_mul_f32_e64 v9, v9, v68
	v_pk_mul_f32 v[6:7], v[6:7], v[68:69] op_sel_hi:[1,0]
	v_pk_mul_f32 v[4:5], v[4:5], v[68:69] op_sel_hi:[1,0]
	v_pk_mul_f32 v[2:3], v[2:3], v[68:69] op_sel_hi:[1,0]
	v_pk_mul_f32 v[0:1], v[0:1], v[68:69] op_sel_hi:[1,0]
	s_waitcnt vmcnt(1)
	v_mfma_f32_32x32x16_bf16 v[32:47], v[242:245], v[52:55], v[32:47]
	s_nop 0
	s_waitcnt vmcnt(0)
; DI unsigned pk2(float lo, float hi) { f32x2 v = {lo, hi}; bf16x2_t b = __builtin_convertvector(v, bf16x2_t); return __builtin_bit_cast(unsigned, b); }
; DI float swap_max(float m) { auto rr = __builtin_amdgcn_permlane32_swap(__float_as_uint(m), __float_as_uint(m), false, false); return fmaxf(__uint_as_float(rr[0]), __uint_as_float(rr[1])); }
; DI float ex2(float x) { return __builtin_amdgcn_exp2f(x); }
; #define MFMA32(a, b, c) __builtin_amdgcn_mfma_f32_32x32x16_bf16((a), (b), (c), 0, 0, 0)
; DI void dil_phase(int wv, const bf16_t* QK, const bf16_t* VTg, int rows, int nb, int S, int rr, int pat, bf16_t* OUT, float* LSE) {
;     ...
;         for (int kb = 0; kb < 5; ++kb) {
;             if (kb < 4) DIL_LOAD(kn, vn, kb + 1);
;             f32x16 sc;
; #pragma unroll
;             for (int i = 0; i < 16; ++i) sc[i] = 0.f;
; #pragma unroll
;             for (int ds = 0; ds < 4; ++ds) sc = MFMA32(kf[ds], qf[ds], sc);
;             float mx = -3.0e38f;
; #pragma unroll
;             for (int i = 0; i < 16; ++i) {
;                 const int kk = 32 * kb + 16 * (i >> 3) + 8 * hi + (i & 7), mk = i0 - 64 + kk, dd = kk - r;
;                 const bool ok = (mk >= 0) && (mk < Sr) && (dd >= 0) && (dd <= 128);
;                 const float v = ok ? sc[i] : -INFINITY; sc[i] = v; mx = fmaxf(mx, v);
;             }
;             mx = swap_max(mx);
;             const float mnew = fmaxf(mrun, mx), alpha = ex2(mrun - mnew);
;             float ps = 0.f;
; #pragma unroll
;             for (int i = 0; i < 16; ++i) { const float p = ex2(sc[i] - mnew); sc[i] = p; ps += p; }
;             lrun = lrun * alpha + ps; mrun = mnew;
; #pragma unroll
;             for (int cb = 0; cb < 2; ++cb) O[cb] = O[cb] * alpha;
;             u32x4 w0, w1;
;             w0.x = pk2(sc[0], sc[1]); w0.y = pk2(sc[2], sc[3]); w0.z = pk2(sc[4], sc[5]); w0.w = pk2(sc[6], sc[7]);
;             w1.x = pk2(sc[8], sc[9]); w1.y = pk2(sc[10], sc[11]); w1.z = pk2(sc[12], sc[13]); w1.w = pk2(sc[14], sc[15]);
;             const bf16x8 pf0 = __builtin_bit_cast(bf16x8, w0), pf1 = __builtin_bit_cast(bf16x8, w1);
; #pragma unroll
;             for (int cb = 0; cb < 2; ++cb) { O[cb] = MFMA32(vf[cb], pf0, O[cb]); O[cb] = MFMA32(vf[2 + cb], pf1, O[cb]); }
	v_mfma_f32_32x32x16_bf16 v[32:47], v[246:249], v[48:51], v[32:47]
	s_nop 11
	v_cndmask_b32_e64 v228, v250, v32, s[72:73]
	v_cmp_lt_i32_e64 s[72:73], s12, v170
	v_or_b32_e32 v32, s13, v72
	s_add_i32 s13, s11, 64
	v_cndmask_b32_e64 v229, v250, v33, s[72:73]
	v_cmp_lt_i32_e64 s[72:73], s12, v171
	v_lshrrev_b32_e32 v33, 3, v32
	v_cndmask_b32_e64 v248, v250, v40, s[74:75]
	v_cndmask_b32_e64 v230, v250, v34, s[72:73]
	v_cmp_lt_i32_e64 s[72:73], s12, v172
	v_cndmask_b32_e64 v247, v250, v41, s[76:77]
	v_cndmask_b32_e64 v246, v250, v42, s[78:79]
	v_cndmask_b32_e64 v231, v250, v35, s[72:73]
	v_cmp_lt_i32_e64 s[72:73], s12, v173
	v_cndmask_b32_e64 v245, v250, v43, s[80:81]
	v_cndmask_b32_e64 v244, v250, v44, s[82:83]
	v_cndmask_b32_e64 v232, v250, v36, s[72:73]
	v_cmp_lt_i32_e64 s[72:73], s12, v174
	v_cndmask_b32_e64 v243, v250, v45, s[84:85]
	v_cndmask_b32_e64 v235, v250, v46, s[86:87]
	v_cndmask_b32_e64 v233, v250, v37, s[72:73]
	v_cmp_lt_i32_e64 s[72:73], s12, v175
	v_cndmask_b32_e64 v227, v250, v47, s[88:89]
	v_cmp_lt_i32_e64 s[74:75], s12, v206
	v_cndmask_b32_e64 v234, v250, v38, s[72:73]
	v_cmp_lt_i32_e64 s[72:73], s12, v176
	s_and_b64 s[74:75], s[74:75], s[66:67]
	v_cmp_lt_i32_e64 s[76:77], s12, v207
	v_cndmask_b32_e64 v249, v250, v39, s[72:73]
	v_cmp_gt_u32_e64 s[72:73], s7, v32
	v_add_u32_e32 v32, s11, v145
	s_and_b64 s[76:77], s[76:77], s[68:69]
	v_cndmask_b32_e64 v192, 0, v33, s[72:73]
	v_lshrrev_b32_e32 v33, 3, v32
	v_cmp_gt_u32_e64 s[72:73], s7, v32
	v_lshlrev_b64 v[64:65], 10, v[192:193]
	v_or_b32_e32 v32, s13, v93
	v_cndmask_b32_e64 v192, 0, v33, s[72:73]
	v_lshlrev_b64 v[66:67], 10, v[192:193]
	v_min_i32_e32 v192, s94, v32
	v_lshlrev_b64 v[32:33], 16, v[192:193]
	v_lshl_add_u64 v[70:71], v[86:87], 0, v[32:33]
	global_load_dwordx4 v[32:35], v[70:71], off offset:3072
	global_load_dwordx4 v[194:197], v[70:71], off offset:3104
	global_load_dwordx4 v[236:239], v[70:71], off offset:3136
	s_waitcnt vmcnt(2)
	v_mfma_f32_32x32x16_bf16 v[32:47], v[32:35], v[60:63], 0
	global_load_dwordx4 v[60:63], v[70:71], off offset:3168
	v_cmp_lt_i32_e64 s[72:73], s12, v185
	s_and_b64 s[72:73], s[72:73], s[42:43]
	v_cmp_lt_i32_e64 s[78:79], s12, v208
	s_and_b64 s[78:79], s[78:79], s[70:71]
	s_waitcnt vmcnt(2)
	v_mfma_f32_32x32x16_bf16 v[32:47], v[194:197], v[56:59], v[32:47]
	s_nop 0
	s_nop 0
	s_waitcnt vmcnt(1)
	v_mfma_f32_32x32x16_bf16 v[32:47], v[236:239], v[52:55], v[32:47]
	s_nop 0
	s_waitcnt vmcnt(0)
	v_mfma_f32_32x32x16_bf16 v[32:47], v[60:63], v[48:51], v[32:47]
	v_lshl_add_u64 v[62:63], v[78:79], 0, v[64:65]
	s_nop 11
	v_cndmask_b32_e64 v49, v250, v32, s[72:73]
	v_cmp_lt_i32_e64 s[72:73], s12, v186
	s_and_b64 s[72:73], s[72:73], s[44:45]
	v_or_b32_e32 v32, s13, v72
	v_cndmask_b32_e64 v51, v250, v33, s[72:73]
	v_cmp_lt_i32_e64 s[72:73], s12, v187
	s_and_b64 s[72:73], s[72:73], s[46:47]
	v_lshrrev_b32_e32 v33, 3, v32
	v_cndmask_b32_e64 v53, v250, v34, s[72:73]
	v_cmp_lt_i32_e64 s[72:73], s12, v188
	s_and_b64 s[72:73], s[72:73], s[48:49]
	v_cndmask_b32_e64 v195, v250, v45, s[74:75]
	v_cndmask_b32_e64 v55, v250, v35, s[72:73]
	v_cmp_lt_i32_e64 s[72:73], s12, v189
	s_and_b64 s[72:73], s[72:73], s[50:51]
	v_cndmask_b32_e64 v194, v250, v46, s[76:77]
	v_cndmask_b32_e64 v57, v250, v36, s[72:73]
	v_cmp_lt_i32_e64 s[72:73], s12, v190
	s_and_b64 s[82:83], s[72:73], s[52:53]
	v_cmp_lt_i32_e64 s[72:73], s12, v191
	s_and_b64 s[84:85], s[72:73], s[54:55]
	v_cmp_lt_i32_e64 s[72:73], s12, v198
	s_and_b64 s[86:87], s[72:73], s[4:5]
	v_cmp_lt_i32_e64 s[72:73], s12, v199
	s_and_b64 s[88:89], s[72:73], s[56:57]
	v_cmp_lt_i32_e64 s[72:73], s12, v202
	s_and_b64 s[90:91], s[72:73], s[58:59]
	v_cmp_lt_i32_e64 s[72:73], s12, v203
	s_and_b64 s[92:93], s[72:73], s[60:61]
	v_cmp_lt_i32_e64 s[72:73], s12, v204
	s_and_b64 s[80:81], s[72:73], s[62:63]
	v_cmp_lt_i32_e64 s[72:73], s12, v205
	s_and_b64 s[72:73], s[72:73], s[64:65]
	v_cndmask_b32_e64 v251, v250, v40, s[88:89]
	v_cndmask_b32_e64 v196, v250, v44, s[72:73]
	v_cmp_gt_u32_e64 s[72:73], s7, v32
	v_add_u32_e32 v32, s11, v210
	v_cndmask_b32_e64 v252, v250, v41, s[90:91]
	v_cndmask_b32_e64 v192, 0, v33, s[72:73]
	v_lshrrev_b32_e32 v33, 3, v32
	v_cmp_gt_u32_e64 s[72:73], s7, v32
	v_add_f32_e32 v32, 0, v223
	v_lshl_add_u64 v[40:41], v[78:79], 0, v[84:85]
	v_lshlrev_b64 v[70:71], 10, v[192:193]
	v_cndmask_b32_e64 v192, 0, v33, s[72:73]
	v_add_f32_e32 v36, v224, v32
	global_load_dwordx4 v[32:35], v[40:41], off
	v_add_f32_e32 v36, v219, v36
	v_add_f32_e32 v36, v220, v36
	v_add_f32_e32 v36, v221, v36
	v_cndmask_b32_e64 v241, v250, v42, s[92:93]
	v_add_f32_e32 v42, v222, v36
	v_lshl_add_u64 v[44:45], v[78:79], 0, v[120:121]
	v_add_f32_e32 v42, v217, v42
	v_cndmask_b32_e64 v59, v250, v37, s[82:83]
	v_cndmask_b32_e64 v61, v250, v38, s[84:85]
	v_cndmask_b32_e64 v87, v250, v39, s[86:87]
	v_cndmask_b32_e64 v242, v250, v43, s[80:81]
	global_load_dwordx4 v[36:39], v[44:45], off
	v_add_f32_e32 v46, v218, v42
	global_load_dwordx4 v[40:43], v[40:41], off offset:512
	v_add_f32_e32 v46, v215, v46
	v_cndmask_b32_e64 v250, v250, v47, s[78:79]
	v_add_f32_e32 v48, v216, v46
	global_load_dwordx4 v[44:47], v[44:45], off offset:512
	v_add_f32_e32 v48, v75, v48
	v_add_f32_e32 v48, v97, v48
	v_add_f32_e32 v48, v211, v48
	v_add_f32_e32 v48, v212, v48
	v_add_f32_e32 v48, v213, v48
	v_add_f32_e32 v48, v214, v48
	global_load_dwordx4 v[212:215], v[62:63], off
	global_load_dwordx4 v[216:219], v[62:63], off offset:512
	v_fmac_f32_e32 v48, v119, v92
	v_mul_f32_e32 v120, v48, v118
	v_add_f32_e32 v48, 0, v225
	v_add_f32_e32 v84, v226, v48
	v_sub_f32_e32 v48, v89, v69
	v_exp_f32_e32 v89, v48
	v_sub_f32_e32 v48, v91, v69
	v_exp_f32_e32 v91, v48
	v_sub_f32_e32 v48, v95, v69
	v_exp_f32_e32 v95, v48
	v_sub_f32_e32 v48, v77, v69
	v_exp_f32_e32 v97, v48
	v_sub_f32_e32 v48, v99, v69
	v_exp_f32_e32 v99, v48
	v_sub_f32_e32 v48, v101, v69
	v_exp_f32_e32 v101, v48
	v_sub_f32_e32 v48, v103, v69
	v_exp_f32_e32 v103, v48
	v_sub_f32_e32 v48, v105, v69
	v_exp_f32_e32 v105, v48
	v_sub_f32_e32 v48, v107, v69
	v_exp_f32_e32 v107, v48
	v_sub_f32_e32 v48, v109, v69
	v_lshl_add_u64 v[62:63], v[78:79], 0, v[66:67]
	v_exp_f32_e32 v109, v48
	v_sub_f32_e32 v48, v111, v69
	global_load_dwordx4 v[220:223], v[62:63], off
	global_load_dwordx4 v[236:239], v[62:63], off offset:512
	v_exp_f32_e32 v111, v48
	v_sub_f32_e32 v48, v113, v69
	v_cvt_pk_bf16_f32 v62, v89, v91
	v_cvt_pk_bf16_f32 v63, v95, v97
	v_cvt_pk_bf16_f32 v64, v99, v101
	v_cvt_pk_bf16_f32 v65, v103, v105
	v_exp_f32_e32 v113, v48
	v_sub_f32_e32 v48, v115, v69
	s_waitcnt vmcnt(7)
; DI unsigned pk2(float lo, float hi) { f32x2 v = {lo, hi}; bf16x2_t b = __builtin_convertvector(v, bf16x2_t); return __builtin_bit_cast(unsigned, b); }
; DI float swap_max(float m) { auto rr = __builtin_amdgcn_permlane32_swap(__float_as_uint(m), __float_as_uint(m), false, false); return fmaxf(__uint_as_float(rr[0]), __uint_as_float(rr[1])); }
; DI float ex2(float x) { return __builtin_amdgcn_exp2f(x); }
; #define MFMA32(a, b, c) __builtin_amdgcn_mfma_f32_32x32x16_bf16((a), (b), (c), 0, 0, 0)
; DI void dil_phase(int wv, const bf16_t* QK, const bf16_t* VTg, int rows, int nb, int S, int rr, int pat, bf16_t* OUT, float* LSE) {
;     ...
;             float mx = -3.0e38f;
; #pragma unroll
;             for (int i = 0; i < 16; ++i) {
;                 const int kk = 32 * kb + 16 * (i >> 3) + 8 * hi + (i & 7), mk = i0 - 64 + kk, dd = kk - r;
;                 const bool ok = (mk >= 0) && (mk < Sr) && (dd >= 0) && (dd <= 128);
;                 const float v = ok ? sc[i] : -INFINITY; sc[i] = v; mx = fmaxf(mx, v);
;             }
;             mx = swap_max(mx);
;             const float mnew = fmaxf(mrun, mx), alpha = ex2(mrun - mnew);
;             float ps = 0.f;
; #pragma unroll
;             for (int i = 0; i < 16; ++i) { const float p = ex2(sc[i] - mnew); sc[i] = p; ps += p; }
;             lrun = lrun * alpha + ps; mrun = mnew;
; #pragma unroll
;             for (int cb = 0; cb < 2; ++cb) O[cb] = O[cb] * alpha;
;             u32x4 w0, w1;
;             w0.x = pk2(sc[0], sc[1]); w0.y = pk2(sc[2], sc[3]); w0.z = pk2(sc[4], sc[5]); w0.w = pk2(sc[6], sc[7]);
;             w1.x = pk2(sc[8], sc[9]); w1.y = pk2(sc[10], sc[11]); w1.z = pk2(sc[12], sc[13]); w1.w = pk2(sc[14], sc[15]);
;             const bf16x8 pf0 = __builtin_bit_cast(bf16x8, w0), pf1 = __builtin_bit_cast(bf16x8, w1);
; #pragma unroll
;             for (int cb = 0; cb < 2; ++cb) { O[cb] = MFMA32(vf[cb], pf0, O[cb]); O[cb] = MFMA32(vf[2 + cb], pf1, O[cb]); }
	v_mfma_f32_32x32x16_bf16 v[16:31], v[32:35], v[62:65], v[16:31]
	v_exp_f32_e32 v115, v48
	v_sub_f32_e32 v48, v117, v69
	v_exp_f32_e32 v117, v48
	v_sub_f32_e32 v48, v201, v69
	v_sub_f32_e32 v32, v200, v69
	v_exp_f32_e32 v121, v48
	v_exp_f32_e32 v67, v32
	v_mov_b32_e32 v85, v193
	v_cvt_pk_bf16_f32 v32, v107, v109
	v_cvt_pk_bf16_f32 v33, v111, v113
	v_cvt_pk_bf16_f32 v34, v115, v117
	v_cvt_pk_bf16_f32 v35, v121, v67
	s_waitcnt vmcnt(5)
	v_mfma_f32_32x32x16_bf16 v[0:15], v[40:43], v[62:65], v[0:15]
	v_max3_f32 v40, v228, s33, v229
	v_max3_f32 v40, v40, v230, v231
	v_max3_f32 v40, v40, v232, v233
	v_max3_f32 v40, v40, v234, v249
	v_max3_f32 v40, v40, v248, v247
	v_max3_f32 v40, v40, v246, v245
	v_max3_f32 v40, v40, v244, v243
	v_mfma_f32_32x32x16_bf16 v[16:31], v[36:39], v[32:35], v[16:31]
	v_add_f32_e64 v36, v88, v84
	v_add_f32_e64 v37, v89, v85
	v_max3_f32 v40, v40, v235, v227
	v_add_f32_e64 v36, v90, v36
	v_add_f32_e64 v37, v91, v37
	v_mov_b32_e32 v41, v40
	v_pk_add_f32 v[36:37], v[94:95], v[36:37]
	s_nop 0
	v_permlane32_swap_b32_e32 v40, v41
	v_pk_add_f32 v[36:37], v[96:97], v[36:37]
	v_max3_f32 v63, v69, v40, v41
	v_pk_add_f32 v[36:37], v[98:99], v[36:37]
	v_sub_f32_e32 v41, v228, v63
	v_pk_add_f32 v[36:37], v[100:101], v[36:37]
	v_exp_f32_e32 v65, v41
	v_pk_add_f32 v[36:37], v[102:103], v[36:37]
	v_sub_f32_e32 v41, v229, v63
	v_pk_add_f32 v[36:37], v[104:105], v[36:37]
	v_sub_f32_e32 v40, v69, v63
	v_pk_add_f32 v[36:37], v[106:107], v[36:37]
	v_exp_f32_e32 v69, v41
	v_pk_add_f32 v[36:37], v[108:109], v[36:37]
	v_sub_f32_e32 v41, v230, v63
	v_pk_add_f32 v[36:37], v[110:111], v[36:37]
	v_exp_f32_e32 v84, v41
	v_pk_add_f32 v[36:37], v[112:113], v[36:37]
	v_sub_f32_e32 v41, v231, v63
	v_pk_add_f32 v[36:37], v[114:115], v[36:37]
	s_waitcnt vmcnt(4)
	v_mfma_f32_32x32x16_bf16 v[0:15], v[44:47], v[32:35], v[0:15]
	v_add_f32_e64 v94, v116, v36
	v_add_f32_e64 v95, v117, v37
	v_lshlrev_b64 v[36:37], 10, v[192:193]
	v_lshl_add_u64 v[32:33], v[78:79], 0, v[70:71]
	v_lshl_add_u64 v[96:97], v[78:79], 0, v[36:37]
	v_exp_f32_e32 v78, v41
	v_sub_f32_e32 v41, v232, v63
	global_load_dwordx4 v[44:47], v[32:33], off
	s_nop 0
	global_load_dwordx4 v[32:35], v[32:33], off offset:512
	v_exp_f32_e32 v70, v41
	v_sub_f32_e32 v41, v233, v63
	v_exp_f32_e32 v66, v41
	v_sub_f32_e32 v41, v234, v63
	v_exp_f32_e32 v64, v41
	v_sub_f32_e32 v41, v249, v63
	v_exp_f32_e32 v62, v41
	v_sub_f32_e32 v41, v248, v63
	v_exp_f32_e32 v60, v41
	v_sub_f32_e32 v41, v247, v63
	v_exp_f32_e32 v58, v41
	v_sub_f32_e32 v41, v246, v63
	v_exp_f32_e32 v92, v40
	v_exp_f32_e32 v56, v41
	v_sub_f32_e32 v41, v245, v63
	v_exp_f32_e32 v54, v41
	v_sub_f32_e32 v41, v244, v63
	v_exp_f32_e32 v52, v41
	v_sub_f32_e32 v41, v243, v63
	v_sub_f32_e32 v40, v235, v63
	v_exp_f32_e32 v50, v41
	v_exp_f32_e32 v48, v40
	v_pk_mul_f32 v[30:31], v[30:31], v[92:93] op_sel_hi:[1,0]
	v_pk_mul_f32 v[28:29], v[28:29], v[92:93] op_sel_hi:[1,0]
	v_pk_mul_f32 v[26:27], v[26:27], v[92:93] op_sel_hi:[1,0]
	v_pk_mul_f32 v[24:25], v[24:25], v[92:93] op_sel_hi:[1,0]
	v_pk_mul_f32 v[22:23], v[22:23], v[92:93] op_sel_hi:[1,0]
	v_pk_mul_f32 v[20:21], v[20:21], v[92:93] op_sel_hi:[1,0]
	v_pk_mul_f32 v[18:19], v[18:19], v[92:93] op_sel_hi:[1,0]
	v_pk_mul_f32 v[16:17], v[16:17], v[92:93] op_sel_hi:[1,0]
	v_cvt_pk_bf16_f32 v40, v65, v69
	v_cvt_pk_bf16_f32 v41, v84, v78
	v_cvt_pk_bf16_f32 v42, v70, v66
	v_cvt_pk_bf16_f32 v43, v64, v62
	v_pk_mul_f32 v[14:15], v[14:15], v[92:93] op_sel_hi:[1,0]
	v_pk_mul_f32 v[12:13], v[12:13], v[92:93] op_sel_hi:[1,0]
	v_pk_mul_f32 v[10:11], v[10:11], v[92:93] op_sel_hi:[1,0]
	v_pk_mul_f32 v[8:9], v[8:9], v[92:93] op_sel_hi:[1,0]
	v_pk_mul_f32 v[6:7], v[6:7], v[92:93] op_sel_hi:[1,0]
	v_pk_mul_f32 v[4:5], v[4:5], v[92:93] op_sel_hi:[1,0]
	v_pk_mul_f32 v[2:3], v[2:3], v[92:93] op_sel_hi:[1,0]
	v_pk_mul_f32 v[0:1], v[0:1], v[92:93] op_sel_hi:[1,0]
	s_waitcnt vmcnt(5)
	v_mfma_f32_32x32x16_bf16 v[16:31], v[212:215], v[40:43], v[16:31]
	global_load_dwordx4 v[36:39], v[96:97], off
	v_add_f32_e32 v65, 0, v65
	v_add_f32_e32 v192, v69, v65
	v_max3_f32 v65, v49, s33, v51
	v_max3_f32 v65, v65, v53, v55
	v_max3_f32 v65, v65, v57, v59
	v_max3_f32 v65, v65, v61, v87
	s_waitcnt vmcnt(5)
	v_mfma_f32_32x32x16_bf16 v[0:15], v[216:219], v[40:43], v[0:15]
	v_add_f32_e64 v40, v120, v94
	v_add_f32_e64 v41, v121, v95
	v_max3_f32 v65, v65, v251, v252
	v_add_f32_e32 v67, v41, v67
	v_fmac_f32_e32 v67, v40, v68
	global_load_dwordx4 v[40:43], v[96:97], off offset:512
	v_max3_f32 v65, v65, v241, v242
	v_max3_f32 v65, v65, v196, v195
	v_max3_f32 v65, v65, v194, v250
	v_mul_f32_e32 v68, v67, v92
	v_mov_b32_e32 v67, v65
	v_sub_f32_e32 v71, v227, v63
	s_nop 0
	v_permlane32_swap_b32_e32 v65, v67
	v_exp_f32_e32 v86, v71
	v_max3_f32 v75, v63, v65, v67
	v_sub_f32_e32 v49, v49, v75
	v_exp_f32_e32 v85, v49
	v_sub_f32_e32 v49, v51, v75
	v_exp_f32_e32 v79, v49
	v_sub_f32_e32 v49, v53, v75
	v_cvt_pk_bf16_f32 v88, v60, v58
	v_cvt_pk_bf16_f32 v89, v56, v54
	v_cvt_pk_bf16_f32 v90, v52, v50
	v_cvt_pk_bf16_f32 v91, v48, v86
	v_exp_f32_e32 v71, v49
	v_sub_f32_e32 v49, v55, v75
	s_waitcnt vmcnt(4)
; #define GAS __attribute__((address_space(1)))
; DI unsigned pk2(float lo, float hi) { f32x2 v = {lo, hi}; bf16x2_t b = __builtin_convertvector(v, bf16x2_t); return __builtin_bit_cast(unsigned, b); }
; DI float swap_max(float m) { auto rr = __builtin_amdgcn_permlane32_swap(__float_as_uint(m), __float_as_uint(m), false, false); return fmaxf(__uint_as_float(rr[0]), __uint_as_float(rr[1])); }
; DI float swap_sum(float m) { auto rr = __builtin_amdgcn_permlane32_swap(__float_as_uint(m), __float_as_uint(m), false, false); return __uint_as_float(rr[0]) + __uint_as_float(rr[1]); }
; DI float ex2(float x) { return __builtin_amdgcn_exp2f(x); }
; #define MFMA32(a, b, c) __builtin_amdgcn_mfma_f32_32x32x16_bf16((a), (b), (c), 0, 0, 0)
; DI void dil_phase(int wv, const bf16_t* QK, const bf16_t* VTg, int rows, int nb, int S, int rr, int pat, bf16_t* OUT, float* LSE) {
;     ...
;             mx = swap_max(mx);
;             const float mnew = fmaxf(mrun, mx), alpha = ex2(mrun - mnew);
;             float ps = 0.f;
; #pragma unroll
;             for (int i = 0; i < 16; ++i) { const float p = ex2(sc[i] - mnew); sc[i] = p; ps += p; }
;             lrun = lrun * alpha + ps; mrun = mnew;
; #pragma unroll
;             for (int cb = 0; cb < 2; ++cb) O[cb] = O[cb] * alpha;
;             u32x4 w0, w1;
;             w0.x = pk2(sc[0], sc[1]); w0.y = pk2(sc[2], sc[3]); w0.z = pk2(sc[4], sc[5]); w0.w = pk2(sc[6], sc[7]);
;             w1.x = pk2(sc[8], sc[9]); w1.y = pk2(sc[10], sc[11]); w1.z = pk2(sc[12], sc[13]); w1.w = pk2(sc[14], sc[15]);
;             const bf16x8 pf0 = __builtin_bit_cast(bf16x8, w0), pf1 = __builtin_bit_cast(bf16x8, w1);
; #pragma unroll
;             for (int cb = 0; cb < 2; ++cb) { O[cb] = MFMA32(vf[cb], pf0, O[cb]); O[cb] = MFMA32(vf[2 + cb], pf1, O[cb]); }
;             if (kb < 4) {
; #pragma unroll
;                 for (int i = 0; i < 4; ++i) { kf[i] = kn[i]; vf[i] = vn[i]; }
;             }
;         }
;     ...
;         const float lt = swap_sum(lrun), inv = __builtin_amdgcn_rcpf(lt);
; #pragma unroll
;         for (int cb = 0; cb < 2; ++cb)
; #pragma unroll
;             for (int j4 = 0; j4 < 4; ++j4) { u32x2 w; w.x = pk2(O[cb][4 * j4] * inv, O[cb][4 * j4 + 1] * inv); w.y = pk2(O[cb][4 * j4 + 2] * inv, O[cb][4 * j4 + 3] * inv); *(GAS u32x2*)(orow + 32 * cb + 8 * j4) = w; }
;         if (hi == 0) *lsep = mrun + __log2f(lt);
	v_mfma_f32_32x32x16_bf16 v[0:15], v[236:239], v[88:91], v[0:15]
	v_exp_f32_e32 v67, v49
	v_sub_f32_e32 v49, v57, v75
	v_exp_f32_e32 v65, v49
	v_sub_f32_e32 v49, v59, v75
	v_sub_f32_e32 v69, v63, v75
	v_exp_f32_e32 v63, v49
	v_sub_f32_e32 v49, v61, v75
	v_exp_f32_e32 v61, v49
	v_sub_f32_e32 v49, v87, v75
	v_exp_f32_e32 v59, v49
	v_exp_f32_e32 v92, v69
	v_mfma_f32_32x32x16_bf16 v[16:31], v[220:223], v[88:91], v[16:31]
	v_cvt_pk_bf16_f32 v88, v85, v79
	v_cvt_pk_bf16_f32 v89, v71, v67
	v_cvt_pk_bf16_f32 v90, v65, v63
	v_cvt_pk_bf16_f32 v91, v61, v59
	v_mul_f32_e64 v14, v14, v92
	v_mul_f32_e64 v15, v15, v92
	v_pk_mul_f32 v[12:13], v[12:13], v[92:93] op_sel_hi:[1,0]
	v_pk_mul_f32 v[10:11], v[10:11], v[92:93] op_sel_hi:[1,0]
	v_pk_mul_f32 v[8:9], v[8:9], v[92:93] op_sel_hi:[1,0]
	v_pk_mul_f32 v[6:7], v[6:7], v[92:93] op_sel_hi:[1,0]
	v_pk_mul_f32 v[4:5], v[4:5], v[92:93] op_sel_hi:[1,0]
	v_pk_mul_f32 v[2:3], v[2:3], v[92:93] op_sel_hi:[1,0]
	v_pk_mul_f32 v[0:1], v[0:1], v[92:93] op_sel_hi:[1,0]
	v_sub_f32_e32 v49, v251, v75
	v_exp_f32_e32 v57, v49
	s_waitcnt vmcnt(2)
	v_mfma_f32_32x32x16_bf16 v[0:15], v[32:35], v[88:91], v[0:15]
	v_add_f32_e64 v32, v84, v192
	v_add_f32_e64 v33, v85, v193
	v_sub_f32_e32 v49, v252, v75
	v_add_f32_e64 v32, v78, v32
	v_add_f32_e64 v33, v79, v33
	v_exp_f32_e32 v55, v49
	v_pk_add_f32 v[32:33], v[70:71], v[32:33]
	v_sub_f32_e32 v49, v241, v75
	v_pk_add_f32 v[32:33], v[66:67], v[32:33]
	v_exp_f32_e32 v53, v49
	v_pk_add_f32 v[32:33], v[64:65], v[32:33]
	v_sub_f32_e32 v49, v242, v75
	v_pk_add_f32 v[32:33], v[62:63], v[32:33]
	v_exp_f32_e32 v51, v49
	v_pk_add_f32 v[32:33], v[60:61], v[32:33]
	v_sub_f32_e32 v49, v196, v75
	v_pk_mul_f32 v[30:31], v[30:31], v[92:93] op_sel_hi:[1,0]
	v_pk_mul_f32 v[28:29], v[28:29], v[92:93] op_sel_hi:[1,0]
	v_pk_mul_f32 v[26:27], v[26:27], v[92:93] op_sel_hi:[1,0]
	v_pk_mul_f32 v[24:25], v[24:25], v[92:93] op_sel_hi:[1,0]
	v_pk_mul_f32 v[22:23], v[22:23], v[92:93] op_sel_hi:[1,0]
	v_pk_mul_f32 v[20:21], v[20:21], v[92:93] op_sel_hi:[1,0]
	v_pk_mul_f32 v[18:19], v[18:19], v[92:93] op_sel_hi:[1,0]
	v_pk_mul_f32 v[16:17], v[16:17], v[92:93] op_sel_hi:[1,0]
	v_pk_add_f32 v[32:33], v[58:59], v[32:33]
	v_exp_f32_e32 v49, v49
	v_sub_f32_e32 v77, v195, v75
	v_mfma_f32_32x32x16_bf16 v[16:31], v[44:47], v[88:91], v[16:31]
	v_add_f32_e64 v32, v56, v32
	v_add_f32_e64 v33, v57, v33
	v_exp_f32_e32 v87, v77
	v_sub_f32_e32 v69, v194, v75
	v_pk_add_f32 v[32:33], v[54:55], v[32:33]
	v_exp_f32_e32 v69, v69
	v_sub_f32_e32 v44, v250, v75
	v_pk_add_f32 v[32:33], v[52:53], v[32:33]
	v_exp_f32_e32 v77, v44
	v_pk_add_f32 v[32:33], v[50:51], v[32:33]
	v_cvt_pk_bf16_f32 v44, v57, v55
	v_pk_add_f32 v[32:33], v[48:49], v[32:33]
	v_cvt_pk_bf16_f32 v45, v53, v51
	v_pk_add_f32 v[32:33], v[86:87], v[32:33]
	v_cvt_pk_bf16_f32 v46, v49, v87
	v_pk_add_f32 v[32:33], v[68:69], v[32:33]
	v_cvt_pk_bf16_f32 v47, v69, v77
	v_add_f32_e32 v33, v77, v33
	v_fmac_f32_e32 v33, v92, v32
	s_waitcnt vmcnt(1)
	v_mfma_f32_32x32x16_bf16 v[16:31], v[36:39], v[44:47], v[16:31]
	v_mov_b32_e32 v32, v33
	s_nop 1
	v_permlane32_swap_b32_e32 v33, v32
	v_add_f32_e32 v32, v33, v32
	v_rcp_f32_e32 v34, v32
	s_mov_b32 s82, 0xff61b1e6
	s_nop 4
	v_pk_mul_f32 v[16:17], v[16:17], v[34:35] op_sel_hi:[1,0]
	s_waitcnt vmcnt(0)
	v_mfma_f32_32x32x16_bf16 v[0:15], v[40:43], v[44:47], v[0:15]
	v_mul_f32_e64 v18, v18, v34
	v_mul_f32_e64 v19, v19, v34
	v_cvt_pk_bf16_f32 v16, v16, v17
	v_cvt_pk_bf16_f32 v17, v18, v19
	global_store_dwordx2 v[80:81], v[16:17], off offset:1024
	v_pk_mul_f32 v[16:17], v[20:21], v[34:35] op_sel_hi:[1,0]
	v_pk_mul_f32 v[18:19], v[22:23], v[34:35] op_sel_hi:[1,0]
	v_cvt_pk_bf16_f32 v16, v16, v17
	s_nop 3
	v_pk_mul_f32 v[0:1], v[0:1], v[34:35] op_sel_hi:[1,0]
	v_pk_mul_f32 v[2:3], v[2:3], v[34:35] op_sel_hi:[1,0]
	v_cvt_pk_bf16_f32 v0, v0, v1
	v_cvt_pk_bf16_f32 v1, v2, v3
	global_store_dwordx2 v[80:81], v[0:1], off offset:1088
	v_pk_mul_f32 v[0:1], v[4:5], v[34:35] op_sel_hi:[1,0]
	v_pk_mul_f32 v[2:3], v[6:7], v[34:35] op_sel_hi:[1,0]
	v_cvt_pk_bf16_f32 v17, v18, v19
	v_cvt_pk_bf16_f32 v0, v0, v1
	v_cvt_pk_bf16_f32 v1, v2, v3
	global_store_dwordx2 v[80:81], v[16:17], off offset:1040
	v_pk_mul_f32 v[16:17], v[24:25], v[34:35] op_sel_hi:[1,0]
	v_pk_mul_f32 v[18:19], v[26:27], v[34:35] op_sel_hi:[1,0]
	global_store_dwordx2 v[80:81], v[0:1], off offset:1104
	v_pk_mul_f32 v[0:1], v[8:9], v[34:35] op_sel_hi:[1,0]
	v_pk_mul_f32 v[2:3], v[10:11], v[34:35] op_sel_hi:[1,0]
	v_cvt_pk_bf16_f32 v16, v16, v17
	v_cvt_pk_bf16_f32 v17, v18, v19
	v_cvt_pk_bf16_f32 v0, v0, v1
	v_cvt_pk_bf16_f32 v1, v2, v3
	global_store_dwordx2 v[80:81], v[16:17], off offset:1056
	v_pk_mul_f32 v[16:17], v[28:29], v[34:35] op_sel_hi:[1,0]
	v_pk_mul_f32 v[18:19], v[30:31], v[34:35] op_sel_hi:[1,0]
	global_store_dwordx2 v[80:81], v[0:1], off offset:1120
	v_pk_mul_f32 v[0:1], v[12:13], v[34:35] op_sel_hi:[1,0]
	v_pk_mul_f32 v[2:3], v[14:15], v[34:35] op_sel_hi:[1,0]
	v_cvt_pk_bf16_f32 v16, v16, v17
	v_cvt_pk_bf16_f32 v17, v18, v19
	v_cvt_pk_bf16_f32 v0, v0, v1
	v_cvt_pk_bf16_f32 v1, v2, v3
	global_store_dwordx2 v[80:81], v[16:17], off offset:1072
	global_store_dwordx2 v[80:81], v[0:1], off offset:1136
	s_and_saveexec_b64 s[72:73], vcc
	s_cbranch_execz .LBB0_406
	v_log_f32_e32 v0, v32
	s_nop 0
	v_add_f32_e32 v0, v75, v0
	global_store_dword v[82:83], v0, off
	s_branch .LBB0_406

; #define LAS __attribute__((address_space(3)))
; #define GAS __attribute__((address_space(1)))
;     DI f32x4 conv1(const Acc& acc, int ai, int bj, int n, int m, int fr, const f32x4& above, const f32x4& below, const f32x4& w0, const f32x4& w1, const f32x4& w2, const f32x4& b, bool zp, bool zn) const {
;         const f32x4 cur = acc[ai][bj][m][n];
;         const f32x4 tp = (m > 0 && fr == 15) ? acc[ai][bj][m > 0 ? m - 1 : 0][n] : cur;
;         const f32x4 tn = (m < 3 && fr == 0) ? acc[ai][bj][m < 3 ? m + 1 : 3][n] : cur;
;         f32x4 pv = ror4(tp), nx = rol4(tn);
;         if (m == 0 && fr == 0) pv = above;
;         if (m == 3 && fr == 15) nx = below;
;         if (zp) pv = (f32x4){0.f, 0.f, 0.f, 0.f};
;         if (zn) nx = (f32x4){0.f, 0.f, 0.f, 0.f};
;         return b + w0 * pv + w1 * cur + w2 * nx;
;     }
;     DI void operator()(const Acc& acc, const Unit& u, int wr, int wc, int fr, int fq, LAS unsigned char* scr) const {
;         LAS float* H = (LAS float*)scr;
;         const int colb = wc * 32 + 8 * fq;
;         if (fr == 0 || fr == 15) {
; #pragma unroll
;             for (int ai = 0; ai < 2; ++ai)
; #pragma unroll
;                 for (int bj = 0; bj < 2; ++bj)
; #pragma unroll
;                     for (int n = 0; n < 2; ++n) {
;                         LAS f32x4* dst = (LAS f32x4*)(H + (((2 * ai + wr) * 2 + (fr == 0 ? 0 : 1)) * 256 + bj * HALF + colb + 4 * n));
;                         *dst = (fr == 0) ? acc[ai][bj][0][n] : acc[ai][bj][3][n];
;                     }
;         }
;         asm volatile("s_waitcnt lgkmcnt(0)" ::: "memory"); __builtin_amdgcn_s_barrier(); asm volatile("" ::: "memory");
;         const int f0 = u.pn * 128 + colb;
;         const int row_base = 254 * u.pm - 1;
; #pragma unroll
;         for (int ai = 0; ai < 2; ++ai) {
;             const int k = 2 * ai + wr, ka = k > 0 ? k - 1 : 0, kb = k < 3 ? k + 1 : 3;
; #pragma unroll
;             for (int n = 0; n < 2; ++n) {
;                 const float* wp = cw + f0 + 4 * n;
;                 const f32x4 g0 = *(const f32x4*)wp, g1 = *(const GAS f32x4*)(wp + DFF2), g2 = *(const GAS f32x4*)(wp + 2 * DFF2), gb = *(const GAS f32x4*)(cb + f0 + 4 * n);
;                 const f32x4 v0 = *(const GAS f32x4*)(wp + DFF), v1 = *(const GAS f32x4*)(wp + DFF + DFF2), v2 = *(const GAS f32x4*)(wp + DFF + 2 * DFF2), vb = *(const GAS f32x4*)(cb + DFF + f0 + 4 * n);
.LBB0_820:
	s_or_b64 exec, exec, s[54:55]
	v_add_u32_e32 v190, s47, v210
	s_movk_i32 s28, 0x3fff
	v_cmp_lt_i32_e32 vcc, s28, v190
	v_mov_b32_e32 v189, 0xfff
	v_mov_b32_e32 v191, 0x3fff
	v_cndmask_b32_e64 v125, v117, v125, s[8:9]
	v_mov_b32_e32 v202, v193
	v_cndmask_b32_e32 v201, v189, v191, vcc
	v_cndmask_b32_e64 v126, v118, v126, s[8:9]
	v_cndmask_b32_e64 v124, v116, v124, s[8:9]
	v_cndmask_b32_e64 v189, v118, v110, s[6:7]
	v_mov_b32_e32 v196, v193
	v_mov_b32_dpp v202, v125 row_ror:1 row_mask:0xf bank_mask:0xf
	v_mov_b32_e32 v197, v193
	v_mov_b32_e32 v125, v193
	v_cndmask_b32_e64 v127, v119, v127, s[8:9]
	v_cndmask_b32_e64 v191, v119, v111, s[6:7]
	v_cndmask_b32_e64 v194, v117, v109, s[6:7]
	v_cndmask_b32_e64 v195, v116, v108, s[6:7]
	v_mov_b32_dpp v196, v124 row_ror:1 row_mask:0xf bank_mask:0xf
	v_mov_b32_dpp v197, v126 row_ror:1 row_mask:0xf bank_mask:0xf
	v_mov_b32_e32 v203, v193
	v_mov_b32_e32 v124, v193
	v_mov_b32_e32 v126, v193
	v_mov_b32_dpp v125, v189 row_ror:15 row_mask:0xf bank_mask:0xf
	v_mov_b32_e32 v189, v193
	v_mov_b32_dpp v203, v127 row_ror:1 row_mask:0xf bank_mask:0xf
	v_mov_b32_dpp v124, v195 row_ror:15 row_mask:0xf bank_mask:0xf
	v_mov_b32_dpp v126, v194 row_ror:15 row_mask:0xf bank_mask:0xf
	v_mov_b32_dpp v189, v191 row_ror:15 row_mask:0xf bank_mask:0xf
	v_cndmask_b32_e64 v123, v115, v123, s[8:9]
	v_cndmask_b32_e64 v122, v114, v122, s[8:9]
	v_cndmask_b32_e64 v121, v113, v121, s[8:9]
	v_cndmask_b32_e64 v120, v112, v120, s[8:9]
	v_mov_b32_e32 v127, v193
	v_mov_b32_e32 v194, v193
	v_mov_b32_e32 v191, v193
	v_mov_b32_e32 v195, v193
	s_mov_b32 s28, 0xc000
	v_add_u32_e32 v204, s33, v210
	v_cndmask_b32_e64 v205, v115, v107, s[6:7]
	v_cndmask_b32_e64 v223, v114, v106, s[6:7]
	v_cndmask_b32_e64 v224, v113, v105, s[6:7]
	v_cndmask_b32_e64 v225, v112, v104, s[6:7]
	v_mov_b32_dpp v127, v120 row_ror:1 row_mask:0xf bank_mask:0xf
	v_mov_b32_dpp v194, v121 row_ror:1 row_mask:0xf bank_mask:0xf
	v_mov_b32_dpp v191, v122 row_ror:1 row_mask:0xf bank_mask:0xf
	v_mov_b32_dpp v195, v123 row_ror:1 row_mask:0xf bank_mask:0xf
	v_mov_b32_e32 v120, v193
	v_mov_b32_e32 v122, v193
	v_mov_b32_e32 v121, v193
	v_mov_b32_e32 v123, v193
	v_cmp_gt_u32_e32 vcc, s28, v190
	v_mov_b32_dpp v120, v225 row_ror:15 row_mask:0xf bank_mask:0xf
	v_mov_b32_dpp v122, v224 row_ror:15 row_mask:0xf bank_mask:0xf
	v_mov_b32_dpp v121, v223 row_ror:15 row_mask:0xf bank_mask:0xf
	v_mov_b32_dpp v123, v205 row_ror:15 row_mask:0xf bank_mask:0xf
	s_and_b64 s[54:55], s[12:13], vcc
	v_and_b32_e32 v225, v201, v190
	v_and_b32_e32 v201, v201, v204
	v_mul_lo_u32 v190, v190, s89
	s_and_saveexec_b64 s[56:57], s[54:55]
	s_cbranch_execz .LBB0_822
	v_cmp_eq_u32_e32 vcc, 0, v225
	v_cmp_eq_u32_e64 s[28:29], 0, v201
	s_nop 0
	v_cndmask_b32_e64 v205, v202, 0, vcc
	v_cndmask_b32_e64 v204, v196, 0, vcc
	v_cndmask_b32_e64 v203, v203, 0, vcc
	v_cndmask_b32_e64 v202, v197, 0, vcc
	s_waitcnt lgkmcnt(0)
	v_pk_fma_f32 v[196:197], v[150:151], v[202:203], v[166:167]
	v_pk_fma_f32 v[202:203], v[148:149], v[204:205], v[164:165]
	v_pk_fma_f32 v[196:197], v[118:119], v[158:159], v[196:197]
	v_pk_fma_f32 v[202:203], v[116:117], v[156:157], v[202:203]
	v_cndmask_b32_e64 v205, v126, 0, s[28:29]
	v_cndmask_b32_e64 v204, v124, 0, s[28:29]
	v_cndmask_b32_e64 v227, v189, 0, s[28:29]
	v_cndmask_b32_e64 v226, v125, 0, s[28:29]
	v_pk_fma_f32 v[124:125], v[138:139], v[226:227], v[196:197]
	v_pk_fma_f32 v[196:197], v[136:137], v[204:205], v[202:203]
	v_cndmask_b32_e64 v202, v127, 0, vcc
	v_cndmask_b32_e64 v127, v195, 0, vcc
	v_cndmask_b32_e64 v126, v191, 0, vcc
	v_cndmask_b32_e64 v203, v194, 0, vcc
	v_pk_fma_f32 v[126:127], v[142:143], v[126:127], v[154:155]
	v_pk_fma_f32 v[194:195], v[140:141], v[202:203], v[152:153]
	v_pk_fma_f32 v[126:127], v[114:115], v[134:135], v[126:127]
	v_cndmask_b32_e64 v203, v122, 0, s[28:29]
	v_cndmask_b32_e64 v123, v123, 0, s[28:29]
	v_cndmask_b32_e64 v122, v121, 0, s[28:29]
	v_cndmask_b32_e64 v202, v120, 0, s[28:29]
	v_pk_fma_f32 v[120:121], v[130:131], v[122:123], v[126:127]
	v_mul_f32_e32 v122, 0x3d372713, v196
	v_mul_f32_e32 v122, v196, v122
	v_fma_f32 v122, v196, v122, v196
	v_mul_f32_e32 v122, 0x3f4c422a, v122
	v_mul_f32_e32 v122, 0x4038aa3b, v122
	v_mul_f32_e32 v189, 0x3d372713, v124
	v_exp_f32_e32 v126, v122
	v_mul_f32_e32 v122, 0x3d372713, v197
	v_mul_f32_e32 v189, v124, v189
	v_mul_f32_e32 v191, 0x3d372713, v125
	v_mul_f32_e32 v122, v197, v122
	v_fma_f32 v189, v124, v189, v124
	v_mul_f32_e32 v191, v125, v191
	v_fma_f32 v122, v197, v122, v197
	v_mul_f32_e32 v189, 0x3f4c422a, v189
	v_fma_f32 v191, v125, v191, v125
	v_mul_f32_e32 v122, 0x3f4c422a, v122
	v_mul_f32_e32 v189, 0x4038aa3b, v189
	v_mul_f32_e32 v191, 0x3f4c422a, v191
	v_mul_f32_e32 v122, 0x4038aa3b, v122
	v_exp_f32_e32 v189, v189
	v_mul_f32_e32 v191, 0x4038aa3b, v191
	v_exp_f32_e32 v127, v122
	v_exp_f32_e32 v191, v191
	v_pk_fma_f32 v[194:195], v[112:113], v[132:133], v[194:195]
	v_add_f32_e32 v189, 1.0, v189
	v_pk_fma_f32 v[122:123], v[128:129], v[202:203], v[194:195]
	v_add_f32_e32 v126, 1.0, v126
	v_add_f32_e32 v127, 1.0, v127
	v_rcp_f32_e32 v194, v189
	v_add_f32_e32 v189, 1.0, v191
	v_rcp_f32_e32 v126, v126
	v_rcp_f32_e32 v127, v127
	v_rcp_f32_e32 v195, v189
	v_mov_b32_e32 v191, v193
	v_pk_fma_f32 v[126:127], v[196:197], v[126:127], v[196:197] neg_lo:[1,0,0] neg_hi:[1,0,0]
	v_pk_fma_f32 v[124:125], v[124:125], v[194:195], v[124:125] neg_lo:[1,0,0] neg_hi:[1,0,0]
	v_pk_mul_f32 v[122:123], v[122:123], v[126:127]
	v_pk_mul_f32 v[120:121], v[120:121], v[124:125]
	v_cvt_pk_bf16_f32 v122, v122, v123
	v_cvt_pk_bf16_f32 v123, v120, v121
	v_lshl_add_u64 v[120:121], s[34:35], 0, v[190:191]
	v_lshl_add_u64 v[120:121], v[180:181], 1, v[120:121]
	global_store_dwordx2 v[120:121], v[122:123], off
; #define LAS __attribute__((address_space(3)))
; #define GAS __attribute__((address_space(1)))
;     DI f32x4 conv1(const Acc& acc, int ai, int bj, int n, int m, int fr, const f32x4& above, const f32x4& below, const f32x4& w0, const f32x4& w1, const f32x4& w2, const f32x4& b, bool zp, bool zn) const {
;         const f32x4 cur = acc[ai][bj][m][n];
;         const f32x4 tp = (m > 0 && fr == 15) ? acc[ai][bj][m > 0 ? m - 1 : 0][n] : cur;
;         const f32x4 tn = (m < 3 && fr == 0) ? acc[ai][bj][m < 3 ? m + 1 : 3][n] : cur;
;         f32x4 pv = ror4(tp), nx = rol4(tn);
;         if (m == 0 && fr == 0) pv = above;
;         if (m == 3 && fr == 15) nx = below;
;         if (zp) pv = (f32x4){0.f, 0.f, 0.f, 0.f};
;         if (zn) nx = (f32x4){0.f, 0.f, 0.f, 0.f};
;         return b + w0 * pv + w1 * cur + w2 * nx;
;     }
;     DI void operator()(const Acc& acc, const Unit& u, int wr, int wc, int fr, int fq, LAS unsigned char* scr) const {
;         LAS float* H = (LAS float*)scr;
;         const int colb = wc * 32 + 8 * fq;
;         if (fr == 0 || fr == 15) {
; #pragma unroll
;             for (int ai = 0; ai < 2; ++ai)
; #pragma unroll
;                 for (int bj = 0; bj < 2; ++bj)
; #pragma unroll
;                     for (int n = 0; n < 2; ++n) {
;                         LAS f32x4* dst = (LAS f32x4*)(H + (((2 * ai + wr) * 2 + (fr == 0 ? 0 : 1)) * 256 + bj * HALF + colb + 4 * n));
;                         *dst = (fr == 0) ? acc[ai][bj][0][n] : acc[ai][bj][3][n];
;                     }
;         }
;         asm volatile("s_waitcnt lgkmcnt(0)" ::: "memory"); __builtin_amdgcn_s_barrier(); asm volatile("" ::: "memory");
;         const int f0 = u.pn * 128 + colb;
;         const int row_base = 254 * u.pm - 1;
; #pragma unroll
;         for (int ai = 0; ai < 2; ++ai) {
;             const int k = 2 * ai + wr, ka = k > 0 ? k - 1 : 0, kb = k < 3 ? k + 1 : 3;
; #pragma unroll
;             for (int n = 0; n < 2; ++n) {
;                 const float* wp = cw + f0 + 4 * n;
;                 const f32x4 g0 = *(const f32x4*)wp, g1 = *(const GAS f32x4*)(wp + DFF2), g2 = *(const GAS f32x4*)(wp + 2 * DFF2), gb = *(const GAS f32x4*)(cb + f0 + 4 * n);
;                 const f32x4 v0 = *(const GAS f32x4*)(wp + DFF), v1 = *(const GAS f32x4*)(wp + DFF + DFF2), v2 = *(const GAS f32x4*)(wp + DFF + 2 * DFF2), vb = *(const GAS f32x4*)(cb + DFF + f0 + 4 * n);
.LBB0_822:
	s_or_b64 exec, exec, s[56:57]
	v_add_u32_e32 v189, s47, v211
	s_movk_i32 s28, 0x3fff
	v_cmp_lt_i32_e32 vcc, s28, v189
	v_mov_b32_e32 v120, 0xfff
	v_mov_b32_e32 v121, 0x3fff
	v_cndmask_b32_e64 v117, v109, v117, s[8:9]
	v_mov_b32_e32 v126, v193
	v_cndmask_b32_e32 v191, v120, v121, vcc
	v_cndmask_b32_e64 v118, v110, v118, s[8:9]
	v_cndmask_b32_e64 v116, v108, v116, s[8:9]
	v_cndmask_b32_e64 v120, v110, v102, s[6:7]
	v_mov_b32_e32 v124, v193
	v_mov_b32_dpp v126, v117 row_ror:1 row_mask:0xf bank_mask:0xf
	v_mov_b32_e32 v125, v193
	v_mov_b32_e32 v117, v193
	v_cndmask_b32_e64 v119, v111, v119, s[8:9]
	v_cndmask_b32_e64 v121, v111, v103, s[6:7]
	v_cndmask_b32_e64 v122, v109, v101, s[6:7]
	v_cndmask_b32_e64 v123, v108, v100, s[6:7]
	v_mov_b32_dpp v124, v116 row_ror:1 row_mask:0xf bank_mask:0xf
	v_mov_b32_dpp v125, v118 row_ror:1 row_mask:0xf bank_mask:0xf
	v_mov_b32_e32 v127, v193
	v_mov_b32_e32 v116, v193
	v_mov_b32_e32 v118, v193
	v_mov_b32_dpp v117, v120 row_ror:15 row_mask:0xf bank_mask:0xf
	v_mov_b32_e32 v120, v193
	v_mov_b32_dpp v127, v119 row_ror:1 row_mask:0xf bank_mask:0xf
	v_mov_b32_dpp v116, v123 row_ror:15 row_mask:0xf bank_mask:0xf
	v_mov_b32_dpp v118, v122 row_ror:15 row_mask:0xf bank_mask:0xf
	v_mov_b32_dpp v120, v121 row_ror:15 row_mask:0xf bank_mask:0xf
	v_cndmask_b32_e64 v115, v107, v115, s[8:9]
	v_cndmask_b32_e64 v114, v106, v114, s[8:9]
	v_cndmask_b32_e64 v113, v105, v113, s[8:9]
	v_cndmask_b32_e64 v112, v104, v112, s[8:9]
	v_mov_b32_e32 v119, v193
	v_mov_b32_e32 v122, v193
	v_mov_b32_e32 v121, v193
	v_mov_b32_e32 v123, v193
	s_mov_b32 s28, 0xc000
	v_add_u32_e32 v194, s33, v211
	v_cndmask_b32_e64 v195, v107, v99, s[6:7]
	v_cndmask_b32_e64 v196, v106, v98, s[6:7]
	v_cndmask_b32_e64 v197, v105, v97, s[6:7]
	v_cndmask_b32_e64 v202, v104, v96, s[6:7]
	v_mov_b32_dpp v119, v112 row_ror:1 row_mask:0xf bank_mask:0xf
	v_mov_b32_dpp v122, v113 row_ror:1 row_mask:0xf bank_mask:0xf
	v_mov_b32_dpp v121, v114 row_ror:1 row_mask:0xf bank_mask:0xf
	v_mov_b32_dpp v123, v115 row_ror:1 row_mask:0xf bank_mask:0xf
	v_mov_b32_e32 v112, v193
	v_mov_b32_e32 v114, v193
	v_mov_b32_e32 v113, v193
	v_mov_b32_e32 v115, v193
	v_cmp_gt_u32_e32 vcc, s28, v189
	v_mov_b32_dpp v112, v202 row_ror:15 row_mask:0xf bank_mask:0xf
	v_mov_b32_dpp v114, v197 row_ror:15 row_mask:0xf bank_mask:0xf
	v_mov_b32_dpp v113, v196 row_ror:15 row_mask:0xf bank_mask:0xf
	v_mov_b32_dpp v115, v195 row_ror:15 row_mask:0xf bank_mask:0xf
	s_and_b64 s[56:57], s[14:15], vcc
	v_and_b32_e32 v226, v191, v189
	v_and_b32_e32 v223, v191, v194
	v_mul_lo_u32 v202, v189, s89
	s_and_saveexec_b64 s[58:59], s[56:57]
	s_cbranch_execz .LBB0_824
	v_cmp_eq_u32_e32 vcc, 0, v226
	v_cmp_eq_u32_e64 s[28:29], 0, v223
	v_mov_b32_e32 v203, v193
	v_cndmask_b32_e64 v195, v126, 0, vcc
	v_cndmask_b32_e64 v194, v124, 0, vcc
	v_cndmask_b32_e64 v127, v127, 0, vcc
	v_cndmask_b32_e64 v126, v125, 0, vcc
	s_waitcnt lgkmcnt(0)
	v_pk_fma_f32 v[124:125], v[150:151], v[126:127], v[166:167]
	v_pk_fma_f32 v[126:127], v[148:149], v[194:195], v[164:165]
	v_pk_fma_f32 v[124:125], v[110:111], v[158:159], v[124:125]
	v_pk_fma_f32 v[126:127], v[108:109], v[156:157], v[126:127]
	v_cndmask_b32_e64 v195, v118, 0, s[28:29]
	v_cndmask_b32_e64 v194, v116, 0, s[28:29]
	v_cndmask_b32_e64 v197, v120, 0, s[28:29]
	v_cndmask_b32_e64 v196, v117, 0, s[28:29]
	v_pk_fma_f32 v[116:117], v[138:139], v[196:197], v[124:125]
	v_pk_fma_f32 v[124:125], v[136:137], v[194:195], v[126:127]
	v_cndmask_b32_e64 v126, v119, 0, vcc
	v_cndmask_b32_e64 v119, v123, 0, vcc
	v_cndmask_b32_e64 v118, v121, 0, vcc
	v_pk_fma_f32 v[118:119], v[142:143], v[118:119], v[154:155]
	v_cndmask_b32_e64 v123, v114, 0, s[28:29]
	v_pk_fma_f32 v[118:119], v[106:107], v[134:135], v[118:119]
	v_cndmask_b32_e64 v115, v115, 0, s[28:29]
	v_cndmask_b32_e64 v114, v113, 0, s[28:29]
	v_cndmask_b32_e64 v127, v122, 0, vcc
	v_cndmask_b32_e64 v122, v112, 0, s[28:29]
	v_pk_fma_f32 v[112:113], v[130:131], v[114:115], v[118:119]
	v_mul_f32_e32 v114, 0x3d372713, v124
	v_mul_f32_e32 v114, v124, v114
	v_fma_f32 v114, v124, v114, v124
	v_mul_f32_e32 v114, 0x3f4c422a, v114
	v_mul_f32_e32 v114, 0x4038aa3b, v114
	v_exp_f32_e32 v118, v114
	v_mul_f32_e32 v114, 0x3d372713, v125
	v_mul_f32_e32 v114, v125, v114
	v_fma_f32 v114, v125, v114, v125
	v_pk_fma_f32 v[120:121], v[140:141], v[126:127], v[152:153]
	v_mul_f32_e32 v114, 0x3f4c422a, v114
	v_pk_fma_f32 v[120:121], v[104:105], v[132:133], v[120:121]
	v_mul_f32_e32 v114, 0x4038aa3b, v114
	v_exp_f32_e32 v119, v114
	v_pk_fma_f32 v[114:115], v[128:129], v[122:123], v[120:121]
	v_mul_f32_e32 v120, 0x3d372713, v116
	v_mul_f32_e32 v121, 0x3d372713, v117
	v_mul_f32_e32 v120, v116, v120
	v_mul_f32_e32 v121, v117, v121
	v_fma_f32 v120, v116, v120, v116
	v_fma_f32 v121, v117, v121, v117
	v_mul_f32_e32 v120, 0x3f4c422a, v120
	v_mul_f32_e32 v121, 0x3f4c422a, v121
	v_mul_f32_e32 v120, 0x4038aa3b, v120
	v_mul_f32_e32 v121, 0x4038aa3b, v121
	v_exp_f32_e32 v120, v120
	v_exp_f32_e32 v121, v121
	v_add_f32_e32 v118, 1.0, v118
	v_add_f32_e32 v119, 1.0, v119
	v_add_f32_e32 v120, 1.0, v120
	v_add_f32_e32 v121, 1.0, v121
	v_rcp_f32_e32 v118, v118
	v_rcp_f32_e32 v119, v119
	v_rcp_f32_e32 v120, v120
	v_rcp_f32_e32 v121, v121
	v_pk_fma_f32 v[118:119], v[124:125], v[118:119], v[124:125] neg_lo:[1,0,0] neg_hi:[1,0,0]
	s_nop 0
	v_pk_mul_f32 v[114:115], v[114:115], v[118:119]
	v_pk_fma_f32 v[116:117], v[116:117], v[120:121], v[116:117] neg_lo:[1,0,0] neg_hi:[1,0,0]
	v_cvt_pk_bf16_f32 v114, v114, v115
	v_pk_mul_f32 v[112:113], v[112:113], v[116:117]
	s_nop 0
	v_cvt_pk_bf16_f32 v115, v112, v113
	v_lshl_add_u64 v[112:113], s[34:35], 0, v[202:203]
	v_lshl_add_u64 v[112:113], v[180:181], 1, v[112:113]
	global_store_dwordx2 v[112:113], v[114:115], off
; #define LAS __attribute__((address_space(3)))
; #define GAS __attribute__((address_space(1)))
;     DI f32x4 conv1(const Acc& acc, int ai, int bj, int n, int m, int fr, const f32x4& above, const f32x4& below, const f32x4& w0, const f32x4& w1, const f32x4& w2, const f32x4& b, bool zp, bool zn) const {
;         const f32x4 cur = acc[ai][bj][m][n];
;         const f32x4 tp = (m > 0 && fr == 15) ? acc[ai][bj][m > 0 ? m - 1 : 0][n] : cur;
;         const f32x4 tn = (m < 3 && fr == 0) ? acc[ai][bj][m < 3 ? m + 1 : 3][n] : cur;
;         f32x4 pv = ror4(tp), nx = rol4(tn);
;         if (m == 0 && fr == 0) pv = above;
;         if (m == 3 && fr == 15) nx = below;
;         if (zp) pv = (f32x4){0.f, 0.f, 0.f, 0.f};
;         if (zn) nx = (f32x4){0.f, 0.f, 0.f, 0.f};
;         return b + w0 * pv + w1 * cur + w2 * nx;
;     }
;     DI void operator()(const Acc& acc, const Unit& u, int wr, int wc, int fr, int fq, LAS unsigned char* scr) const {
;         LAS float* H = (LAS float*)scr;
;         const int colb = wc * 32 + 8 * fq;
;         if (fr == 0 || fr == 15) {
; #pragma unroll
;             for (int ai = 0; ai < 2; ++ai)
; #pragma unroll
;                 for (int bj = 0; bj < 2; ++bj)
; #pragma unroll
;                     for (int n = 0; n < 2; ++n) {
;                         LAS f32x4* dst = (LAS f32x4*)(H + (((2 * ai + wr) * 2 + (fr == 0 ? 0 : 1)) * 256 + bj * HALF + colb + 4 * n));
;                         *dst = (fr == 0) ? acc[ai][bj][0][n] : acc[ai][bj][3][n];
;                     }
;         }
;         asm volatile("s_waitcnt lgkmcnt(0)" ::: "memory"); __builtin_amdgcn_s_barrier(); asm volatile("" ::: "memory");
;         const int f0 = u.pn * 128 + colb;
;         const int row_base = 254 * u.pm - 1;
; #pragma unroll
;         for (int ai = 0; ai < 2; ++ai) {
;             const int k = 2 * ai + wr, ka = k > 0 ? k - 1 : 0, kb = k < 3 ? k + 1 : 3;
; #pragma unroll
;             for (int n = 0; n < 2; ++n) {
;                 const float* wp = cw + f0 + 4 * n;
;                 const f32x4 g0 = *(const f32x4*)wp, g1 = *(const GAS f32x4*)(wp + DFF2), g2 = *(const GAS f32x4*)(wp + 2 * DFF2), gb = *(const GAS f32x4*)(cb + f0 + 4 * n);
;                 const f32x4 v0 = *(const GAS f32x4*)(wp + DFF), v1 = *(const GAS f32x4*)(wp + DFF + DFF2), v2 = *(const GAS f32x4*)(wp + DFF + 2 * DFF2), vb = *(const GAS f32x4*)(cb + DFF + f0 + 4 * n);
.LBB0_824:
	s_or_b64 exec, exec, s[58:59]
	v_add_u32_e32 v120, s47, v212
	s_movk_i32 s28, 0x3fff
	v_cmp_lt_i32_e32 vcc, s28, v120
	v_mov_b32_e32 v112, 0xfff
	v_mov_b32_e32 v113, 0x3fff
	v_cndmask_b32_e64 v110, v102, v110, s[8:9]
	v_cndmask_b32_e64 v109, v101, v109, s[8:9]
	v_cndmask_b32_e64 v108, v100, v108, s[8:9]
	v_mov_b32_e32 v116, v193
	v_mov_b32_e32 v118, v193
	v_mov_b32_e32 v117, v193
	v_cndmask_b32_e32 v121, v112, v113, vcc
	v_cndmask_b32_e64 v111, v103, v111, s[8:9]
	v_mov_b32_dpp v116, v108 row_ror:1 row_mask:0xf bank_mask:0xf
	v_mov_b32_dpp v118, v109 row_ror:1 row_mask:0xf bank_mask:0xf
	v_mov_b32_dpp v117, v110 row_ror:1 row_mask:0xf bank_mask:0xf
	v_mov_b32_e32 v119, v193
	v_cndmask_b32_e64 v107, v99, v107, s[8:9]
	v_cndmask_b32_e64 v106, v98, v106, s[8:9]
	v_cndmask_b32_e64 v105, v97, v105, s[8:9]
	v_cndmask_b32_e64 v104, v96, v104, s[8:9]
	v_mov_b32_e32 v108, v193
	v_mov_b32_e32 v110, v193
	v_mov_b32_e32 v109, v193
	v_mov_b32_e32 v113, v193
	s_mov_b32 s28, 0xc000
	v_add_u32_e32 v122, s33, v212
	v_mov_b32_dpp v119, v111 row_ror:1 row_mask:0xf bank_mask:0xf
	v_mov_b32_e32 v111, v193
	v_mov_b32_e32 v112, v193
	v_mov_b32_e32 v114, v193
	v_mov_b32_e32 v115, v193
	v_mov_b32_dpp v108, v104 row_ror:1 row_mask:0xf bank_mask:0xf
	v_mov_b32_dpp v110, v105 row_ror:1 row_mask:0xf bank_mask:0xf
	v_mov_b32_dpp v109, v106 row_ror:1 row_mask:0xf bank_mask:0xf
	v_mov_b32_dpp v113, v107 row_ror:1 row_mask:0xf bank_mask:0xf
	v_mov_b32_e32 v104, v193
	v_mov_b32_e32 v105, v193
	v_mov_b32_e32 v106, v193
	v_mov_b32_e32 v107, v193
	v_cmp_gt_u32_e32 vcc, s28, v120
	v_mov_b32_dpp v111, v100 row_ror:15 row_mask:0xf bank_mask:0xf
	v_mov_b32_dpp v112, v101 row_ror:15 row_mask:0xf bank_mask:0xf
	v_mov_b32_dpp v114, v102 row_ror:15 row_mask:0xf bank_mask:0xf
	v_mov_b32_dpp v115, v103 row_ror:15 row_mask:0xf bank_mask:0xf
	v_mov_b32_dpp v104, v96 row_ror:15 row_mask:0xf bank_mask:0xf
	v_mov_b32_dpp v105, v97 row_ror:15 row_mask:0xf bank_mask:0xf
	v_mov_b32_dpp v106, v98 row_ror:15 row_mask:0xf bank_mask:0xf
	v_mov_b32_dpp v107, v99 row_ror:15 row_mask:0xf bank_mask:0xf
	s_and_b64 s[58:59], s[16:17], vcc
	v_and_b32_e32 v227, v121, v120
	v_and_b32_e32 v224, v121, v122
	v_mul_lo_u32 v204, v120, s89
	s_and_saveexec_b64 s[60:61], s[58:59]
	s_cbranch_execz .LBB0_826
	v_cmp_eq_u32_e32 vcc, 0, v227
	s_waitcnt lgkmcnt(0)
	v_cndmask_b32_e64 v112, v112, v161, s[8:9]
	v_cmp_eq_u32_e64 s[28:29], 0, v224
	v_cndmask_b32_e64 v121, v118, 0, vcc
	v_cndmask_b32_e64 v119, v119, 0, vcc
	v_cndmask_b32_e64 v118, v117, 0, vcc
	v_cndmask_b32_e64 v120, v116, 0, vcc
	v_pk_fma_f32 v[116:117], v[150:151], v[118:119], v[166:167]
	v_pk_fma_f32 v[118:119], v[148:149], v[120:121], v[164:165]
	v_pk_fma_f32 v[102:103], v[102:103], v[158:159], v[116:117]
	v_cndmask_b32_e64 v117, v115, v163, s[8:9]
	v_cndmask_b32_e64 v111, v111, v160, s[8:9]
	v_cndmask_b32_e64 v115, v112, 0, s[28:29]
	v_cndmask_b32_e64 v113, v113, 0, vcc
	v_cndmask_b32_e64 v112, v109, 0, vcc
	v_pk_fma_f32 v[100:101], v[100:101], v[156:157], v[118:119]
	v_cndmask_b32_e64 v116, v114, v162, s[8:9]
	v_cndmask_b32_e64 v114, v111, 0, s[28:29]
	v_cndmask_b32_e64 v111, v110, 0, vcc
	v_cndmask_b32_e64 v110, v108, 0, vcc
	v_pk_fma_f32 v[108:109], v[142:143], v[112:113], v[154:155]
	v_cndmask_b32_e64 v106, v106, v146, s[8:9]
	v_cndmask_b32_e64 v107, v107, v147, s[8:9]
	v_pk_fma_f32 v[100:101], v[136:137], v[114:115], v[100:101]
	v_pk_fma_f32 v[98:99], v[98:99], v[134:135], v[108:109]
	v_cndmask_b32_e64 v107, v107, 0, s[28:29]
	v_cndmask_b32_e64 v106, v106, 0, s[28:29]
	v_pk_fma_f32 v[98:99], v[130:131], v[106:107], v[98:99]
	v_mul_f32_e32 v106, 0x3d372713, v100
	v_mul_f32_e32 v107, 0x3d372713, v101
	v_mul_f32_e32 v106, v100, v106
	v_mul_f32_e32 v107, v101, v107
	v_fma_f32 v106, v100, v106, v100
	v_fma_f32 v107, v101, v107, v101
	v_mul_f32_e32 v106, 0x3f4c422a, v106
	v_mul_f32_e32 v107, 0x3f4c422a, v107
	v_mul_f32_e32 v106, 0x4038aa3b, v106
	v_mul_f32_e32 v107, 0x4038aa3b, v107
	v_exp_f32_e32 v106, v106
	v_exp_f32_e32 v107, v107
	v_cndmask_b32_e64 v117, v117, 0, s[28:29]
	v_cndmask_b32_e64 v116, v116, 0, s[28:29]
	v_pk_fma_f32 v[110:111], v[140:141], v[110:111], v[152:153]
	v_cndmask_b32_e64 v104, v104, v144, s[8:9]
	v_cndmask_b32_e64 v105, v105, v145, s[8:9]
	v_pk_fma_f32 v[102:103], v[138:139], v[116:117], v[102:103]
	v_pk_fma_f32 v[96:97], v[96:97], v[132:133], v[110:111]
	v_cndmask_b32_e64 v105, v105, 0, s[28:29]
	v_cndmask_b32_e64 v104, v104, 0, s[28:29]
	v_pk_fma_f32 v[96:97], v[128:129], v[104:105], v[96:97]
	v_add_f32_e32 v104, 1.0, v106
	v_add_f32_e32 v105, 1.0, v107
	v_mul_f32_e32 v106, 0x3d372713, v102
	v_mul_f32_e32 v107, 0x3d372713, v103
	v_mul_f32_e32 v106, v102, v106
	v_mul_f32_e32 v107, v103, v107
	v_fma_f32 v106, v102, v106, v102
	v_fma_f32 v107, v103, v107, v103
	v_mul_f32_e32 v106, 0x3f4c422a, v106
	v_mul_f32_e32 v107, 0x3f4c422a, v107
	v_mul_f32_e32 v106, 0x4038aa3b, v106
	v_mul_f32_e32 v107, 0x4038aa3b, v107
	v_exp_f32_e32 v106, v106
	v_exp_f32_e32 v107, v107
	v_rcp_f32_e32 v104, v104
	v_rcp_f32_e32 v105, v105
	v_add_f32_e32 v106, 1.0, v106
	v_add_f32_e32 v107, 1.0, v107
	v_rcp_f32_e32 v106, v106
	v_rcp_f32_e32 v107, v107
	v_pk_fma_f32 v[100:101], v[100:101], v[104:105], v[100:101] neg_lo:[1,0,0] neg_hi:[1,0,0]
	v_mov_b32_e32 v205, v193
	v_pk_mul_f32 v[96:97], v[96:97], v[100:101]
	v_pk_fma_f32 v[100:101], v[102:103], v[106:107], v[102:103] neg_lo:[1,0,0] neg_hi:[1,0,0]
	v_cvt_pk_bf16_f32 v96, v96, v97
	v_pk_mul_f32 v[98:99], v[98:99], v[100:101]
	s_nop 0
	v_cvt_pk_bf16_f32 v97, v98, v99
	v_lshl_add_u64 v[98:99], s[34:35], 0, v[204:205]
	v_lshl_add_u64 v[98:99], v[180:181], 1, v[98:99]
	global_store_dwordx2 v[98:99], v[96:97], off

; #define LAS __attribute__((address_space(3)))
; #define GAS __attribute__((address_space(1)))
;     DI f32x4 conv1(const Acc& acc, int ai, int bj, int n, int m, int fr, const f32x4& above, const f32x4& below, const f32x4& w0, const f32x4& w1, const f32x4& w2, const f32x4& b, bool zp, bool zn) const {
;         const f32x4 cur = acc[ai][bj][m][n];
;         const f32x4 tp = (m > 0 && fr == 15) ? acc[ai][bj][m > 0 ? m - 1 : 0][n] : cur;
;         const f32x4 tn = (m < 3 && fr == 0) ? acc[ai][bj][m < 3 ? m + 1 : 3][n] : cur;
;         f32x4 pv = ror4(tp), nx = rol4(tn);
;         if (m == 0 && fr == 0) pv = above;
;         if (m == 3 && fr == 15) nx = below;
;         if (zp) pv = (f32x4){0.f, 0.f, 0.f, 0.f};
;         if (zn) nx = (f32x4){0.f, 0.f, 0.f, 0.f};
;         return b + w0 * pv + w1 * cur + w2 * nx;
;     }
;     DI void operator()(const Acc& acc, const Unit& u, int wr, int wc, int fr, int fq, LAS unsigned char* scr) const {
;         LAS float* H = (LAS float*)scr;
;         const int colb = wc * 32 + 8 * fq;
;         if (fr == 0 || fr == 15) {
; #pragma unroll
;             for (int ai = 0; ai < 2; ++ai)
; #pragma unroll
;                 for (int bj = 0; bj < 2; ++bj)
; #pragma unroll
;                     for (int n = 0; n < 2; ++n) {
;                         LAS f32x4* dst = (LAS f32x4*)(H + (((2 * ai + wr) * 2 + (fr == 0 ? 0 : 1)) * 256 + bj * HALF + colb + 4 * n));
;                         *dst = (fr == 0) ? acc[ai][bj][0][n] : acc[ai][bj][3][n];
;                     }
;         }
;         asm volatile("s_waitcnt lgkmcnt(0)" ::: "memory"); __builtin_amdgcn_s_barrier(); asm volatile("" ::: "memory");
;         const int f0 = u.pn * 128 + colb;
;         const int row_base = 254 * u.pm - 1;
; #pragma unroll
;         for (int ai = 0; ai < 2; ++ai) {
;             const int k = 2 * ai + wr, ka = k > 0 ? k - 1 : 0, kb = k < 3 ? k + 1 : 3;
; #pragma unroll
;             for (int n = 0; n < 2; ++n) {
;                 const float* wp = cw + f0 + 4 * n;
;                 const f32x4 g0 = *(const f32x4*)wp, g1 = *(const GAS f32x4*)(wp + DFF2), g2 = *(const GAS f32x4*)(wp + 2 * DFF2), gb = *(const GAS f32x4*)(cb + f0 + 4 * n);
;                 const f32x4 v0 = *(const GAS f32x4*)(wp + DFF), v1 = *(const GAS f32x4*)(wp + DFF + DFF2), v2 = *(const GAS f32x4*)(wp + DFF + 2 * DFF2), vb = *(const GAS f32x4*)(cb + DFF + f0 + 4 * n);
.LBB0_828:
	s_or_b64 exec, exec, s[60:61]
	v_cndmask_b32_e64 v93, v85, v93, s[8:9]
	v_mov_b32_e32 v142, v193
	v_cndmask_b32_e64 v94, v86, v94, s[8:9]
	v_cndmask_b32_e64 v92, v84, v92, s[8:9]
	v_cndmask_b32_e64 v136, v86, v78, s[6:7]
	v_mov_b32_e32 v140, v193
	v_mov_b32_dpp v142, v93 row_ror:1 row_mask:0xf bank_mask:0xf
	v_mov_b32_e32 v141, v193
	v_mov_b32_e32 v93, v193
	v_cndmask_b32_e64 v95, v87, v95, s[8:9]
	v_cndmask_b32_e64 v137, v87, v79, s[6:7]
	v_cndmask_b32_e64 v138, v85, v77, s[6:7]
	v_cndmask_b32_e64 v139, v84, v76, s[6:7]
	v_mov_b32_dpp v140, v92 row_ror:1 row_mask:0xf bank_mask:0xf
	v_mov_b32_dpp v141, v94 row_ror:1 row_mask:0xf bank_mask:0xf
	v_mov_b32_e32 v143, v193
	v_mov_b32_e32 v92, v193
	v_mov_b32_e32 v94, v193
	v_mov_b32_dpp v93, v136 row_ror:15 row_mask:0xf bank_mask:0xf
	v_mov_b32_e32 v136, v193
	v_mov_b32_dpp v143, v95 row_ror:1 row_mask:0xf bank_mask:0xf
	v_mov_b32_dpp v92, v139 row_ror:15 row_mask:0xf bank_mask:0xf
	v_mov_b32_dpp v94, v138 row_ror:15 row_mask:0xf bank_mask:0xf
	v_mov_b32_dpp v136, v137 row_ror:15 row_mask:0xf bank_mask:0xf
	v_cndmask_b32_e64 v91, v83, v91, s[8:9]
	v_cndmask_b32_e64 v90, v82, v90, s[8:9]
	v_cndmask_b32_e64 v89, v81, v89, s[8:9]
	v_cndmask_b32_e64 v88, v80, v88, s[8:9]
	v_mov_b32_e32 v95, v193
	v_mov_b32_e32 v138, v193
	v_mov_b32_e32 v137, v193
	v_mov_b32_e32 v139, v193
	v_cndmask_b32_e64 v144, v83, v75, s[6:7]
	v_cndmask_b32_e64 v145, v82, v74, s[6:7]
	v_cndmask_b32_e64 v146, v81, v73, s[6:7]
	v_cndmask_b32_e64 v147, v80, v72, s[6:7]
	v_mov_b32_dpp v95, v88 row_ror:1 row_mask:0xf bank_mask:0xf
	v_mov_b32_dpp v138, v89 row_ror:1 row_mask:0xf bank_mask:0xf
	v_mov_b32_dpp v137, v90 row_ror:1 row_mask:0xf bank_mask:0xf
	v_mov_b32_dpp v139, v91 row_ror:1 row_mask:0xf bank_mask:0xf
	v_mov_b32_e32 v88, v193
	v_mov_b32_e32 v90, v193
	v_mov_b32_e32 v89, v193
	v_mov_b32_e32 v91, v193
	v_mov_b32_dpp v88, v147 row_ror:15 row_mask:0xf bank_mask:0xf
	v_mov_b32_dpp v90, v146 row_ror:15 row_mask:0xf bank_mask:0xf
	v_mov_b32_dpp v89, v145 row_ror:15 row_mask:0xf bank_mask:0xf
	v_mov_b32_dpp v91, v144 row_ror:15 row_mask:0xf bank_mask:0xf
	s_and_saveexec_b64 s[52:53], s[54:55]
	s_cbranch_execz .LBB0_830
	v_cmp_eq_u32_e32 vcc, 0, v225
	v_cmp_eq_u32_e64 s[28:29], 0, v201
	v_mov_b32_e32 v191, v193
	v_cndmask_b32_e64 v145, v142, 0, vcc
	v_cndmask_b32_e64 v144, v140, 0, vcc
	v_cndmask_b32_e64 v143, v143, 0, vcc
	v_cndmask_b32_e64 v142, v141, 0, vcc
	s_waitcnt vmcnt(4)
	v_pk_fma_f32 v[140:141], v[110:111], v[142:143], v[126:127]
	v_pk_fma_f32 v[142:143], v[108:109], v[144:145], v[124:125]
	v_pk_fma_f32 v[140:141], v[86:87], v[118:119], v[140:141]
	v_pk_fma_f32 v[142:143], v[84:85], v[116:117], v[142:143]
	v_cndmask_b32_e64 v145, v94, 0, s[28:29]
	v_cndmask_b32_e64 v144, v92, 0, s[28:29]
	v_cndmask_b32_e64 v147, v136, 0, s[28:29]
	v_cndmask_b32_e64 v146, v93, 0, s[28:29]
	v_pk_fma_f32 v[92:93], v[102:103], v[146:147], v[140:141]
	v_pk_fma_f32 v[140:141], v[100:101], v[144:145], v[142:143]
	v_cndmask_b32_e64 v142, v95, 0, vcc
	v_cndmask_b32_e64 v95, v139, 0, vcc
	v_cndmask_b32_e64 v94, v137, 0, vcc
	v_pk_fma_f32 v[94:95], v[114:115], v[94:95], v[130:131]
	v_cndmask_b32_e64 v139, v90, 0, s[28:29]
	v_pk_fma_f32 v[94:95], v[82:83], v[106:107], v[94:95]
	v_cndmask_b32_e64 v91, v91, 0, s[28:29]
	v_cndmask_b32_e64 v90, v89, 0, s[28:29]
	v_cndmask_b32_e64 v143, v138, 0, vcc
	v_cndmask_b32_e64 v138, v88, 0, s[28:29]
	v_pk_fma_f32 v[88:89], v[98:99], v[90:91], v[94:95]
	v_mul_f32_e32 v90, 0x3d372713, v140
	v_mul_f32_e32 v90, v140, v90
	v_fma_f32 v90, v140, v90, v140
	v_mul_f32_e32 v90, 0x3f4c422a, v90
	v_mul_f32_e32 v90, 0x4038aa3b, v90
	v_exp_f32_e32 v94, v90
	v_mul_f32_e32 v90, 0x3d372713, v141
	v_mul_f32_e32 v90, v141, v90
	v_fma_f32 v90, v141, v90, v141
	v_pk_fma_f32 v[136:137], v[112:113], v[142:143], v[128:129]
	v_mul_f32_e32 v90, 0x3f4c422a, v90
	v_pk_fma_f32 v[136:137], v[80:81], v[104:105], v[136:137]
	v_mul_f32_e32 v90, 0x4038aa3b, v90
	v_exp_f32_e32 v95, v90
	v_pk_fma_f32 v[90:91], v[96:97], v[138:139], v[136:137]
	v_mul_f32_e32 v136, 0x3d372713, v92
	v_mul_f32_e32 v137, 0x3d372713, v93
	v_mul_f32_e32 v136, v92, v136
	v_mul_f32_e32 v137, v93, v137
	v_fma_f32 v136, v92, v136, v92
	v_fma_f32 v137, v93, v137, v93
	v_mul_f32_e32 v136, 0x3f4c422a, v136
	v_mul_f32_e32 v137, 0x3f4c422a, v137
	v_mul_f32_e32 v136, 0x4038aa3b, v136
	v_mul_f32_e32 v137, 0x4038aa3b, v137
	v_exp_f32_e32 v136, v136
	v_exp_f32_e32 v137, v137
	v_add_f32_e32 v94, 1.0, v94
	v_add_f32_e32 v95, 1.0, v95
	v_add_f32_e32 v136, 1.0, v136
	v_add_f32_e32 v137, 1.0, v137
	v_rcp_f32_e32 v94, v94
	v_rcp_f32_e32 v95, v95
	v_rcp_f32_e32 v136, v136
	v_rcp_f32_e32 v137, v137
	v_pk_fma_f32 v[94:95], v[140:141], v[94:95], v[140:141] neg_lo:[1,0,0] neg_hi:[1,0,0]
	s_nop 0
	v_pk_mul_f32 v[90:91], v[90:91], v[94:95]
	v_pk_fma_f32 v[92:93], v[92:93], v[136:137], v[92:93] neg_lo:[1,0,0] neg_hi:[1,0,0]
	v_cvt_pk_bf16_f32 v90, v90, v91
	v_pk_mul_f32 v[88:89], v[88:89], v[92:93]
	s_nop 0
	v_cvt_pk_bf16_f32 v91, v88, v89
	v_lshl_add_u64 v[88:89], s[34:35], 0, v[190:191]
	v_lshl_add_u64 v[88:89], v[180:181], 1, v[88:89]
	global_store_dwordx2 v[88:89], v[90:91], off offset:8
; #define LAS __attribute__((address_space(3)))
; #define GAS __attribute__((address_space(1)))
;     DI f32x4 conv1(const Acc& acc, int ai, int bj, int n, int m, int fr, const f32x4& above, const f32x4& below, const f32x4& w0, const f32x4& w1, const f32x4& w2, const f32x4& b, bool zp, bool zn) const {
;         const f32x4 cur = acc[ai][bj][m][n];
;         const f32x4 tp = (m > 0 && fr == 15) ? acc[ai][bj][m > 0 ? m - 1 : 0][n] : cur;
;         const f32x4 tn = (m < 3 && fr == 0) ? acc[ai][bj][m < 3 ? m + 1 : 3][n] : cur;
;         f32x4 pv = ror4(tp), nx = rol4(tn);
;         if (m == 0 && fr == 0) pv = above;
;         if (m == 3 && fr == 15) nx = below;
;         if (zp) pv = (f32x4){0.f, 0.f, 0.f, 0.f};
;         if (zn) nx = (f32x4){0.f, 0.f, 0.f, 0.f};
;         return b + w0 * pv + w1 * cur + w2 * nx;
;     }
;     DI void operator()(const Acc& acc, const Unit& u, int wr, int wc, int fr, int fq, LAS unsigned char* scr) const {
;         LAS float* H = (LAS float*)scr;
;         const int colb = wc * 32 + 8 * fq;
;         if (fr == 0 || fr == 15) {
; #pragma unroll
;             for (int ai = 0; ai < 2; ++ai)
; #pragma unroll
;                 for (int bj = 0; bj < 2; ++bj)
; #pragma unroll
;                     for (int n = 0; n < 2; ++n) {
;                         LAS f32x4* dst = (LAS f32x4*)(H + (((2 * ai + wr) * 2 + (fr == 0 ? 0 : 1)) * 256 + bj * HALF + colb + 4 * n));
;                         *dst = (fr == 0) ? acc[ai][bj][0][n] : acc[ai][bj][3][n];
;                     }
;         }
;         asm volatile("s_waitcnt lgkmcnt(0)" ::: "memory"); __builtin_amdgcn_s_barrier(); asm volatile("" ::: "memory");
;         const int f0 = u.pn * 128 + colb;
;         const int row_base = 254 * u.pm - 1;
; #pragma unroll
;         for (int ai = 0; ai < 2; ++ai) {
;             const int k = 2 * ai + wr, ka = k > 0 ? k - 1 : 0, kb = k < 3 ? k + 1 : 3;
; #pragma unroll
;             for (int n = 0; n < 2; ++n) {
;                 const float* wp = cw + f0 + 4 * n;
;                 const f32x4 g0 = *(const f32x4*)wp, g1 = *(const GAS f32x4*)(wp + DFF2), g2 = *(const GAS f32x4*)(wp + 2 * DFF2), gb = *(const GAS f32x4*)(cb + f0 + 4 * n);
;                 const f32x4 v0 = *(const GAS f32x4*)(wp + DFF), v1 = *(const GAS f32x4*)(wp + DFF + DFF2), v2 = *(const GAS f32x4*)(wp + DFF + 2 * DFF2), vb = *(const GAS f32x4*)(cb + DFF + f0 + 4 * n);
.LBB0_830:
	s_or_b64 exec, exec, s[52:53]
	v_cndmask_b32_e64 v85, v77, v85, s[8:9]
	v_mov_b32_e32 v94, v193
	v_cndmask_b32_e64 v86, v78, v86, s[8:9]
	v_cndmask_b32_e64 v84, v76, v84, s[8:9]
	v_cndmask_b32_e64 v88, v78, v70, s[6:7]
	v_mov_b32_e32 v92, v193
	v_mov_b32_dpp v94, v85 row_ror:1 row_mask:0xf bank_mask:0xf
	v_mov_b32_e32 v93, v193
	v_mov_b32_e32 v85, v193
	v_cndmask_b32_e64 v87, v79, v87, s[8:9]
	v_cndmask_b32_e64 v89, v79, v71, s[6:7]
	v_cndmask_b32_e64 v90, v77, v69, s[6:7]
	v_cndmask_b32_e64 v91, v76, v68, s[6:7]
	v_mov_b32_dpp v92, v84 row_ror:1 row_mask:0xf bank_mask:0xf
	v_mov_b32_dpp v93, v86 row_ror:1 row_mask:0xf bank_mask:0xf
	v_mov_b32_e32 v95, v193
	v_mov_b32_e32 v84, v193
	v_mov_b32_e32 v86, v193
	v_mov_b32_dpp v85, v88 row_ror:15 row_mask:0xf bank_mask:0xf
	v_mov_b32_e32 v88, v193
	v_mov_b32_dpp v95, v87 row_ror:1 row_mask:0xf bank_mask:0xf
	v_mov_b32_dpp v84, v91 row_ror:15 row_mask:0xf bank_mask:0xf
	v_mov_b32_dpp v86, v90 row_ror:15 row_mask:0xf bank_mask:0xf
	v_mov_b32_dpp v88, v89 row_ror:15 row_mask:0xf bank_mask:0xf
	v_cndmask_b32_e64 v83, v75, v83, s[8:9]
	v_cndmask_b32_e64 v82, v74, v82, s[8:9]
	v_cndmask_b32_e64 v81, v73, v81, s[8:9]
	v_cndmask_b32_e64 v80, v72, v80, s[8:9]
	v_mov_b32_e32 v87, v193
	v_mov_b32_e32 v90, v193
	v_mov_b32_e32 v89, v193
	v_mov_b32_e32 v91, v193
	v_cndmask_b32_e64 v136, v75, v67, s[6:7]
	v_cndmask_b32_e64 v137, v74, v66, s[6:7]
	v_cndmask_b32_e64 v138, v73, v65, s[6:7]
	v_cndmask_b32_e64 v139, v72, v64, s[6:7]
	v_mov_b32_dpp v87, v80 row_ror:1 row_mask:0xf bank_mask:0xf
	v_mov_b32_dpp v90, v81 row_ror:1 row_mask:0xf bank_mask:0xf
	v_mov_b32_dpp v89, v82 row_ror:1 row_mask:0xf bank_mask:0xf
	v_mov_b32_dpp v91, v83 row_ror:1 row_mask:0xf bank_mask:0xf
	v_mov_b32_e32 v80, v193
	v_mov_b32_e32 v82, v193
	v_mov_b32_e32 v81, v193
	v_mov_b32_e32 v83, v193
	v_mov_b32_dpp v80, v139 row_ror:15 row_mask:0xf bank_mask:0xf
	v_mov_b32_dpp v82, v138 row_ror:15 row_mask:0xf bank_mask:0xf
	v_mov_b32_dpp v81, v137 row_ror:15 row_mask:0xf bank_mask:0xf
	v_mov_b32_dpp v83, v136 row_ror:15 row_mask:0xf bank_mask:0xf
	s_and_saveexec_b64 s[52:53], s[56:57]
	s_cbranch_execz .LBB0_832
	v_cmp_eq_u32_e32 vcc, 0, v226
	v_cmp_eq_u32_e64 s[28:29], 0, v223
	v_mov_b32_e32 v203, v193
	v_cndmask_b32_e64 v137, v94, 0, vcc
	v_cndmask_b32_e64 v136, v92, 0, vcc
	v_cndmask_b32_e64 v95, v95, 0, vcc
	v_cndmask_b32_e64 v94, v93, 0, vcc
	s_waitcnt vmcnt(4)
	v_pk_fma_f32 v[92:93], v[110:111], v[94:95], v[126:127]
	v_pk_fma_f32 v[94:95], v[108:109], v[136:137], v[124:125]
	v_pk_fma_f32 v[92:93], v[78:79], v[118:119], v[92:93]
	v_pk_fma_f32 v[94:95], v[76:77], v[116:117], v[94:95]
	v_cndmask_b32_e64 v137, v86, 0, s[28:29]
	v_cndmask_b32_e64 v136, v84, 0, s[28:29]
	v_cndmask_b32_e64 v139, v88, 0, s[28:29]
	v_cndmask_b32_e64 v138, v85, 0, s[28:29]
	v_pk_fma_f32 v[84:85], v[102:103], v[138:139], v[92:93]
	v_pk_fma_f32 v[92:93], v[100:101], v[136:137], v[94:95]
	v_cndmask_b32_e64 v94, v87, 0, vcc
	v_cndmask_b32_e64 v87, v91, 0, vcc
	v_cndmask_b32_e64 v86, v89, 0, vcc
	v_pk_fma_f32 v[86:87], v[114:115], v[86:87], v[130:131]
	v_cndmask_b32_e64 v91, v82, 0, s[28:29]
	v_pk_fma_f32 v[86:87], v[74:75], v[106:107], v[86:87]
	v_cndmask_b32_e64 v83, v83, 0, s[28:29]
	v_cndmask_b32_e64 v82, v81, 0, s[28:29]
	v_cndmask_b32_e64 v95, v90, 0, vcc
	v_cndmask_b32_e64 v90, v80, 0, s[28:29]
	v_pk_fma_f32 v[80:81], v[98:99], v[82:83], v[86:87]
	v_mul_f32_e32 v82, 0x3d372713, v92
	v_mul_f32_e32 v82, v92, v82
	v_fma_f32 v82, v92, v82, v92
	v_mul_f32_e32 v82, 0x3f4c422a, v82
	v_mul_f32_e32 v82, 0x4038aa3b, v82
	v_exp_f32_e32 v86, v82
	v_mul_f32_e32 v82, 0x3d372713, v93
	v_mul_f32_e32 v82, v93, v82
	v_fma_f32 v82, v93, v82, v93
	v_pk_fma_f32 v[88:89], v[112:113], v[94:95], v[128:129]
	v_mul_f32_e32 v82, 0x3f4c422a, v82
	v_pk_fma_f32 v[88:89], v[72:73], v[104:105], v[88:89]
	v_mul_f32_e32 v82, 0x4038aa3b, v82
	v_exp_f32_e32 v87, v82
	v_pk_fma_f32 v[82:83], v[96:97], v[90:91], v[88:89]
	v_mul_f32_e32 v88, 0x3d372713, v84
	v_mul_f32_e32 v89, 0x3d372713, v85
	v_mul_f32_e32 v88, v84, v88
	v_mul_f32_e32 v89, v85, v89
	v_fma_f32 v88, v84, v88, v84
	v_fma_f32 v89, v85, v89, v85
	v_mul_f32_e32 v88, 0x3f4c422a, v88
	v_mul_f32_e32 v89, 0x3f4c422a, v89
	v_mul_f32_e32 v88, 0x4038aa3b, v88
	v_mul_f32_e32 v89, 0x4038aa3b, v89
	v_exp_f32_e32 v88, v88
	v_exp_f32_e32 v89, v89
	v_add_f32_e32 v86, 1.0, v86
	v_add_f32_e32 v87, 1.0, v87
	v_add_f32_e32 v88, 1.0, v88
	v_add_f32_e32 v89, 1.0, v89
	v_rcp_f32_e32 v86, v86
	v_rcp_f32_e32 v87, v87
	v_rcp_f32_e32 v88, v88
	v_rcp_f32_e32 v89, v89
	v_pk_fma_f32 v[86:87], v[92:93], v[86:87], v[92:93] neg_lo:[1,0,0] neg_hi:[1,0,0]
	s_nop 0
	v_pk_mul_f32 v[82:83], v[82:83], v[86:87]
	v_pk_fma_f32 v[84:85], v[84:85], v[88:89], v[84:85] neg_lo:[1,0,0] neg_hi:[1,0,0]
	v_cvt_pk_bf16_f32 v82, v82, v83
	v_pk_mul_f32 v[80:81], v[80:81], v[84:85]
	s_nop 0
	v_cvt_pk_bf16_f32 v83, v80, v81
	v_lshl_add_u64 v[80:81], s[34:35], 0, v[202:203]
	v_lshl_add_u64 v[80:81], v[180:181], 1, v[80:81]
	global_store_dwordx2 v[80:81], v[82:83], off offset:8
; #define LAS __attribute__((address_space(3)))
; #define GAS __attribute__((address_space(1)))
;     DI f32x4 conv1(const Acc& acc, int ai, int bj, int n, int m, int fr, const f32x4& above, const f32x4& below, const f32x4& w0, const f32x4& w1, const f32x4& w2, const f32x4& b, bool zp, bool zn) const {
;         const f32x4 cur = acc[ai][bj][m][n];
;         const f32x4 tp = (m > 0 && fr == 15) ? acc[ai][bj][m > 0 ? m - 1 : 0][n] : cur;
;         const f32x4 tn = (m < 3 && fr == 0) ? acc[ai][bj][m < 3 ? m + 1 : 3][n] : cur;
;         f32x4 pv = ror4(tp), nx = rol4(tn);
;         if (m == 0 && fr == 0) pv = above;
;         if (m == 3 && fr == 15) nx = below;
;         if (zp) pv = (f32x4){0.f, 0.f, 0.f, 0.f};
;         if (zn) nx = (f32x4){0.f, 0.f, 0.f, 0.f};
;         return b + w0 * pv + w1 * cur + w2 * nx;
;     }
;     DI void operator()(const Acc& acc, const Unit& u, int wr, int wc, int fr, int fq, LAS unsigned char* scr) const {
;         LAS float* H = (LAS float*)scr;
;         const int colb = wc * 32 + 8 * fq;
;         if (fr == 0 || fr == 15) {
; #pragma unroll
;             for (int ai = 0; ai < 2; ++ai)
; #pragma unroll
;                 for (int bj = 0; bj < 2; ++bj)
; #pragma unroll
;                     for (int n = 0; n < 2; ++n) {
;                         LAS f32x4* dst = (LAS f32x4*)(H + (((2 * ai + wr) * 2 + (fr == 0 ? 0 : 1)) * 256 + bj * HALF + colb + 4 * n));
;                         *dst = (fr == 0) ? acc[ai][bj][0][n] : acc[ai][bj][3][n];
;                     }
;         }
;         asm volatile("s_waitcnt lgkmcnt(0)" ::: "memory"); __builtin_amdgcn_s_barrier(); asm volatile("" ::: "memory");
;         const int f0 = u.pn * 128 + colb;
;         const int row_base = 254 * u.pm - 1;
; #pragma unroll
;         for (int ai = 0; ai < 2; ++ai) {
;             const int k = 2 * ai + wr, ka = k > 0 ? k - 1 : 0, kb = k < 3 ? k + 1 : 3;
; #pragma unroll
;             for (int n = 0; n < 2; ++n) {
;                 const float* wp = cw + f0 + 4 * n;
;                 const f32x4 g0 = *(const f32x4*)wp, g1 = *(const GAS f32x4*)(wp + DFF2), g2 = *(const GAS f32x4*)(wp + 2 * DFF2), gb = *(const GAS f32x4*)(cb + f0 + 4 * n);
;                 const f32x4 v0 = *(const GAS f32x4*)(wp + DFF), v1 = *(const GAS f32x4*)(wp + DFF + DFF2), v2 = *(const GAS f32x4*)(wp + DFF + 2 * DFF2), vb = *(const GAS f32x4*)(cb + DFF + f0 + 4 * n);
.LBB0_832:
	s_or_b64 exec, exec, s[52:53]
	v_cndmask_b32_e64 v78, v70, v78, s[8:9]
	v_cndmask_b32_e64 v77, v69, v77, s[8:9]
	v_cndmask_b32_e64 v76, v68, v76, s[8:9]
	v_mov_b32_e32 v84, v193
	v_mov_b32_e32 v86, v193
	v_mov_b32_e32 v85, v193
	v_cndmask_b32_e64 v79, v71, v79, s[8:9]
	v_mov_b32_dpp v84, v76 row_ror:1 row_mask:0xf bank_mask:0xf
	v_mov_b32_dpp v86, v77 row_ror:1 row_mask:0xf bank_mask:0xf
	v_mov_b32_dpp v85, v78 row_ror:1 row_mask:0xf bank_mask:0xf
	v_mov_b32_e32 v87, v193
	v_cndmask_b32_e64 v75, v67, v75, s[8:9]
	v_cndmask_b32_e64 v74, v66, v74, s[8:9]
	v_cndmask_b32_e64 v73, v65, v73, s[8:9]
	v_cndmask_b32_e64 v72, v64, v72, s[8:9]
	v_mov_b32_e32 v76, v193
	v_mov_b32_e32 v78, v193
	v_mov_b32_e32 v77, v193
	v_mov_b32_e32 v81, v193
	v_mov_b32_dpp v87, v79 row_ror:1 row_mask:0xf bank_mask:0xf
	v_mov_b32_e32 v79, v193
	v_mov_b32_e32 v80, v193
	v_mov_b32_e32 v82, v193
	v_mov_b32_e32 v83, v193
	v_mov_b32_dpp v76, v72 row_ror:1 row_mask:0xf bank_mask:0xf
	v_mov_b32_dpp v78, v73 row_ror:1 row_mask:0xf bank_mask:0xf
	v_mov_b32_dpp v77, v74 row_ror:1 row_mask:0xf bank_mask:0xf
	v_mov_b32_dpp v81, v75 row_ror:1 row_mask:0xf bank_mask:0xf
	v_mov_b32_e32 v72, v193
	v_mov_b32_e32 v73, v193
	v_mov_b32_e32 v74, v193
	v_mov_b32_e32 v75, v193
	v_mov_b32_dpp v79, v68 row_ror:15 row_mask:0xf bank_mask:0xf
	v_mov_b32_dpp v80, v69 row_ror:15 row_mask:0xf bank_mask:0xf
	v_mov_b32_dpp v82, v70 row_ror:15 row_mask:0xf bank_mask:0xf
	v_mov_b32_dpp v83, v71 row_ror:15 row_mask:0xf bank_mask:0xf
	v_mov_b32_dpp v72, v64 row_ror:15 row_mask:0xf bank_mask:0xf
	v_mov_b32_dpp v73, v65 row_ror:15 row_mask:0xf bank_mask:0xf
	v_mov_b32_dpp v74, v66 row_ror:15 row_mask:0xf bank_mask:0xf
	v_mov_b32_dpp v75, v67 row_ror:15 row_mask:0xf bank_mask:0xf
	s_and_saveexec_b64 s[52:53], s[58:59]
	s_cbranch_execz .LBB0_834
	v_cmp_eq_u32_e32 vcc, 0, v227
	s_waitcnt lgkmcnt(1)
	v_cndmask_b32_e64 v80, v80, v133, s[8:9]
	v_cmp_eq_u32_e64 s[28:29], 0, v224
	v_cndmask_b32_e64 v89, v86, 0, vcc
	v_cndmask_b32_e64 v87, v87, 0, vcc
	v_cndmask_b32_e64 v86, v85, 0, vcc
	v_cndmask_b32_e64 v88, v84, 0, vcc
	s_waitcnt vmcnt(4)
	v_pk_fma_f32 v[84:85], v[110:111], v[86:87], v[126:127]
	v_pk_fma_f32 v[86:87], v[108:109], v[88:89], v[124:125]
	v_pk_fma_f32 v[70:71], v[70:71], v[118:119], v[84:85]
	v_cndmask_b32_e64 v85, v83, v135, s[8:9]
	v_cndmask_b32_e64 v79, v79, v132, s[8:9]
	v_cndmask_b32_e64 v83, v80, 0, s[28:29]
	v_cndmask_b32_e64 v81, v81, 0, vcc
	v_cndmask_b32_e64 v80, v77, 0, vcc
	v_pk_fma_f32 v[68:69], v[68:69], v[116:117], v[86:87]
	v_cndmask_b32_e64 v84, v82, v134, s[8:9]
	v_cndmask_b32_e64 v82, v79, 0, s[28:29]
	v_cndmask_b32_e64 v79, v78, 0, vcc
	v_cndmask_b32_e64 v78, v76, 0, vcc
	v_pk_fma_f32 v[76:77], v[114:115], v[80:81], v[130:131]
	s_waitcnt lgkmcnt(0)
	v_cndmask_b32_e64 v74, v74, v122, s[8:9]
	v_cndmask_b32_e64 v75, v75, v123, s[8:9]
	v_pk_fma_f32 v[68:69], v[100:101], v[82:83], v[68:69]
	v_pk_fma_f32 v[66:67], v[66:67], v[106:107], v[76:77]
	v_cndmask_b32_e64 v75, v75, 0, s[28:29]
	v_cndmask_b32_e64 v74, v74, 0, s[28:29]
	v_pk_fma_f32 v[66:67], v[98:99], v[74:75], v[66:67]
	v_mul_f32_e32 v74, 0x3d372713, v68
	v_mul_f32_e32 v75, 0x3d372713, v69
	v_mul_f32_e32 v74, v68, v74
	v_mul_f32_e32 v75, v69, v75
	v_fma_f32 v74, v68, v74, v68
	v_fma_f32 v75, v69, v75, v69
	v_mul_f32_e32 v74, 0x3f4c422a, v74
	v_mul_f32_e32 v75, 0x3f4c422a, v75
	v_mul_f32_e32 v74, 0x4038aa3b, v74
	v_mul_f32_e32 v75, 0x4038aa3b, v75
	v_exp_f32_e32 v74, v74
	v_exp_f32_e32 v75, v75
	v_cndmask_b32_e64 v85, v85, 0, s[28:29]
	v_cndmask_b32_e64 v84, v84, 0, s[28:29]
	v_pk_fma_f32 v[78:79], v[112:113], v[78:79], v[128:129]
	v_cndmask_b32_e64 v72, v72, v120, s[8:9]
	v_cndmask_b32_e64 v73, v73, v121, s[8:9]
	v_pk_fma_f32 v[70:71], v[102:103], v[84:85], v[70:71]
	v_pk_fma_f32 v[64:65], v[64:65], v[104:105], v[78:79]
	v_cndmask_b32_e64 v73, v73, 0, s[28:29]
	v_cndmask_b32_e64 v72, v72, 0, s[28:29]
	v_pk_fma_f32 v[64:65], v[96:97], v[72:73], v[64:65]
	v_add_f32_e32 v72, 1.0, v74
	v_add_f32_e32 v73, 1.0, v75
	v_mul_f32_e32 v74, 0x3d372713, v70
	v_mul_f32_e32 v75, 0x3d372713, v71
	v_mul_f32_e32 v74, v70, v74
	v_mul_f32_e32 v75, v71, v75
	v_fma_f32 v74, v70, v74, v70
	v_fma_f32 v75, v71, v75, v71
	v_mul_f32_e32 v74, 0x3f4c422a, v74
	v_mul_f32_e32 v75, 0x3f4c422a, v75
	v_mul_f32_e32 v74, 0x4038aa3b, v74
	v_mul_f32_e32 v75, 0x4038aa3b, v75
	v_exp_f32_e32 v74, v74
	v_exp_f32_e32 v75, v75
	v_rcp_f32_e32 v72, v72
	v_rcp_f32_e32 v73, v73
	v_add_f32_e32 v74, 1.0, v74
	v_add_f32_e32 v75, 1.0, v75
	v_rcp_f32_e32 v74, v74
	v_rcp_f32_e32 v75, v75
	v_pk_fma_f32 v[68:69], v[68:69], v[72:73], v[68:69] neg_lo:[1,0,0] neg_hi:[1,0,0]
	v_mov_b32_e32 v205, v193
	v_pk_mul_f32 v[64:65], v[64:65], v[68:69]
	v_pk_fma_f32 v[68:69], v[70:71], v[74:75], v[70:71] neg_lo:[1,0,0] neg_hi:[1,0,0]
	v_cvt_pk_bf16_f32 v64, v64, v65
	v_pk_mul_f32 v[66:67], v[66:67], v[68:69]
	s_nop 0
	v_cvt_pk_bf16_f32 v65, v66, v67
	v_lshl_add_u64 v[66:67], s[34:35], 0, v[204:205]
	v_lshl_add_u64 v[66:67], v[180:181], 1, v[66:67]
	global_store_dwordx2 v[66:67], v[64:65], off offset:8

; #define LAS __attribute__((address_space(3)))
; #define GAS __attribute__((address_space(1)))
;     DI f32x4 conv1(const Acc& acc, int ai, int bj, int n, int m, int fr, const f32x4& above, const f32x4& below, const f32x4& w0, const f32x4& w1, const f32x4& w2, const f32x4& b, bool zp, bool zn) const {
;         const f32x4 cur = acc[ai][bj][m][n];
;         const f32x4 tp = (m > 0 && fr == 15) ? acc[ai][bj][m > 0 ? m - 1 : 0][n] : cur;
;         const f32x4 tn = (m < 3 && fr == 0) ? acc[ai][bj][m < 3 ? m + 1 : 3][n] : cur;
;         f32x4 pv = ror4(tp), nx = rol4(tn);
;         if (m == 0 && fr == 0) pv = above;
;         if (m == 3 && fr == 15) nx = below;
;         if (zp) pv = (f32x4){0.f, 0.f, 0.f, 0.f};
;         if (zn) nx = (f32x4){0.f, 0.f, 0.f, 0.f};
;         return b + w0 * pv + w1 * cur + w2 * nx;
;     }
;     DI void operator()(const Acc& acc, const Unit& u, int wr, int wc, int fr, int fq, LAS unsigned char* scr) const {
;         LAS float* H = (LAS float*)scr;
;         const int colb = wc * 32 + 8 * fq;
;         if (fr == 0 || fr == 15) {
; #pragma unroll
;             for (int ai = 0; ai < 2; ++ai)
; #pragma unroll
;                 for (int bj = 0; bj < 2; ++bj)
; #pragma unroll
;                     for (int n = 0; n < 2; ++n) {
;                         LAS f32x4* dst = (LAS f32x4*)(H + (((2 * ai + wr) * 2 + (fr == 0 ? 0 : 1)) * 256 + bj * HALF + colb + 4 * n));
;                         *dst = (fr == 0) ? acc[ai][bj][0][n] : acc[ai][bj][3][n];
;                     }
;         }
;         asm volatile("s_waitcnt lgkmcnt(0)" ::: "memory"); __builtin_amdgcn_s_barrier(); asm volatile("" ::: "memory");
;         const int f0 = u.pn * 128 + colb;
;         const int row_base = 254 * u.pm - 1;
; #pragma unroll
;         for (int ai = 0; ai < 2; ++ai) {
;             const int k = 2 * ai + wr, ka = k > 0 ? k - 1 : 0, kb = k < 3 ? k + 1 : 3;
; #pragma unroll
;             for (int n = 0; n < 2; ++n) {
;                 const float* wp = cw + f0 + 4 * n;
;                 const f32x4 g0 = *(const f32x4*)wp, g1 = *(const GAS f32x4*)(wp + DFF2), g2 = *(const GAS f32x4*)(wp + 2 * DFF2), gb = *(const GAS f32x4*)(cb + f0 + 4 * n);
;                 const f32x4 v0 = *(const GAS f32x4*)(wp + DFF), v1 = *(const GAS f32x4*)(wp + DFF + DFF2), v2 = *(const GAS f32x4*)(wp + DFF + 2 * DFF2), vb = *(const GAS f32x4*)(cb + DFF + f0 + 4 * n);
.LBB0_836:
	s_or_b64 exec, exec, s[54:55]
	v_add_u32_e32 v106, s47, v217
	s_movk_i32 s28, 0x3fff
	v_cmp_lt_i32_e32 vcc, s28, v106
	v_mov_b32_e32 v105, 0xfff
	v_mov_b32_e32 v107, 0x3fff
	v_cndmask_b32_e64 v61, v53, v61, s[8:9]
	v_mov_b32_e32 v115, v193
	v_cndmask_b32_e32 v113, v105, v107, vcc
	v_cndmask_b32_e64 v62, v54, v62, s[8:9]
	v_cndmask_b32_e64 v60, v52, v60, s[8:9]
	v_cndmask_b32_e64 v105, v54, v46, s[6:7]
	v_mov_b32_e32 v110, v193
	v_mov_b32_dpp v115, v61 row_ror:1 row_mask:0xf bank_mask:0xf
	v_mov_b32_e32 v111, v193
	v_mov_b32_e32 v61, v193
	v_cndmask_b32_e64 v63, v55, v63, s[8:9]
	v_cndmask_b32_e64 v107, v55, v47, s[6:7]
	v_cndmask_b32_e64 v108, v53, v45, s[6:7]
	v_cndmask_b32_e64 v109, v52, v44, s[6:7]
	v_mov_b32_dpp v110, v60 row_ror:1 row_mask:0xf bank_mask:0xf
	v_mov_b32_dpp v111, v62 row_ror:1 row_mask:0xf bank_mask:0xf
	v_mov_b32_e32 v116, v193
	v_mov_b32_e32 v60, v193
	v_mov_b32_e32 v62, v193
	v_mov_b32_dpp v61, v105 row_ror:15 row_mask:0xf bank_mask:0xf
	v_mov_b32_e32 v105, v193
	v_mov_b32_dpp v116, v63 row_ror:1 row_mask:0xf bank_mask:0xf
	v_mov_b32_dpp v60, v109 row_ror:15 row_mask:0xf bank_mask:0xf
	v_mov_b32_dpp v62, v108 row_ror:15 row_mask:0xf bank_mask:0xf
	v_mov_b32_dpp v105, v107 row_ror:15 row_mask:0xf bank_mask:0xf
	v_cndmask_b32_e64 v59, v51, v59, s[8:9]
	v_cndmask_b32_e64 v58, v50, v58, s[8:9]
	v_cndmask_b32_e64 v57, v49, v57, s[8:9]
	v_cndmask_b32_e64 v56, v48, v56, s[8:9]
	v_mov_b32_e32 v63, v193
	v_mov_b32_e32 v108, v193
	v_mov_b32_e32 v107, v193
	v_mov_b32_e32 v109, v193
	s_mov_b32 s28, 0xc000
	v_add_u32_e32 v118, s33, v217
	v_cndmask_b32_e64 v117, v51, v43, s[6:7]
	v_cndmask_b32_e64 v119, v50, v42, s[6:7]
	v_cndmask_b32_e64 v120, v49, v41, s[6:7]
	v_cndmask_b32_e64 v121, v48, v40, s[6:7]
	v_mov_b32_dpp v63, v56 row_ror:1 row_mask:0xf bank_mask:0xf
	v_mov_b32_dpp v108, v57 row_ror:1 row_mask:0xf bank_mask:0xf
	v_mov_b32_dpp v107, v58 row_ror:1 row_mask:0xf bank_mask:0xf
	v_mov_b32_dpp v109, v59 row_ror:1 row_mask:0xf bank_mask:0xf
	v_mov_b32_e32 v56, v193
	v_mov_b32_e32 v58, v193
	v_mov_b32_e32 v57, v193
	v_mov_b32_e32 v59, v193
	v_cmp_gt_u32_e32 vcc, s28, v106
	v_mov_b32_dpp v56, v121 row_ror:15 row_mask:0xf bank_mask:0xf
	v_mov_b32_dpp v58, v120 row_ror:15 row_mask:0xf bank_mask:0xf
	v_mov_b32_dpp v57, v119 row_ror:15 row_mask:0xf bank_mask:0xf
	v_mov_b32_dpp v59, v117 row_ror:15 row_mask:0xf bank_mask:0xf
	s_and_b64 s[54:55], s[20:21], vcc
	v_and_b32_e32 v117, v113, v106
	v_and_b32_e32 v113, v113, v118
	v_mul_lo_u32 v106, v106, s89
	s_and_saveexec_b64 s[56:57], s[54:55]
	s_cbranch_execz .LBB0_838
	v_cmp_eq_u32_e32 vcc, 0, v117
	v_cmp_eq_u32_e64 s[28:29], 0, v113
	s_nop 0
	v_cndmask_b32_e64 v119, v115, 0, vcc
	v_cndmask_b32_e64 v118, v110, 0, vcc
	v_cndmask_b32_e64 v121, v116, 0, vcc
	v_cndmask_b32_e64 v120, v111, 0, vcc
	v_pk_fma_f32 v[110:111], v[98:99], v[120:121], v[102:103]
	v_pk_fma_f32 v[118:119], v[96:97], v[118:119], v[100:101]
	v_pk_fma_f32 v[110:111], v[54:55], v[90:91], v[110:111]
	v_pk_fma_f32 v[118:119], v[52:53], v[88:89], v[118:119]
	v_cndmask_b32_e64 v121, v62, 0, s[28:29]
	v_cndmask_b32_e64 v120, v60, 0, s[28:29]
	v_cndmask_b32_e64 v123, v105, 0, s[28:29]
	v_cndmask_b32_e64 v122, v61, 0, s[28:29]
	v_pk_fma_f32 v[60:61], v[86:87], v[122:123], v[110:111]
	v_pk_fma_f32 v[110:111], v[84:85], v[120:121], v[118:119]
	v_cndmask_b32_e64 v118, v63, 0, vcc
	v_cndmask_b32_e64 v63, v109, 0, vcc
	v_cndmask_b32_e64 v62, v107, 0, vcc
	v_cndmask_b32_e64 v119, v108, 0, vcc
	v_pk_fma_f32 v[62:63], v[78:79], v[62:63], v[82:83]
	v_pk_fma_f32 v[108:109], v[76:77], v[118:119], v[80:81]
	v_pk_fma_f32 v[62:63], v[50:51], v[70:71], v[62:63]
	v_cndmask_b32_e64 v119, v58, 0, s[28:29]
	v_cndmask_b32_e64 v59, v59, 0, s[28:29]
	v_cndmask_b32_e64 v58, v57, 0, s[28:29]
	v_cndmask_b32_e64 v118, v56, 0, s[28:29]
	v_pk_fma_f32 v[56:57], v[66:67], v[58:59], v[62:63]
	v_mul_f32_e32 v58, 0x3d372713, v110
	v_mul_f32_e32 v58, v110, v58
	v_fma_f32 v58, v110, v58, v110
	v_mul_f32_e32 v58, 0x3f4c422a, v58
	v_mul_f32_e32 v58, 0x4038aa3b, v58
	v_mul_f32_e32 v105, 0x3d372713, v60
	v_exp_f32_e32 v62, v58
	v_mul_f32_e32 v58, 0x3d372713, v111
	v_mul_f32_e32 v105, v60, v105
	v_mul_f32_e32 v107, 0x3d372713, v61
	v_mul_f32_e32 v58, v111, v58
	v_fma_f32 v105, v60, v105, v60
	v_mul_f32_e32 v107, v61, v107
	v_fma_f32 v58, v111, v58, v111
	v_mul_f32_e32 v105, 0x3f4c422a, v105
	v_fma_f32 v107, v61, v107, v61
	v_mul_f32_e32 v58, 0x3f4c422a, v58
	v_mul_f32_e32 v105, 0x4038aa3b, v105
	v_mul_f32_e32 v107, 0x3f4c422a, v107
	v_mul_f32_e32 v58, 0x4038aa3b, v58
	v_exp_f32_e32 v105, v105
	v_mul_f32_e32 v107, 0x4038aa3b, v107
	v_exp_f32_e32 v63, v58
	v_exp_f32_e32 v107, v107
	v_pk_fma_f32 v[108:109], v[48:49], v[68:69], v[108:109]
	v_add_f32_e32 v105, 1.0, v105
	v_pk_fma_f32 v[58:59], v[64:65], v[118:119], v[108:109]
	v_add_f32_e32 v62, 1.0, v62
	v_add_f32_e32 v63, 1.0, v63
	v_rcp_f32_e32 v108, v105
	v_add_f32_e32 v105, 1.0, v107
	v_rcp_f32_e32 v62, v62
	v_rcp_f32_e32 v63, v63
	v_rcp_f32_e32 v109, v105
	v_mov_b32_e32 v107, v193
	v_pk_fma_f32 v[62:63], v[110:111], v[62:63], v[110:111] neg_lo:[1,0,0] neg_hi:[1,0,0]
	v_pk_fma_f32 v[60:61], v[60:61], v[108:109], v[60:61] neg_lo:[1,0,0] neg_hi:[1,0,0]
	v_pk_mul_f32 v[58:59], v[58:59], v[62:63]
	v_pk_mul_f32 v[56:57], v[56:57], v[60:61]
	v_cvt_pk_bf16_f32 v58, v58, v59
	v_cvt_pk_bf16_f32 v59, v56, v57
	v_lshl_add_u64 v[56:57], s[34:35], 0, v[106:107]
	v_lshl_add_u64 v[56:57], v[180:181], 1, v[56:57]
	global_store_dwordx2 v[56:57], v[58:59], off
; #define LAS __attribute__((address_space(3)))
; #define GAS __attribute__((address_space(1)))
;     DI f32x4 conv1(const Acc& acc, int ai, int bj, int n, int m, int fr, const f32x4& above, const f32x4& below, const f32x4& w0, const f32x4& w1, const f32x4& w2, const f32x4& b, bool zp, bool zn) const {
;         const f32x4 cur = acc[ai][bj][m][n];
;         const f32x4 tp = (m > 0 && fr == 15) ? acc[ai][bj][m > 0 ? m - 1 : 0][n] : cur;
;         const f32x4 tn = (m < 3 && fr == 0) ? acc[ai][bj][m < 3 ? m + 1 : 3][n] : cur;
;         f32x4 pv = ror4(tp), nx = rol4(tn);
;         if (m == 0 && fr == 0) pv = above;
;         if (m == 3 && fr == 15) nx = below;
;         if (zp) pv = (f32x4){0.f, 0.f, 0.f, 0.f};
;         if (zn) nx = (f32x4){0.f, 0.f, 0.f, 0.f};
;         return b + w0 * pv + w1 * cur + w2 * nx;
;     }
;     DI void operator()(const Acc& acc, const Unit& u, int wr, int wc, int fr, int fq, LAS unsigned char* scr) const {
;         LAS float* H = (LAS float*)scr;
;         const int colb = wc * 32 + 8 * fq;
;         if (fr == 0 || fr == 15) {
; #pragma unroll
;             for (int ai = 0; ai < 2; ++ai)
; #pragma unroll
;                 for (int bj = 0; bj < 2; ++bj)
; #pragma unroll
;                     for (int n = 0; n < 2; ++n) {
;                         LAS f32x4* dst = (LAS f32x4*)(H + (((2 * ai + wr) * 2 + (fr == 0 ? 0 : 1)) * 256 + bj * HALF + colb + 4 * n));
;                         *dst = (fr == 0) ? acc[ai][bj][0][n] : acc[ai][bj][3][n];
;                     }
;         }
;         asm volatile("s_waitcnt lgkmcnt(0)" ::: "memory"); __builtin_amdgcn_s_barrier(); asm volatile("" ::: "memory");
;         const int f0 = u.pn * 128 + colb;
;         const int row_base = 254 * u.pm - 1;
; #pragma unroll
;         for (int ai = 0; ai < 2; ++ai) {
;             const int k = 2 * ai + wr, ka = k > 0 ? k - 1 : 0, kb = k < 3 ? k + 1 : 3;
; #pragma unroll
;             for (int n = 0; n < 2; ++n) {
;                 const float* wp = cw + f0 + 4 * n;
;                 const f32x4 g0 = *(const f32x4*)wp, g1 = *(const GAS f32x4*)(wp + DFF2), g2 = *(const GAS f32x4*)(wp + 2 * DFF2), gb = *(const GAS f32x4*)(cb + f0 + 4 * n);
;                 const f32x4 v0 = *(const GAS f32x4*)(wp + DFF), v1 = *(const GAS f32x4*)(wp + DFF + DFF2), v2 = *(const GAS f32x4*)(wp + DFF + 2 * DFF2), vb = *(const GAS f32x4*)(cb + DFF + f0 + 4 * n);
.LBB0_838:
	s_or_b64 exec, exec, s[56:57]
	v_add_u32_e32 v105, s47, v218
	s_movk_i32 s28, 0x3fff
	v_cmp_lt_i32_e32 vcc, s28, v105
	v_mov_b32_e32 v56, 0xfff
	v_mov_b32_e32 v57, 0x3fff
	v_cndmask_b32_e64 v53, v45, v53, s[8:9]
	v_mov_b32_e32 v62, v193
	v_cndmask_b32_e32 v107, v56, v57, vcc
	v_cndmask_b32_e64 v54, v46, v54, s[8:9]
	v_cndmask_b32_e64 v52, v44, v52, s[8:9]
	v_cndmask_b32_e64 v56, v46, v38, s[6:7]
	v_mov_b32_e32 v60, v193
	v_mov_b32_dpp v62, v53 row_ror:1 row_mask:0xf bank_mask:0xf
	v_mov_b32_e32 v61, v193
	v_mov_b32_e32 v53, v193
	v_cndmask_b32_e64 v55, v47, v55, s[8:9]
	v_cndmask_b32_e64 v57, v47, v39, s[6:7]
	v_cndmask_b32_e64 v58, v45, v37, s[6:7]
	v_cndmask_b32_e64 v59, v44, v36, s[6:7]
	v_mov_b32_dpp v60, v52 row_ror:1 row_mask:0xf bank_mask:0xf
	v_mov_b32_dpp v61, v54 row_ror:1 row_mask:0xf bank_mask:0xf
	v_mov_b32_e32 v63, v193
	v_mov_b32_e32 v52, v193
	v_mov_b32_e32 v54, v193
	v_mov_b32_dpp v53, v56 row_ror:15 row_mask:0xf bank_mask:0xf
	v_mov_b32_e32 v56, v193
	v_mov_b32_dpp v63, v55 row_ror:1 row_mask:0xf bank_mask:0xf
	v_mov_b32_dpp v52, v59 row_ror:15 row_mask:0xf bank_mask:0xf
	v_mov_b32_dpp v54, v58 row_ror:15 row_mask:0xf bank_mask:0xf
	v_mov_b32_dpp v56, v57 row_ror:15 row_mask:0xf bank_mask:0xf
	v_cndmask_b32_e64 v51, v43, v51, s[8:9]
	v_cndmask_b32_e64 v50, v42, v50, s[8:9]
	v_cndmask_b32_e64 v49, v41, v49, s[8:9]
	v_cndmask_b32_e64 v48, v40, v48, s[8:9]
	v_mov_b32_e32 v55, v193
	v_mov_b32_e32 v58, v193
	v_mov_b32_e32 v57, v193
	v_mov_b32_e32 v59, v193
	s_mov_b32 s28, 0xc000
	v_add_u32_e32 v108, s33, v218
	v_cndmask_b32_e64 v109, v43, v35, s[6:7]
	v_cndmask_b32_e64 v110, v42, v34, s[6:7]
	v_cndmask_b32_e64 v111, v41, v33, s[6:7]
	v_cndmask_b32_e64 v115, v40, v32, s[6:7]
	v_mov_b32_dpp v55, v48 row_ror:1 row_mask:0xf bank_mask:0xf
	v_mov_b32_dpp v58, v49 row_ror:1 row_mask:0xf bank_mask:0xf
	v_mov_b32_dpp v57, v50 row_ror:1 row_mask:0xf bank_mask:0xf
	v_mov_b32_dpp v59, v51 row_ror:1 row_mask:0xf bank_mask:0xf
	v_mov_b32_e32 v48, v193
	v_mov_b32_e32 v50, v193
	v_mov_b32_e32 v49, v193
	v_mov_b32_e32 v51, v193
	v_cmp_gt_u32_e32 vcc, s28, v105
	v_mov_b32_dpp v48, v115 row_ror:15 row_mask:0xf bank_mask:0xf
	v_mov_b32_dpp v50, v111 row_ror:15 row_mask:0xf bank_mask:0xf
	v_mov_b32_dpp v49, v110 row_ror:15 row_mask:0xf bank_mask:0xf
	v_mov_b32_dpp v51, v109 row_ror:15 row_mask:0xf bank_mask:0xf
	s_and_b64 s[56:57], s[22:23], vcc
	v_and_b32_e32 v118, v107, v105
	v_and_b32_e32 v115, v107, v108
	v_mul_lo_u32 v108, v105, s89
	s_and_saveexec_b64 s[58:59], s[56:57]
	s_cbranch_execz .LBB0_840
	v_cmp_eq_u32_e32 vcc, 0, v118
	v_cmp_eq_u32_e64 s[28:29], 0, v115
	v_mov_b32_e32 v109, v193
	v_cndmask_b32_e64 v111, v62, 0, vcc
	v_cndmask_b32_e64 v110, v60, 0, vcc
	v_cndmask_b32_e64 v63, v63, 0, vcc
	v_cndmask_b32_e64 v62, v61, 0, vcc
	v_pk_fma_f32 v[60:61], v[98:99], v[62:63], v[102:103]
	v_pk_fma_f32 v[62:63], v[96:97], v[110:111], v[100:101]
	v_pk_fma_f32 v[60:61], v[46:47], v[90:91], v[60:61]
	v_pk_fma_f32 v[62:63], v[44:45], v[88:89], v[62:63]
	v_cndmask_b32_e64 v111, v54, 0, s[28:29]
	v_cndmask_b32_e64 v110, v52, 0, s[28:29]
	v_cndmask_b32_e64 v121, v56, 0, s[28:29]
	v_cndmask_b32_e64 v120, v53, 0, s[28:29]
	v_pk_fma_f32 v[52:53], v[86:87], v[120:121], v[60:61]
	v_pk_fma_f32 v[60:61], v[84:85], v[110:111], v[62:63]
	v_cndmask_b32_e64 v62, v55, 0, vcc
	v_cndmask_b32_e64 v55, v59, 0, vcc
	v_cndmask_b32_e64 v54, v57, 0, vcc
	v_pk_fma_f32 v[54:55], v[78:79], v[54:55], v[82:83]
	v_cndmask_b32_e64 v59, v50, 0, s[28:29]
	v_pk_fma_f32 v[54:55], v[42:43], v[70:71], v[54:55]
	v_cndmask_b32_e64 v51, v51, 0, s[28:29]
	v_cndmask_b32_e64 v50, v49, 0, s[28:29]
	v_cndmask_b32_e64 v63, v58, 0, vcc
	v_cndmask_b32_e64 v58, v48, 0, s[28:29]
	v_pk_fma_f32 v[48:49], v[66:67], v[50:51], v[54:55]
	v_mul_f32_e32 v50, 0x3d372713, v60
	v_mul_f32_e32 v50, v60, v50
	v_fma_f32 v50, v60, v50, v60
	v_mul_f32_e32 v50, 0x3f4c422a, v50
	v_mul_f32_e32 v50, 0x4038aa3b, v50
	v_exp_f32_e32 v54, v50
	v_mul_f32_e32 v50, 0x3d372713, v61
	v_mul_f32_e32 v50, v61, v50
	v_fma_f32 v50, v61, v50, v61
	v_pk_fma_f32 v[56:57], v[76:77], v[62:63], v[80:81]
	v_mul_f32_e32 v50, 0x3f4c422a, v50
	v_pk_fma_f32 v[56:57], v[40:41], v[68:69], v[56:57]
	v_mul_f32_e32 v50, 0x4038aa3b, v50
	v_exp_f32_e32 v55, v50
	v_pk_fma_f32 v[50:51], v[64:65], v[58:59], v[56:57]
	v_mul_f32_e32 v56, 0x3d372713, v52
	v_mul_f32_e32 v57, 0x3d372713, v53
	v_mul_f32_e32 v56, v52, v56
	v_mul_f32_e32 v57, v53, v57
	v_fma_f32 v56, v52, v56, v52
	v_fma_f32 v57, v53, v57, v53
	v_mul_f32_e32 v56, 0x3f4c422a, v56
	v_mul_f32_e32 v57, 0x3f4c422a, v57
	v_mul_f32_e32 v56, 0x4038aa3b, v56
	v_mul_f32_e32 v57, 0x4038aa3b, v57
	v_exp_f32_e32 v56, v56
	v_exp_f32_e32 v57, v57
	v_add_f32_e32 v54, 1.0, v54
	v_add_f32_e32 v55, 1.0, v55
	v_add_f32_e32 v56, 1.0, v56
	v_add_f32_e32 v57, 1.0, v57
	v_rcp_f32_e32 v54, v54
	v_rcp_f32_e32 v55, v55
	v_rcp_f32_e32 v56, v56
	v_rcp_f32_e32 v57, v57
	v_pk_fma_f32 v[54:55], v[60:61], v[54:55], v[60:61] neg_lo:[1,0,0] neg_hi:[1,0,0]
	s_nop 0
	v_pk_mul_f32 v[50:51], v[50:51], v[54:55]
	v_pk_fma_f32 v[52:53], v[52:53], v[56:57], v[52:53] neg_lo:[1,0,0] neg_hi:[1,0,0]
	v_cvt_pk_bf16_f32 v50, v50, v51
	v_pk_mul_f32 v[48:49], v[48:49], v[52:53]
	s_nop 0
	v_cvt_pk_bf16_f32 v51, v48, v49
	v_lshl_add_u64 v[48:49], s[34:35], 0, v[108:109]
	v_lshl_add_u64 v[48:49], v[180:181], 1, v[48:49]
	global_store_dwordx2 v[48:49], v[50:51], off
; #define LAS __attribute__((address_space(3)))
; #define GAS __attribute__((address_space(1)))
;     DI f32x4 conv1(const Acc& acc, int ai, int bj, int n, int m, int fr, const f32x4& above, const f32x4& below, const f32x4& w0, const f32x4& w1, const f32x4& w2, const f32x4& b, bool zp, bool zn) const {
;         const f32x4 cur = acc[ai][bj][m][n];
;         const f32x4 tp = (m > 0 && fr == 15) ? acc[ai][bj][m > 0 ? m - 1 : 0][n] : cur;
;         const f32x4 tn = (m < 3 && fr == 0) ? acc[ai][bj][m < 3 ? m + 1 : 3][n] : cur;
;         f32x4 pv = ror4(tp), nx = rol4(tn);
;         if (m == 0 && fr == 0) pv = above;
;         if (m == 3 && fr == 15) nx = below;
;         if (zp) pv = (f32x4){0.f, 0.f, 0.f, 0.f};
;         if (zn) nx = (f32x4){0.f, 0.f, 0.f, 0.f};
;         return b + w0 * pv + w1 * cur + w2 * nx;
;     }
;     DI void operator()(const Acc& acc, const Unit& u, int wr, int wc, int fr, int fq, LAS unsigned char* scr) const {
;         LAS float* H = (LAS float*)scr;
;         const int colb = wc * 32 + 8 * fq;
;         if (fr == 0 || fr == 15) {
; #pragma unroll
;             for (int ai = 0; ai < 2; ++ai)
; #pragma unroll
;                 for (int bj = 0; bj < 2; ++bj)
; #pragma unroll
;                     for (int n = 0; n < 2; ++n) {
;                         LAS f32x4* dst = (LAS f32x4*)(H + (((2 * ai + wr) * 2 + (fr == 0 ? 0 : 1)) * 256 + bj * HALF + colb + 4 * n));
;                         *dst = (fr == 0) ? acc[ai][bj][0][n] : acc[ai][bj][3][n];
;                     }
;         }
;         asm volatile("s_waitcnt lgkmcnt(0)" ::: "memory"); __builtin_amdgcn_s_barrier(); asm volatile("" ::: "memory");
;         const int f0 = u.pn * 128 + colb;
;         const int row_base = 254 * u.pm - 1;
; #pragma unroll
;         for (int ai = 0; ai < 2; ++ai) {
;             const int k = 2 * ai + wr, ka = k > 0 ? k - 1 : 0, kb = k < 3 ? k + 1 : 3;
; #pragma unroll
;             for (int n = 0; n < 2; ++n) {
;                 const float* wp = cw + f0 + 4 * n;
;                 const f32x4 g0 = *(const f32x4*)wp, g1 = *(const GAS f32x4*)(wp + DFF2), g2 = *(const GAS f32x4*)(wp + 2 * DFF2), gb = *(const GAS f32x4*)(cb + f0 + 4 * n);
;                 const f32x4 v0 = *(const GAS f32x4*)(wp + DFF), v1 = *(const GAS f32x4*)(wp + DFF + DFF2), v2 = *(const GAS f32x4*)(wp + DFF + 2 * DFF2), vb = *(const GAS f32x4*)(cb + DFF + f0 + 4 * n);
.LBB0_840:
	s_or_b64 exec, exec, s[58:59]
	v_add_u32_e32 v56, s47, v219
	s_movk_i32 s28, 0x3fff
	v_cmp_lt_i32_e32 vcc, s28, v56
	v_mov_b32_e32 v48, 0xfff
	v_mov_b32_e32 v49, 0x3fff
	v_cndmask_b32_e64 v46, v38, v46, s[8:9]
	v_cndmask_b32_e64 v45, v37, v45, s[8:9]
	v_cndmask_b32_e64 v44, v36, v44, s[8:9]
	v_mov_b32_e32 v52, v193
	v_mov_b32_e32 v54, v193
	v_mov_b32_e32 v53, v193
	v_cndmask_b32_e32 v57, v48, v49, vcc
	v_cndmask_b32_e64 v47, v39, v47, s[8:9]
	v_mov_b32_dpp v52, v44 row_ror:1 row_mask:0xf bank_mask:0xf
	v_mov_b32_dpp v54, v45 row_ror:1 row_mask:0xf bank_mask:0xf
	v_mov_b32_dpp v53, v46 row_ror:1 row_mask:0xf bank_mask:0xf
	v_mov_b32_e32 v55, v193
	v_cndmask_b32_e64 v43, v35, v43, s[8:9]
	v_cndmask_b32_e64 v42, v34, v42, s[8:9]
	v_cndmask_b32_e64 v41, v33, v41, s[8:9]
	v_cndmask_b32_e64 v40, v32, v40, s[8:9]
	v_mov_b32_e32 v44, v193
	v_mov_b32_e32 v46, v193
	v_mov_b32_e32 v45, v193
	v_mov_b32_e32 v49, v193
	s_mov_b32 s28, 0xc000
	v_add_u32_e32 v58, s33, v219
	v_mov_b32_dpp v55, v47 row_ror:1 row_mask:0xf bank_mask:0xf
	v_mov_b32_e32 v47, v193
	v_mov_b32_e32 v48, v193
	v_mov_b32_e32 v50, v193
	v_mov_b32_e32 v51, v193
	v_mov_b32_dpp v44, v40 row_ror:1 row_mask:0xf bank_mask:0xf
	v_mov_b32_dpp v46, v41 row_ror:1 row_mask:0xf bank_mask:0xf
	v_mov_b32_dpp v45, v42 row_ror:1 row_mask:0xf bank_mask:0xf
	v_mov_b32_dpp v49, v43 row_ror:1 row_mask:0xf bank_mask:0xf
	v_mov_b32_e32 v40, v193
	v_mov_b32_e32 v41, v193
	v_mov_b32_e32 v42, v193
	v_mov_b32_e32 v43, v193
	v_cmp_gt_u32_e32 vcc, s28, v56
	v_mov_b32_dpp v47, v36 row_ror:15 row_mask:0xf bank_mask:0xf
	v_mov_b32_dpp v48, v37 row_ror:15 row_mask:0xf bank_mask:0xf
	v_mov_b32_dpp v50, v38 row_ror:15 row_mask:0xf bank_mask:0xf
	v_mov_b32_dpp v51, v39 row_ror:15 row_mask:0xf bank_mask:0xf
	v_mov_b32_dpp v40, v32 row_ror:15 row_mask:0xf bank_mask:0xf
	v_mov_b32_dpp v41, v33 row_ror:15 row_mask:0xf bank_mask:0xf
	v_mov_b32_dpp v42, v34 row_ror:15 row_mask:0xf bank_mask:0xf
	v_mov_b32_dpp v43, v35 row_ror:15 row_mask:0xf bank_mask:0xf
	s_and_b64 s[58:59], s[24:25], vcc
	v_and_b32_e32 v119, v57, v56
	v_and_b32_e32 v116, v57, v58
	v_mul_lo_u32 v110, v56, s89
	s_and_saveexec_b64 s[60:61], s[58:59]
	s_cbranch_execz .LBB0_842
	v_cmp_eq_u32_e32 vcc, 0, v119
	s_waitcnt lgkmcnt(0)
	v_cndmask_b32_e64 v48, v48, v93, s[8:9]
	v_cmp_eq_u32_e64 s[28:29], 0, v116
	v_cndmask_b32_e64 v57, v54, 0, vcc
	v_cndmask_b32_e64 v55, v55, 0, vcc
	v_cndmask_b32_e64 v54, v53, 0, vcc
	v_cndmask_b32_e64 v56, v52, 0, vcc
	v_pk_fma_f32 v[52:53], v[98:99], v[54:55], v[102:103]
	v_pk_fma_f32 v[54:55], v[96:97], v[56:57], v[100:101]
	v_pk_fma_f32 v[38:39], v[38:39], v[90:91], v[52:53]
	v_cndmask_b32_e64 v53, v51, v95, s[8:9]
	v_cndmask_b32_e64 v47, v47, v92, s[8:9]
	v_cndmask_b32_e64 v51, v48, 0, s[28:29]
	v_cndmask_b32_e64 v49, v49, 0, vcc
	v_cndmask_b32_e64 v48, v45, 0, vcc
	v_pk_fma_f32 v[36:37], v[36:37], v[88:89], v[54:55]
	v_cndmask_b32_e64 v52, v50, v94, s[8:9]
	v_cndmask_b32_e64 v50, v47, 0, s[28:29]
	v_cndmask_b32_e64 v47, v46, 0, vcc
	v_cndmask_b32_e64 v46, v44, 0, vcc
	v_pk_fma_f32 v[44:45], v[78:79], v[48:49], v[82:83]
	v_cndmask_b32_e64 v42, v42, v74, s[8:9]
	v_cndmask_b32_e64 v43, v43, v75, s[8:9]
	v_pk_fma_f32 v[36:37], v[84:85], v[50:51], v[36:37]
	v_pk_fma_f32 v[34:35], v[34:35], v[70:71], v[44:45]
	v_cndmask_b32_e64 v43, v43, 0, s[28:29]
	v_cndmask_b32_e64 v42, v42, 0, s[28:29]
	v_pk_fma_f32 v[34:35], v[66:67], v[42:43], v[34:35]
	v_mul_f32_e32 v42, 0x3d372713, v36
	v_mul_f32_e32 v43, 0x3d372713, v37
	v_mul_f32_e32 v42, v36, v42
	v_mul_f32_e32 v43, v37, v43
	v_fma_f32 v42, v36, v42, v36
	v_fma_f32 v43, v37, v43, v37
	v_mul_f32_e32 v42, 0x3f4c422a, v42
	v_mul_f32_e32 v43, 0x3f4c422a, v43
	v_mul_f32_e32 v42, 0x4038aa3b, v42
	v_mul_f32_e32 v43, 0x4038aa3b, v43
	v_exp_f32_e32 v42, v42
	v_exp_f32_e32 v43, v43
	v_cndmask_b32_e64 v53, v53, 0, s[28:29]
	v_cndmask_b32_e64 v52, v52, 0, s[28:29]
	v_pk_fma_f32 v[46:47], v[76:77], v[46:47], v[80:81]
	v_cndmask_b32_e64 v40, v40, v72, s[8:9]
	v_cndmask_b32_e64 v41, v41, v73, s[8:9]
	v_pk_fma_f32 v[38:39], v[86:87], v[52:53], v[38:39]
	v_pk_fma_f32 v[32:33], v[32:33], v[68:69], v[46:47]
	v_cndmask_b32_e64 v41, v41, 0, s[28:29]
	v_cndmask_b32_e64 v40, v40, 0, s[28:29]
	v_pk_fma_f32 v[32:33], v[64:65], v[40:41], v[32:33]
	v_add_f32_e32 v40, 1.0, v42
	v_add_f32_e32 v41, 1.0, v43
	v_mul_f32_e32 v42, 0x3d372713, v38
	v_mul_f32_e32 v43, 0x3d372713, v39
	v_mul_f32_e32 v42, v38, v42
	v_mul_f32_e32 v43, v39, v43
	v_fma_f32 v42, v38, v42, v38
	v_fma_f32 v43, v39, v43, v39
	v_mul_f32_e32 v42, 0x3f4c422a, v42
	v_mul_f32_e32 v43, 0x3f4c422a, v43
	v_mul_f32_e32 v42, 0x4038aa3b, v42
	v_mul_f32_e32 v43, 0x4038aa3b, v43
	v_exp_f32_e32 v42, v42
	v_exp_f32_e32 v43, v43
	v_rcp_f32_e32 v40, v40
	v_rcp_f32_e32 v41, v41
	v_add_f32_e32 v42, 1.0, v42
	v_add_f32_e32 v43, 1.0, v43
	v_rcp_f32_e32 v42, v42
	v_rcp_f32_e32 v43, v43
	v_pk_fma_f32 v[36:37], v[36:37], v[40:41], v[36:37] neg_lo:[1,0,0] neg_hi:[1,0,0]
	v_mov_b32_e32 v111, v193
	v_pk_mul_f32 v[32:33], v[32:33], v[36:37]
	v_pk_fma_f32 v[36:37], v[38:39], v[42:43], v[38:39] neg_lo:[1,0,0] neg_hi:[1,0,0]
	v_cvt_pk_bf16_f32 v32, v32, v33
	v_pk_mul_f32 v[34:35], v[34:35], v[36:37]
	s_nop 0
	v_cvt_pk_bf16_f32 v33, v34, v35
	v_lshl_add_u64 v[34:35], s[34:35], 0, v[110:111]
	v_lshl_add_u64 v[34:35], v[180:181], 1, v[34:35]
	global_store_dwordx2 v[34:35], v[32:33], off
; #define LAS __attribute__((address_space(3)))
; #define GAS __attribute__((address_space(1)))
;     DI f32x4 conv1(const Acc& acc, int ai, int bj, int n, int m, int fr, const f32x4& above, const f32x4& below, const f32x4& w0, const f32x4& w1, const f32x4& w2, const f32x4& b, bool zp, bool zn) const {
;         const f32x4 cur = acc[ai][bj][m][n];
;         const f32x4 tp = (m > 0 && fr == 15) ? acc[ai][bj][m > 0 ? m - 1 : 0][n] : cur;
;         const f32x4 tn = (m < 3 && fr == 0) ? acc[ai][bj][m < 3 ? m + 1 : 3][n] : cur;
;         f32x4 pv = ror4(tp), nx = rol4(tn);
;         if (m == 0 && fr == 0) pv = above;
;         if (m == 3 && fr == 15) nx = below;
;         if (zp) pv = (f32x4){0.f, 0.f, 0.f, 0.f};
;         if (zn) nx = (f32x4){0.f, 0.f, 0.f, 0.f};
;         return b + w0 * pv + w1 * cur + w2 * nx;
;     }
;     DI void operator()(const Acc& acc, const Unit& u, int wr, int wc, int fr, int fq, LAS unsigned char* scr) const {
;         LAS float* H = (LAS float*)scr;
;         const int colb = wc * 32 + 8 * fq;
;         if (fr == 0 || fr == 15) {
; #pragma unroll
;             for (int ai = 0; ai < 2; ++ai)
; #pragma unroll
;                 for (int bj = 0; bj < 2; ++bj)
; #pragma unroll
;                     for (int n = 0; n < 2; ++n) {
;                         LAS f32x4* dst = (LAS f32x4*)(H + (((2 * ai + wr) * 2 + (fr == 0 ? 0 : 1)) * 256 + bj * HALF + colb + 4 * n));
;                         *dst = (fr == 0) ? acc[ai][bj][0][n] : acc[ai][bj][3][n];
;                     }
;         }
;         asm volatile("s_waitcnt lgkmcnt(0)" ::: "memory"); __builtin_amdgcn_s_barrier(); asm volatile("" ::: "memory");
;         const int f0 = u.pn * 128 + colb;
;         const int row_base = 254 * u.pm - 1;
; #pragma unroll
;         for (int ai = 0; ai < 2; ++ai) {
;             const int k = 2 * ai + wr, ka = k > 0 ? k - 1 : 0, kb = k < 3 ? k + 1 : 3;
; #pragma unroll
;             for (int n = 0; n < 2; ++n) {
;                 const float* wp = cw + f0 + 4 * n;
;                 const f32x4 g0 = *(const f32x4*)wp, g1 = *(const GAS f32x4*)(wp + DFF2), g2 = *(const GAS f32x4*)(wp + 2 * DFF2), gb = *(const GAS f32x4*)(cb + f0 + 4 * n);
;                 const f32x4 v0 = *(const GAS f32x4*)(wp + DFF), v1 = *(const GAS f32x4*)(wp + DFF + DFF2), v2 = *(const GAS f32x4*)(wp + DFF + 2 * DFF2), vb = *(const GAS f32x4*)(cb + DFF + f0 + 4 * n);
.LBB0_842:
	s_or_b64 exec, exec, s[60:61]
	s_mov_b64 s[28:29], 0x5810
	v_lshl_add_u64 v[32:33], v[182:183], 0, s[28:29]
	s_mov_b64 s[28:29], 0xb010
	v_lshl_add_u64 v[34:35], v[182:183], 0, s[28:29]
	s_mov_b64 s[60:61], 0x2c10
	s_mov_b64 s[28:29], 0x8410
	v_lshl_add_u64 v[36:37], v[182:183], 0, s[60:61]
	v_lshl_add_u64 v[38:39], v[182:183], 0, s[28:29]
	s_mov_b64 s[28:29], 0xdc10
	v_lshl_add_u64 v[40:41], v[182:183], 0, s[28:29]
	v_lshl_add_u64 v[42:43], v[184:185], 0, s[60:61]
	flat_load_dwordx4 v[64:67], v[182:183] offset:16
	global_load_dwordx4 v[56:59], v[32:33], off
	global_load_dwordx4 v[52:55], v[34:35], off
	global_load_dwordx4 v[68:71], v[184:185], off offset:16
	global_load_dwordx4 v[44:47], v[36:37], off
	s_nop 0
	global_load_dwordx4 v[36:39], v[38:39], off
	s_nop 0
	global_load_dwordx4 v[32:35], v[40:41], off
	global_load_dwordx4 v[48:51], v[42:43], off
	s_waitcnt lgkmcnt(0)
	v_cndmask_b32_e64 v74, v31, v23, s[6:7]
	v_cndmask_b32_e64 v73, v29, v21, s[6:7]
	v_cndmask_b32_e64 v76, v28, v20, s[6:7]
	v_mov_b32_e32 v72, v193
	v_mov_b32_e32 v82, v193
	v_mov_b32_e32 v85, v193
	ds_read_b128 v[60:63], v214 offset:2064
	ds_read_b128 v[40:43], v214 offset:2576
	v_cndmask_b32_e64 v75, v30, v22, s[6:7]
	v_mov_b32_dpp v72, v76 row_ror:15 row_mask:0xf bank_mask:0xf
	v_mov_b32_dpp v82, v73 row_ror:15 row_mask:0xf bank_mask:0xf
	v_mov_b32_e32 v73, v193
	v_mov_b32_dpp v85, v74 row_ror:15 row_mask:0xf bank_mask:0xf
	v_cndmask_b32_e64 v76, v24, v16, s[6:7]
	v_mov_b32_e32 v74, v193
	v_mov_b32_dpp v73, v75 row_ror:15 row_mask:0xf bank_mask:0xf
	v_cndmask_b32_e64 v75, v25, v17, s[6:7]
	v_mov_b32_dpp v74, v76 row_ror:15 row_mask:0xf bank_mask:0xf
	v_mov_b32_e32 v76, v193
	v_cndmask_b32_e64 v77, v26, v18, s[6:7]
	v_mov_b32_e32 v83, v193
	v_mov_b32_dpp v76, v75 row_ror:15 row_mask:0xf bank_mask:0xf
	v_mov_b32_e32 v75, v193
	v_mov_b32_e32 v84, v193
	v_mov_b32_e32 v86, v193
	v_mov_b32_e32 v87, v193
	v_cndmask_b32_e64 v88, v27, v19, s[6:7]
	v_mov_b32_e32 v78, v193
	v_mov_b32_e32 v79, v193
	v_mov_b32_e32 v80, v193
	v_mov_b32_e32 v81, v193
	v_mov_b32_dpp v75, v77 row_ror:15 row_mask:0xf bank_mask:0xf
	v_mov_b32_e32 v77, v193
	v_mov_b32_dpp v83, v28 row_ror:1 row_mask:0xf bank_mask:0xf
	v_mov_b32_dpp v84, v29 row_ror:1 row_mask:0xf bank_mask:0xf
	v_mov_b32_dpp v86, v30 row_ror:1 row_mask:0xf bank_mask:0xf
	v_mov_b32_dpp v87, v31 row_ror:1 row_mask:0xf bank_mask:0xf
	v_mov_b32_dpp v78, v24 row_ror:1 row_mask:0xf bank_mask:0xf
	v_mov_b32_dpp v79, v25 row_ror:1 row_mask:0xf bank_mask:0xf
	v_mov_b32_dpp v80, v26 row_ror:1 row_mask:0xf bank_mask:0xf
	v_mov_b32_dpp v81, v27 row_ror:1 row_mask:0xf bank_mask:0xf
	v_mov_b32_dpp v77, v88 row_ror:15 row_mask:0xf bank_mask:0xf
	s_and_saveexec_b64 s[60:61], s[52:53]
	s_cbranch_execz .LBB0_844
	ds_read_b128 v[88:91], v213 offset:16
	v_cmp_eq_u32_e64 s[28:29], 0, v114
	v_cmp_eq_u32_e32 vcc, 0, v112
	v_mov_b32_e32 v105, v193
	s_waitcnt lgkmcnt(0)
	v_cndmask_b32_e64 v90, v86, v90, s[6:7]
	v_cndmask_b32_e64 v91, v87, v91, s[6:7]
	v_cndmask_b32_e64 v83, v83, v88, s[6:7]
	v_cndmask_b32_e64 v84, v84, v89, s[6:7]
	v_cndmask_b32_e64 v87, v84, 0, s[28:29]
	v_cndmask_b32_e64 v86, v83, 0, s[28:29]
	v_cndmask_b32_e64 v89, v91, 0, s[28:29]
	v_cndmask_b32_e64 v88, v90, 0, s[28:29]
	s_waitcnt vmcnt(0)
	v_pk_fma_f32 v[88:89], v[66:67], v[88:89], v[70:71]
	v_pk_fma_f32 v[86:87], v[64:65], v[86:87], v[68:69]
	v_pk_fma_f32 v[88:89], v[30:31], v[58:59], v[88:89]
	v_pk_fma_f32 v[86:87], v[28:29], v[56:57], v[86:87]
	v_cndmask_b32_e64 v83, v82, 0, vcc
	v_cndmask_b32_e64 v82, v72, 0, vcc
	v_cndmask_b32_e64 v85, v85, 0, vcc
	v_cndmask_b32_e64 v84, v73, 0, vcc
	v_pk_fma_f32 v[72:73], v[54:55], v[84:85], v[88:89]
	v_pk_fma_f32 v[86:87], v[52:53], v[82:83], v[86:87]
	ds_read_b128 v[82:85], v215 offset:16
	v_cndmask_b32_e64 v77, v77, 0, vcc
	s_waitcnt lgkmcnt(0)
	v_cndmask_b32_e64 v80, v80, v84, s[6:7]
	v_cndmask_b32_e64 v81, v81, v85, s[6:7]
	v_cndmask_b32_e64 v78, v78, v82, s[6:7]
	v_cndmask_b32_e64 v79, v79, v83, s[6:7]
	v_cndmask_b32_e64 v79, v79, 0, s[28:29]
	v_cndmask_b32_e64 v78, v78, 0, s[28:29]
	v_cndmask_b32_e64 v81, v81, 0, s[28:29]
	v_cndmask_b32_e64 v80, v80, 0, s[28:29]
	v_pk_fma_f32 v[80:81], v[46:47], v[80:81], v[50:51]
	v_pk_fma_f32 v[78:79], v[44:45], v[78:79], v[48:49]
	v_pk_fma_f32 v[80:81], v[26:27], v[38:39], v[80:81]
	v_pk_fma_f32 v[78:79], v[24:25], v[36:37], v[78:79]
	v_cndmask_b32_e64 v83, v76, 0, vcc
	v_cndmask_b32_e64 v82, v74, 0, vcc
	v_cndmask_b32_e64 v76, v75, 0, vcc
	v_pk_fma_f32 v[74:75], v[34:35], v[76:77], v[80:81]
	v_pk_fma_f32 v[76:77], v[32:33], v[82:83], v[78:79]
	v_mul_f32_e32 v78, 0x3d372713, v86
	v_mul_f32_e32 v79, 0x3d372713, v87
	v_mul_f32_e32 v78, v86, v78
	v_mul_f32_e32 v79, v87, v79
	v_fma_f32 v78, v86, v78, v86
	v_fma_f32 v79, v87, v79, v87
	v_mul_f32_e32 v78, 0x3f4c422a, v78
	v_mul_f32_e32 v79, 0x3f4c422a, v79
	v_mul_f32_e32 v78, 0x4038aa3b, v78
	v_mul_f32_e32 v79, 0x4038aa3b, v79
	v_exp_f32_e32 v78, v78
	v_exp_f32_e32 v79, v79
	v_add_f32_e32 v78, 1.0, v78
	v_add_f32_e32 v79, 1.0, v79
	v_rcp_f32_e32 v78, v78
	v_rcp_f32_e32 v79, v79
	s_nop 0
	v_pk_fma_f32 v[78:79], v[86:87], v[78:79], v[86:87] neg_lo:[1,0,0] neg_hi:[1,0,0]
	s_nop 0
	v_pk_mul_f32 v[76:77], v[76:77], v[78:79]
	s_nop 0
	v_cvt_pk_bf16_f32 v76, v76, v77
	v_mul_f32_e32 v77, 0x3d372713, v72
	v_mul_f32_e32 v77, v72, v77
	v_fma_f32 v77, v72, v77, v72
	v_mul_f32_e32 v77, 0x3f4c422a, v77
	v_mul_f32_e32 v77, 0x4038aa3b, v77
	v_exp_f32_e32 v77, v77
	s_nop 0
	v_add_f32_e32 v77, 1.0, v77
	v_rcp_f32_e32 v78, v77
	v_mul_f32_e32 v77, 0x3d372713, v73
	v_mul_f32_e32 v77, v73, v77
	v_fma_f32 v77, v73, v77, v73
	v_mul_f32_e32 v77, 0x3f4c422a, v77
	v_mul_f32_e32 v77, 0x4038aa3b, v77
	v_exp_f32_e32 v77, v77
	s_nop 0
	v_add_f32_e32 v77, 1.0, v77
	v_rcp_f32_e32 v79, v77
	s_nop 0
	v_pk_fma_f32 v[72:73], v[72:73], v[78:79], v[72:73] neg_lo:[1,0,0] neg_hi:[1,0,0]
	s_nop 0
	v_pk_mul_f32 v[72:73], v[74:75], v[72:73]
	s_nop 0
	v_cvt_pk_bf16_f32 v77, v72, v73
	v_lshl_add_u64 v[72:73], s[34:35], 0, v[104:105]
	v_lshl_add_u64 v[72:73], v[180:181], 1, v[72:73]
	global_store_dwordx2 v[72:73], v[76:77], off offset:8
; #define LAS __attribute__((address_space(3)))
; #define GAS __attribute__((address_space(1)))
;     DI f32x4 conv1(const Acc& acc, int ai, int bj, int n, int m, int fr, const f32x4& above, const f32x4& below, const f32x4& w0, const f32x4& w1, const f32x4& w2, const f32x4& b, bool zp, bool zn) const {
;         const f32x4 cur = acc[ai][bj][m][n];
;         const f32x4 tp = (m > 0 && fr == 15) ? acc[ai][bj][m > 0 ? m - 1 : 0][n] : cur;
;         const f32x4 tn = (m < 3 && fr == 0) ? acc[ai][bj][m < 3 ? m + 1 : 3][n] : cur;
;         f32x4 pv = ror4(tp), nx = rol4(tn);
;         if (m == 0 && fr == 0) pv = above;
;         if (m == 3 && fr == 15) nx = below;
;         if (zp) pv = (f32x4){0.f, 0.f, 0.f, 0.f};
;         if (zn) nx = (f32x4){0.f, 0.f, 0.f, 0.f};
;         return b + w0 * pv + w1 * cur + w2 * nx;
;     }
;     DI void operator()(const Acc& acc, const Unit& u, int wr, int wc, int fr, int fq, LAS unsigned char* scr) const {
;         LAS float* H = (LAS float*)scr;
;         const int colb = wc * 32 + 8 * fq;
;         if (fr == 0 || fr == 15) {
; #pragma unroll
;             for (int ai = 0; ai < 2; ++ai)
; #pragma unroll
;                 for (int bj = 0; bj < 2; ++bj)
; #pragma unroll
;                     for (int n = 0; n < 2; ++n) {
;                         LAS f32x4* dst = (LAS f32x4*)(H + (((2 * ai + wr) * 2 + (fr == 0 ? 0 : 1)) * 256 + bj * HALF + colb + 4 * n));
;                         *dst = (fr == 0) ? acc[ai][bj][0][n] : acc[ai][bj][3][n];
;                     }
;         }
;         asm volatile("s_waitcnt lgkmcnt(0)" ::: "memory"); __builtin_amdgcn_s_barrier(); asm volatile("" ::: "memory");
;         const int f0 = u.pn * 128 + colb;
;         const int row_base = 254 * u.pm - 1;
; #pragma unroll
;         for (int ai = 0; ai < 2; ++ai) {
;             const int k = 2 * ai + wr, ka = k > 0 ? k - 1 : 0, kb = k < 3 ? k + 1 : 3;
; #pragma unroll
;             for (int n = 0; n < 2; ++n) {
;                 const float* wp = cw + f0 + 4 * n;
;                 const f32x4 g0 = *(const f32x4*)wp, g1 = *(const GAS f32x4*)(wp + DFF2), g2 = *(const GAS f32x4*)(wp + 2 * DFF2), gb = *(const GAS f32x4*)(cb + f0 + 4 * n);
;                 const f32x4 v0 = *(const GAS f32x4*)(wp + DFF), v1 = *(const GAS f32x4*)(wp + DFF + DFF2), v2 = *(const GAS f32x4*)(wp + DFF + 2 * DFF2), vb = *(const GAS f32x4*)(cb + DFF + f0 + 4 * n);
.LBB0_844:
	s_or_b64 exec, exec, s[60:61]
	v_cndmask_b32_e64 v29, v21, v29, s[8:9]
	v_mov_b32_e32 v78, v193
	v_cndmask_b32_e64 v30, v22, v30, s[8:9]
	v_cndmask_b32_e64 v28, v20, v28, s[8:9]
	v_cndmask_b32_e64 v72, v22, v14, s[6:7]
	v_mov_b32_e32 v76, v193
	v_mov_b32_dpp v78, v29 row_ror:1 row_mask:0xf bank_mask:0xf
	v_mov_b32_e32 v77, v193
	v_mov_b32_e32 v29, v193
	v_cndmask_b32_e64 v31, v23, v31, s[8:9]
	v_cndmask_b32_e64 v73, v23, v15, s[6:7]
	v_cndmask_b32_e64 v74, v21, v13, s[6:7]
	v_cndmask_b32_e64 v75, v20, v12, s[6:7]
	v_mov_b32_dpp v76, v28 row_ror:1 row_mask:0xf bank_mask:0xf
	v_mov_b32_dpp v77, v30 row_ror:1 row_mask:0xf bank_mask:0xf
	v_mov_b32_e32 v79, v193
	v_mov_b32_e32 v28, v193
	v_mov_b32_e32 v30, v193
	v_mov_b32_dpp v29, v72 row_ror:15 row_mask:0xf bank_mask:0xf
	v_mov_b32_e32 v72, v193
	v_mov_b32_dpp v79, v31 row_ror:1 row_mask:0xf bank_mask:0xf
	v_mov_b32_dpp v28, v75 row_ror:15 row_mask:0xf bank_mask:0xf
	v_mov_b32_dpp v30, v74 row_ror:15 row_mask:0xf bank_mask:0xf
	v_mov_b32_dpp v72, v73 row_ror:15 row_mask:0xf bank_mask:0xf
	v_cndmask_b32_e64 v27, v19, v27, s[8:9]
	v_cndmask_b32_e64 v26, v18, v26, s[8:9]
	v_cndmask_b32_e64 v25, v17, v25, s[8:9]
	v_cndmask_b32_e64 v24, v16, v24, s[8:9]
	v_mov_b32_e32 v31, v193
	v_mov_b32_e32 v74, v193
	v_mov_b32_e32 v73, v193
	v_mov_b32_e32 v75, v193
	v_cndmask_b32_e64 v80, v19, v11, s[6:7]
	v_cndmask_b32_e64 v81, v18, v10, s[6:7]
	v_cndmask_b32_e64 v82, v17, v9, s[6:7]
	v_cndmask_b32_e64 v83, v16, v8, s[6:7]
	v_mov_b32_dpp v31, v24 row_ror:1 row_mask:0xf bank_mask:0xf
	v_mov_b32_dpp v74, v25 row_ror:1 row_mask:0xf bank_mask:0xf
	v_mov_b32_dpp v73, v26 row_ror:1 row_mask:0xf bank_mask:0xf
	v_mov_b32_dpp v75, v27 row_ror:1 row_mask:0xf bank_mask:0xf
	v_mov_b32_e32 v24, v193
	v_mov_b32_e32 v26, v193
	v_mov_b32_e32 v25, v193
	v_mov_b32_e32 v27, v193
	v_mov_b32_dpp v24, v83 row_ror:15 row_mask:0xf bank_mask:0xf
	v_mov_b32_dpp v26, v82 row_ror:15 row_mask:0xf bank_mask:0xf
	v_mov_b32_dpp v25, v81 row_ror:15 row_mask:0xf bank_mask:0xf
	v_mov_b32_dpp v27, v80 row_ror:15 row_mask:0xf bank_mask:0xf
	s_and_saveexec_b64 s[52:53], s[54:55]
	s_cbranch_execz .LBB0_846
	v_cmp_eq_u32_e32 vcc, 0, v117
	v_cmp_eq_u32_e64 s[28:29], 0, v113
	v_mov_b32_e32 v107, v193
	v_cndmask_b32_e64 v81, v78, 0, vcc
	v_cndmask_b32_e64 v80, v76, 0, vcc
	v_cndmask_b32_e64 v79, v79, 0, vcc
	v_cndmask_b32_e64 v78, v77, 0, vcc
	v_pk_fma_f32 v[76:77], v[66:67], v[78:79], v[70:71]
	v_pk_fma_f32 v[78:79], v[64:65], v[80:81], v[68:69]
	v_pk_fma_f32 v[76:77], v[22:23], v[58:59], v[76:77]
	v_pk_fma_f32 v[78:79], v[20:21], v[56:57], v[78:79]
	v_cndmask_b32_e64 v81, v30, 0, s[28:29]
	v_cndmask_b32_e64 v80, v28, 0, s[28:29]
	v_cndmask_b32_e64 v83, v72, 0, s[28:29]
	v_cndmask_b32_e64 v82, v29, 0, s[28:29]
	v_pk_fma_f32 v[28:29], v[54:55], v[82:83], v[76:77]
	v_pk_fma_f32 v[76:77], v[52:53], v[80:81], v[78:79]
	v_cndmask_b32_e64 v78, v31, 0, vcc
	v_cndmask_b32_e64 v31, v75, 0, vcc
	v_cndmask_b32_e64 v30, v73, 0, vcc
	v_pk_fma_f32 v[30:31], v[46:47], v[30:31], v[50:51]
	v_cndmask_b32_e64 v75, v26, 0, s[28:29]
	v_pk_fma_f32 v[30:31], v[18:19], v[38:39], v[30:31]
	v_cndmask_b32_e64 v27, v27, 0, s[28:29]
	v_cndmask_b32_e64 v26, v25, 0, s[28:29]
	v_cndmask_b32_e64 v79, v74, 0, vcc
	v_cndmask_b32_e64 v74, v24, 0, s[28:29]
	v_pk_fma_f32 v[24:25], v[34:35], v[26:27], v[30:31]
	v_mul_f32_e32 v26, 0x3d372713, v76
	v_mul_f32_e32 v26, v76, v26
	v_fma_f32 v26, v76, v26, v76
	v_mul_f32_e32 v26, 0x3f4c422a, v26
	v_mul_f32_e32 v26, 0x4038aa3b, v26
	v_exp_f32_e32 v30, v26
	v_mul_f32_e32 v26, 0x3d372713, v77
	v_mul_f32_e32 v26, v77, v26
	v_fma_f32 v26, v77, v26, v77
	v_pk_fma_f32 v[72:73], v[44:45], v[78:79], v[48:49]
	v_mul_f32_e32 v26, 0x3f4c422a, v26
	v_pk_fma_f32 v[72:73], v[16:17], v[36:37], v[72:73]
	v_mul_f32_e32 v26, 0x4038aa3b, v26
	v_exp_f32_e32 v31, v26
	v_pk_fma_f32 v[26:27], v[32:33], v[74:75], v[72:73]
	v_mul_f32_e32 v72, 0x3d372713, v28
	v_mul_f32_e32 v73, 0x3d372713, v29
	v_mul_f32_e32 v72, v28, v72
	v_mul_f32_e32 v73, v29, v73
	v_fma_f32 v72, v28, v72, v28
	v_fma_f32 v73, v29, v73, v29
	v_mul_f32_e32 v72, 0x3f4c422a, v72
	v_mul_f32_e32 v73, 0x3f4c422a, v73
	v_mul_f32_e32 v72, 0x4038aa3b, v72
	v_mul_f32_e32 v73, 0x4038aa3b, v73
	v_exp_f32_e32 v72, v72
	v_exp_f32_e32 v73, v73
	v_add_f32_e32 v30, 1.0, v30
	v_add_f32_e32 v31, 1.0, v31
	v_add_f32_e32 v72, 1.0, v72
	v_add_f32_e32 v73, 1.0, v73
	v_rcp_f32_e32 v30, v30
	v_rcp_f32_e32 v31, v31
	v_rcp_f32_e32 v72, v72
	v_rcp_f32_e32 v73, v73
	v_pk_fma_f32 v[30:31], v[76:77], v[30:31], v[76:77] neg_lo:[1,0,0] neg_hi:[1,0,0]
	s_nop 0
	v_pk_mul_f32 v[26:27], v[26:27], v[30:31]
	v_pk_fma_f32 v[28:29], v[28:29], v[72:73], v[28:29] neg_lo:[1,0,0] neg_hi:[1,0,0]
	v_cvt_pk_bf16_f32 v26, v26, v27
	v_pk_mul_f32 v[24:25], v[24:25], v[28:29]
	s_nop 0
	v_cvt_pk_bf16_f32 v27, v24, v25
	v_lshl_add_u64 v[24:25], s[34:35], 0, v[106:107]
	v_lshl_add_u64 v[24:25], v[180:181], 1, v[24:25]
	global_store_dwordx2 v[24:25], v[26:27], off offset:8
; #define LAS __attribute__((address_space(3)))
; #define GAS __attribute__((address_space(1)))
;     DI f32x4 conv1(const Acc& acc, int ai, int bj, int n, int m, int fr, const f32x4& above, const f32x4& below, const f32x4& w0, const f32x4& w1, const f32x4& w2, const f32x4& b, bool zp, bool zn) const {
;         const f32x4 cur = acc[ai][bj][m][n];
;         const f32x4 tp = (m > 0 && fr == 15) ? acc[ai][bj][m > 0 ? m - 1 : 0][n] : cur;
;         const f32x4 tn = (m < 3 && fr == 0) ? acc[ai][bj][m < 3 ? m + 1 : 3][n] : cur;
;         f32x4 pv = ror4(tp), nx = rol4(tn);
;         if (m == 0 && fr == 0) pv = above;
;         if (m == 3 && fr == 15) nx = below;
;         if (zp) pv = (f32x4){0.f, 0.f, 0.f, 0.f};
;         if (zn) nx = (f32x4){0.f, 0.f, 0.f, 0.f};
;         return b + w0 * pv + w1 * cur + w2 * nx;
;     }
;     DI void operator()(const Acc& acc, const Unit& u, int wr, int wc, int fr, int fq, LAS unsigned char* scr) const {
;         LAS float* H = (LAS float*)scr;
;         const int colb = wc * 32 + 8 * fq;
;         if (fr == 0 || fr == 15) {
; #pragma unroll
;             for (int ai = 0; ai < 2; ++ai)
; #pragma unroll
;                 for (int bj = 0; bj < 2; ++bj)
; #pragma unroll
;                     for (int n = 0; n < 2; ++n) {
;                         LAS f32x4* dst = (LAS f32x4*)(H + (((2 * ai + wr) * 2 + (fr == 0 ? 0 : 1)) * 256 + bj * HALF + colb + 4 * n));
;                         *dst = (fr == 0) ? acc[ai][bj][0][n] : acc[ai][bj][3][n];
;                     }
;         }
;         asm volatile("s_waitcnt lgkmcnt(0)" ::: "memory"); __builtin_amdgcn_s_barrier(); asm volatile("" ::: "memory");
;         const int f0 = u.pn * 128 + colb;
;         const int row_base = 254 * u.pm - 1;
; #pragma unroll
;         for (int ai = 0; ai < 2; ++ai) {
;             const int k = 2 * ai + wr, ka = k > 0 ? k - 1 : 0, kb = k < 3 ? k + 1 : 3;
; #pragma unroll
;             for (int n = 0; n < 2; ++n) {
;                 const float* wp = cw + f0 + 4 * n;
;                 const f32x4 g0 = *(const f32x4*)wp, g1 = *(const GAS f32x4*)(wp + DFF2), g2 = *(const GAS f32x4*)(wp + 2 * DFF2), gb = *(const GAS f32x4*)(cb + f0 + 4 * n);
;                 const f32x4 v0 = *(const GAS f32x4*)(wp + DFF), v1 = *(const GAS f32x4*)(wp + DFF + DFF2), v2 = *(const GAS f32x4*)(wp + DFF + 2 * DFF2), vb = *(const GAS f32x4*)(cb + DFF + f0 + 4 * n);
.LBB0_846:
	s_or_b64 exec, exec, s[52:53]
	v_cndmask_b32_e64 v21, v13, v21, s[8:9]
	v_mov_b32_e32 v30, v193
	v_cndmask_b32_e64 v22, v14, v22, s[8:9]
	v_cndmask_b32_e64 v20, v12, v20, s[8:9]
	v_cndmask_b32_e64 v24, v14, v6, s[6:7]
	v_mov_b32_e32 v28, v193
	v_mov_b32_dpp v30, v21 row_ror:1 row_mask:0xf bank_mask:0xf
	v_mov_b32_e32 v29, v193
	v_mov_b32_e32 v21, v193
	v_cndmask_b32_e64 v23, v15, v23, s[8:9]
	v_cndmask_b32_e64 v25, v15, v7, s[6:7]
	v_cndmask_b32_e64 v26, v13, v5, s[6:7]
	v_cndmask_b32_e64 v27, v12, v4, s[6:7]
	v_mov_b32_dpp v28, v20 row_ror:1 row_mask:0xf bank_mask:0xf
	v_mov_b32_dpp v29, v22 row_ror:1 row_mask:0xf bank_mask:0xf
	v_mov_b32_e32 v31, v193
	v_mov_b32_e32 v20, v193
	v_mov_b32_e32 v22, v193
	v_mov_b32_dpp v21, v24 row_ror:15 row_mask:0xf bank_mask:0xf
	v_mov_b32_e32 v24, v193
	v_mov_b32_dpp v31, v23 row_ror:1 row_mask:0xf bank_mask:0xf
	v_mov_b32_dpp v20, v27 row_ror:15 row_mask:0xf bank_mask:0xf
	v_mov_b32_dpp v22, v26 row_ror:15 row_mask:0xf bank_mask:0xf
	v_mov_b32_dpp v24, v25 row_ror:15 row_mask:0xf bank_mask:0xf
	v_cndmask_b32_e64 v19, v11, v19, s[8:9]
	v_cndmask_b32_e64 v18, v10, v18, s[8:9]
	v_cndmask_b32_e64 v17, v9, v17, s[8:9]
	v_cndmask_b32_e64 v16, v8, v16, s[8:9]
	v_mov_b32_e32 v23, v193
	v_mov_b32_e32 v26, v193
	v_mov_b32_e32 v25, v193
	v_mov_b32_e32 v27, v193
	v_cndmask_b32_e64 v72, v11, v3, s[6:7]
	v_cndmask_b32_e64 v73, v10, v2, s[6:7]
	v_cndmask_b32_e64 v74, v9, v1, s[6:7]
	v_cndmask_b32_e64 v75, v8, v0, s[6:7]
	v_mov_b32_dpp v23, v16 row_ror:1 row_mask:0xf bank_mask:0xf
	v_mov_b32_dpp v26, v17 row_ror:1 row_mask:0xf bank_mask:0xf
	v_mov_b32_dpp v25, v18 row_ror:1 row_mask:0xf bank_mask:0xf
	v_mov_b32_dpp v27, v19 row_ror:1 row_mask:0xf bank_mask:0xf
	v_mov_b32_e32 v16, v193
	v_mov_b32_e32 v18, v193
	v_mov_b32_e32 v17, v193
	v_mov_b32_e32 v19, v193
	v_mov_b32_dpp v16, v75 row_ror:15 row_mask:0xf bank_mask:0xf
	v_mov_b32_dpp v18, v74 row_ror:15 row_mask:0xf bank_mask:0xf
	v_mov_b32_dpp v17, v73 row_ror:15 row_mask:0xf bank_mask:0xf
	v_mov_b32_dpp v19, v72 row_ror:15 row_mask:0xf bank_mask:0xf
	s_and_saveexec_b64 s[52:53], s[56:57]
	s_cbranch_execz .LBB0_848
	v_cmp_eq_u32_e32 vcc, 0, v118
	v_cmp_eq_u32_e64 s[28:29], 0, v115
	v_mov_b32_e32 v109, v193
	v_cndmask_b32_e64 v73, v30, 0, vcc
	v_cndmask_b32_e64 v72, v28, 0, vcc
	v_cndmask_b32_e64 v31, v31, 0, vcc
	v_cndmask_b32_e64 v30, v29, 0, vcc
	v_pk_fma_f32 v[28:29], v[66:67], v[30:31], v[70:71]
	v_pk_fma_f32 v[30:31], v[64:65], v[72:73], v[68:69]
	v_pk_fma_f32 v[28:29], v[14:15], v[58:59], v[28:29]
	v_pk_fma_f32 v[30:31], v[12:13], v[56:57], v[30:31]
	v_cndmask_b32_e64 v73, v22, 0, s[28:29]
	v_cndmask_b32_e64 v72, v20, 0, s[28:29]
	v_cndmask_b32_e64 v75, v24, 0, s[28:29]
	v_cndmask_b32_e64 v74, v21, 0, s[28:29]
	v_pk_fma_f32 v[20:21], v[54:55], v[74:75], v[28:29]
	v_pk_fma_f32 v[28:29], v[52:53], v[72:73], v[30:31]
	v_cndmask_b32_e64 v30, v23, 0, vcc
	v_cndmask_b32_e64 v23, v27, 0, vcc
	v_cndmask_b32_e64 v22, v25, 0, vcc
	v_pk_fma_f32 v[22:23], v[46:47], v[22:23], v[50:51]
	v_cndmask_b32_e64 v27, v18, 0, s[28:29]
	v_pk_fma_f32 v[22:23], v[10:11], v[38:39], v[22:23]
	v_cndmask_b32_e64 v19, v19, 0, s[28:29]
	v_cndmask_b32_e64 v18, v17, 0, s[28:29]
	v_cndmask_b32_e64 v31, v26, 0, vcc
	v_cndmask_b32_e64 v26, v16, 0, s[28:29]
	v_pk_fma_f32 v[16:17], v[34:35], v[18:19], v[22:23]
	v_mul_f32_e32 v18, 0x3d372713, v28
	v_mul_f32_e32 v18, v28, v18
	v_fma_f32 v18, v28, v18, v28
	v_mul_f32_e32 v18, 0x3f4c422a, v18
	v_mul_f32_e32 v18, 0x4038aa3b, v18
	v_exp_f32_e32 v22, v18
	v_mul_f32_e32 v18, 0x3d372713, v29
	v_mul_f32_e32 v18, v29, v18
	v_fma_f32 v18, v29, v18, v29
	v_pk_fma_f32 v[24:25], v[44:45], v[30:31], v[48:49]
	v_mul_f32_e32 v18, 0x3f4c422a, v18
	v_pk_fma_f32 v[24:25], v[8:9], v[36:37], v[24:25]
	v_mul_f32_e32 v18, 0x4038aa3b, v18
	v_exp_f32_e32 v23, v18
	v_pk_fma_f32 v[18:19], v[32:33], v[26:27], v[24:25]
	v_mul_f32_e32 v24, 0x3d372713, v20
	v_mul_f32_e32 v25, 0x3d372713, v21
	v_mul_f32_e32 v24, v20, v24
	v_mul_f32_e32 v25, v21, v25
	v_fma_f32 v24, v20, v24, v20
	v_fma_f32 v25, v21, v25, v21
	v_mul_f32_e32 v24, 0x3f4c422a, v24
	v_mul_f32_e32 v25, 0x3f4c422a, v25
	v_mul_f32_e32 v24, 0x4038aa3b, v24
	v_mul_f32_e32 v25, 0x4038aa3b, v25
	v_exp_f32_e32 v24, v24
	v_exp_f32_e32 v25, v25
	v_add_f32_e32 v22, 1.0, v22
	v_add_f32_e32 v23, 1.0, v23
	v_add_f32_e32 v24, 1.0, v24
	v_add_f32_e32 v25, 1.0, v25
	v_rcp_f32_e32 v22, v22
	v_rcp_f32_e32 v23, v23
	v_rcp_f32_e32 v24, v24
	v_rcp_f32_e32 v25, v25
	v_pk_fma_f32 v[22:23], v[28:29], v[22:23], v[28:29] neg_lo:[1,0,0] neg_hi:[1,0,0]
	s_nop 0
	v_pk_mul_f32 v[18:19], v[18:19], v[22:23]
	v_pk_fma_f32 v[20:21], v[20:21], v[24:25], v[20:21] neg_lo:[1,0,0] neg_hi:[1,0,0]
	v_cvt_pk_bf16_f32 v18, v18, v19
	v_pk_mul_f32 v[16:17], v[16:17], v[20:21]
	s_nop 0
	v_cvt_pk_bf16_f32 v19, v16, v17
	v_lshl_add_u64 v[16:17], s[34:35], 0, v[108:109]
	v_lshl_add_u64 v[16:17], v[180:181], 1, v[16:17]
	global_store_dwordx2 v[16:17], v[18:19], off offset:8
; #define LAS __attribute__((address_space(3)))
; #define GAS __attribute__((address_space(1)))
;     DI f32x4 conv1(const Acc& acc, int ai, int bj, int n, int m, int fr, const f32x4& above, const f32x4& below, const f32x4& w0, const f32x4& w1, const f32x4& w2, const f32x4& b, bool zp, bool zn) const {
;         const f32x4 cur = acc[ai][bj][m][n];
;         const f32x4 tp = (m > 0 && fr == 15) ? acc[ai][bj][m > 0 ? m - 1 : 0][n] : cur;
;         const f32x4 tn = (m < 3 && fr == 0) ? acc[ai][bj][m < 3 ? m + 1 : 3][n] : cur;
;         f32x4 pv = ror4(tp), nx = rol4(tn);
;         if (m == 0 && fr == 0) pv = above;
;         if (m == 3 && fr == 15) nx = below;
;         if (zp) pv = (f32x4){0.f, 0.f, 0.f, 0.f};
;         if (zn) nx = (f32x4){0.f, 0.f, 0.f, 0.f};
;         return b + w0 * pv + w1 * cur + w2 * nx;
;     }
;     DI void operator()(const Acc& acc, const Unit& u, int wr, int wc, int fr, int fq, LAS unsigned char* scr) const {
;         LAS float* H = (LAS float*)scr;
;         const int colb = wc * 32 + 8 * fq;
;         if (fr == 0 || fr == 15) {
; #pragma unroll
;             for (int ai = 0; ai < 2; ++ai)
; #pragma unroll
;                 for (int bj = 0; bj < 2; ++bj)
; #pragma unroll
;                     for (int n = 0; n < 2; ++n) {
;                         LAS f32x4* dst = (LAS f32x4*)(H + (((2 * ai + wr) * 2 + (fr == 0 ? 0 : 1)) * 256 + bj * HALF + colb + 4 * n));
;                         *dst = (fr == 0) ? acc[ai][bj][0][n] : acc[ai][bj][3][n];
;                     }
;         }
;         asm volatile("s_waitcnt lgkmcnt(0)" ::: "memory"); __builtin_amdgcn_s_barrier(); asm volatile("" ::: "memory");
;         const int f0 = u.pn * 128 + colb;
;         const int row_base = 254 * u.pm - 1;
; #pragma unroll
;         for (int ai = 0; ai < 2; ++ai) {
;             const int k = 2 * ai + wr, ka = k > 0 ? k - 1 : 0, kb = k < 3 ? k + 1 : 3;
; #pragma unroll
;             for (int n = 0; n < 2; ++n) {
;                 const float* wp = cw + f0 + 4 * n;
;                 const f32x4 g0 = *(const f32x4*)wp, g1 = *(const GAS f32x4*)(wp + DFF2), g2 = *(const GAS f32x4*)(wp + 2 * DFF2), gb = *(const GAS f32x4*)(cb + f0 + 4 * n);
;                 const f32x4 v0 = *(const GAS f32x4*)(wp + DFF), v1 = *(const GAS f32x4*)(wp + DFF + DFF2), v2 = *(const GAS f32x4*)(wp + DFF + 2 * DFF2), vb = *(const GAS f32x4*)(cb + DFF + f0 + 4 * n);
.LBB0_848:
	s_or_b64 exec, exec, s[52:53]
	v_cndmask_b32_e64 v14, v6, v14, s[8:9]
	v_cndmask_b32_e64 v13, v5, v13, s[8:9]
	v_cndmask_b32_e64 v12, v4, v12, s[8:9]
	v_mov_b32_e32 v20, v193
	v_mov_b32_e32 v22, v193
	v_mov_b32_e32 v21, v193
	v_cndmask_b32_e64 v15, v7, v15, s[8:9]
	v_mov_b32_dpp v20, v12 row_ror:1 row_mask:0xf bank_mask:0xf
	v_mov_b32_dpp v22, v13 row_ror:1 row_mask:0xf bank_mask:0xf
	v_mov_b32_dpp v21, v14 row_ror:1 row_mask:0xf bank_mask:0xf
	v_mov_b32_e32 v23, v193
	v_cndmask_b32_e64 v11, v3, v11, s[8:9]
	v_cndmask_b32_e64 v10, v2, v10, s[8:9]
	v_cndmask_b32_e64 v9, v1, v9, s[8:9]
	v_cndmask_b32_e64 v8, v0, v8, s[8:9]
	v_mov_b32_e32 v12, v193
	v_mov_b32_e32 v14, v193
	v_mov_b32_e32 v13, v193
	v_mov_b32_e32 v17, v193
	v_mov_b32_dpp v23, v15 row_ror:1 row_mask:0xf bank_mask:0xf
	v_mov_b32_e32 v15, v193
	v_mov_b32_e32 v16, v193
	v_mov_b32_e32 v18, v193
	v_mov_b32_e32 v19, v193
	v_mov_b32_dpp v12, v8 row_ror:1 row_mask:0xf bank_mask:0xf
	v_mov_b32_dpp v14, v9 row_ror:1 row_mask:0xf bank_mask:0xf
	v_mov_b32_dpp v13, v10 row_ror:1 row_mask:0xf bank_mask:0xf
	v_mov_b32_dpp v17, v11 row_ror:1 row_mask:0xf bank_mask:0xf
	v_mov_b32_e32 v8, v193
	v_mov_b32_e32 v9, v193
	v_mov_b32_e32 v10, v193
	v_mov_b32_e32 v11, v193
	v_mov_b32_dpp v15, v4 row_ror:15 row_mask:0xf bank_mask:0xf
	v_mov_b32_dpp v16, v5 row_ror:15 row_mask:0xf bank_mask:0xf
	v_mov_b32_dpp v18, v6 row_ror:15 row_mask:0xf bank_mask:0xf
	v_mov_b32_dpp v19, v7 row_ror:15 row_mask:0xf bank_mask:0xf
	v_mov_b32_dpp v8, v0 row_ror:15 row_mask:0xf bank_mask:0xf
	v_mov_b32_dpp v9, v1 row_ror:15 row_mask:0xf bank_mask:0xf
	v_mov_b32_dpp v10, v2 row_ror:15 row_mask:0xf bank_mask:0xf
	v_mov_b32_dpp v11, v3 row_ror:15 row_mask:0xf bank_mask:0xf
	s_and_saveexec_b64 s[52:53], s[58:59]
	s_cbranch_execz .LBB0_850
	v_cmp_eq_u32_e32 vcc, 0, v119
	s_waitcnt lgkmcnt(0)
	v_cndmask_b32_e64 v16, v16, v61, s[8:9]
	v_cmp_eq_u32_e64 s[28:29], 0, v116
	v_cndmask_b32_e64 v25, v22, 0, vcc
	v_cndmask_b32_e64 v23, v23, 0, vcc
	v_cndmask_b32_e64 v22, v21, 0, vcc
	v_cndmask_b32_e64 v24, v20, 0, vcc
	v_pk_fma_f32 v[20:21], v[66:67], v[22:23], v[70:71]
	v_pk_fma_f32 v[22:23], v[64:65], v[24:25], v[68:69]
	v_pk_fma_f32 v[6:7], v[6:7], v[58:59], v[20:21]
	v_cndmask_b32_e64 v21, v19, v63, s[8:9]
	v_cndmask_b32_e64 v15, v15, v60, s[8:9]
	v_cndmask_b32_e64 v19, v16, 0, s[28:29]
	v_cndmask_b32_e64 v17, v17, 0, vcc
	v_cndmask_b32_e64 v16, v13, 0, vcc
	v_pk_fma_f32 v[4:5], v[4:5], v[56:57], v[22:23]
	v_cndmask_b32_e64 v20, v18, v62, s[8:9]
	v_cndmask_b32_e64 v18, v15, 0, s[28:29]
	v_cndmask_b32_e64 v15, v14, 0, vcc
	v_cndmask_b32_e64 v14, v12, 0, vcc
	v_pk_fma_f32 v[12:13], v[46:47], v[16:17], v[50:51]
	v_cndmask_b32_e64 v10, v10, v42, s[8:9]
	v_cndmask_b32_e64 v11, v11, v43, s[8:9]
	v_pk_fma_f32 v[4:5], v[52:53], v[18:19], v[4:5]
	v_pk_fma_f32 v[2:3], v[2:3], v[38:39], v[12:13]
	v_cndmask_b32_e64 v11, v11, 0, s[28:29]
	v_cndmask_b32_e64 v10, v10, 0, s[28:29]
	v_pk_fma_f32 v[2:3], v[34:35], v[10:11], v[2:3]
	v_mul_f32_e32 v10, 0x3d372713, v4
	v_mul_f32_e32 v11, 0x3d372713, v5
	v_mul_f32_e32 v10, v4, v10
	v_mul_f32_e32 v11, v5, v11
	v_fma_f32 v10, v4, v10, v4
	v_fma_f32 v11, v5, v11, v5
	v_mul_f32_e32 v10, 0x3f4c422a, v10
	v_mul_f32_e32 v11, 0x3f4c422a, v11
	v_mul_f32_e32 v10, 0x4038aa3b, v10
	v_mul_f32_e32 v11, 0x4038aa3b, v11
	v_exp_f32_e32 v10, v10
	v_exp_f32_e32 v11, v11
	v_cndmask_b32_e64 v21, v21, 0, s[28:29]
	v_cndmask_b32_e64 v20, v20, 0, s[28:29]
	v_pk_fma_f32 v[14:15], v[44:45], v[14:15], v[48:49]
	v_cndmask_b32_e64 v8, v8, v40, s[8:9]
	v_cndmask_b32_e64 v9, v9, v41, s[8:9]
	v_pk_fma_f32 v[6:7], v[54:55], v[20:21], v[6:7]
	v_pk_fma_f32 v[0:1], v[0:1], v[36:37], v[14:15]
	v_cndmask_b32_e64 v9, v9, 0, s[28:29]
	v_cndmask_b32_e64 v8, v8, 0, s[28:29]
	v_pk_fma_f32 v[0:1], v[32:33], v[8:9], v[0:1]
	v_add_f32_e32 v8, 1.0, v10
	v_add_f32_e32 v9, 1.0, v11
	v_mul_f32_e32 v10, 0x3d372713, v6
	v_mul_f32_e32 v11, 0x3d372713, v7
	v_mul_f32_e32 v10, v6, v10
	v_mul_f32_e32 v11, v7, v11
	v_fma_f32 v10, v6, v10, v6
	v_fma_f32 v11, v7, v11, v7
	v_mul_f32_e32 v10, 0x3f4c422a, v10
	v_mul_f32_e32 v11, 0x3f4c422a, v11
	v_mul_f32_e32 v10, 0x4038aa3b, v10
	v_mul_f32_e32 v11, 0x4038aa3b, v11
	v_exp_f32_e32 v10, v10
	v_exp_f32_e32 v11, v11
	v_rcp_f32_e32 v8, v8
	v_rcp_f32_e32 v9, v9
	v_add_f32_e32 v10, 1.0, v10
	v_add_f32_e32 v11, 1.0, v11
	v_rcp_f32_e32 v10, v10
	v_rcp_f32_e32 v11, v11
	v_pk_fma_f32 v[4:5], v[4:5], v[8:9], v[4:5] neg_lo:[1,0,0] neg_hi:[1,0,0]
	v_mov_b32_e32 v111, v193
	v_pk_mul_f32 v[0:1], v[0:1], v[4:5]
	v_pk_fma_f32 v[4:5], v[6:7], v[10:11], v[6:7] neg_lo:[1,0,0] neg_hi:[1,0,0]
	v_cvt_pk_bf16_f32 v0, v0, v1
	v_pk_mul_f32 v[2:3], v[2:3], v[4:5]
	s_nop 0
	v_cvt_pk_bf16_f32 v1, v2, v3
	v_lshl_add_u64 v[2:3], s[34:35], 0, v[110:111]
	v_lshl_add_u64 v[2:3], v[180:181], 1, v[2:3]
	global_store_dwordx2 v[2:3], v[0:1], off offset:8
